# K-loops: hoisted address adds + merged vmcnt/lgkmcnt wait + loop tail rotated in front of the loop-back barrier
# baseline (speedup 1.0000x reference)
; #define PG8_STAGE(bufoff, gbase, voff) do { _Pragma("unroll") for (int _i = 0; _i < 2; ++_i) \
;         __builtin_amdgcn_global_load_lds((const unsigned*)((const char*)(gbase) + (voff)[_i]), (PG8_LAS unsigned*)(lds + (bufoff) + ldsw + _i * 8192), 16, 0, 0); } while (0)
; #define PG8_LDA(dst, b, h) do { _Pragma("unroll") for (int m = 0; m < 4; ++m) _Pragma("unroll") for (int k = 0; k < 2; ++k) dst[m][k] = *(const PG8_LAS bf16x8*)(lds + PG8_SA(b, h) + aoff + m * 2048 + k * 1024); } while (0)
; #define PG8_LDB(dst, b, h) do { _Pragma("unroll") for (int n = 0; n < 2; ++n) _Pragma("unroll") for (int k = 0; k < 2; ++k) dst[n][k] = *(const PG8_LAS bf16x8*)(lds + PG8_SB(b, h) + boff + n * 2048 + k * 1024); } while (0)
; #define PG8_WAIT_V(n) asm volatile("s_waitcnt vmcnt(" #n ")" ::: "memory")
; #define PG8_WAIT_L(n) asm volatile("s_waitcnt lgkmcnt(" #n ")" ::: "memory")
; #define PG8_BAR __builtin_amdgcn_s_barrier()
; #define PG8_SCHED __builtin_amdgcn_sched_barrier(0)
; template <class Epi, class Sched, bool ALIGN_EPI = false, bool SP2 = false>
; __device__ __forceinline__ void gemm_phase(PG8_LAS unsigned char* lds, const Gemm g, const Sched& S, const Epi& E) {
;     ...
;         const char* nA = has_next ? (const char*)g.A + (size_t)nxt.pm * tstep : cA; const char* nB = has_next ? (const char*)g.Bt + (size_t)nxt.pn * tstep : cB;
;         for (int t = 0; t < nt; t += 2) {
;             const bool last = (t == nt - 2);
;             const char* a1 = cA + (size_t)(t + 1) * kstepA;
;             const char* a2 = last ? nA : cA + (size_t)(t + 2) * kstepA; const char* b2 = last ? nB : cB + (size_t)(t + 2) * kstep;
;             const char* a3 = a2 + kstepA; const char* b3 = b2 + kstep;
;             if (last && has_next) S.a_ready(nxt);
;             if constexpr (SP2) {
;             PG8_LDB(B0, 0, 0); PG8_LDB(B1, 0, 1); PG8_SCHED; PG8_LDA(At, 0, 0); PG8_STAGE(PG8_SA(1, 1), a1 + hstepA, voffA);
;             PG8_WAIT_V(8); PG8_WAIT_L(0); PG8_BAR; PG8_MMA(0, 0, At, B0); PG8_MMA(0, 1, At, B1); PG8_BAR; PG8_SCHED;
;             PG8_LDA(At, 0, 1); PG8_STAGE(PG8_SB(0, 0), b2, voffB); PG8_STAGE(PG8_SB(0, 1), b2 + hstep, voffB); PG8_STAGE(PG8_SA(0, 0), a2, voffA);
;             PG8_WAIT_V(8); PG8_WAIT_L(0); PG8_BAR; PG8_MMA(1, 0, At, B0); PG8_MMA(1, 1, At, B1); PG8_BAR; PG8_SCHED;
.LBB0_115:
	ds_read_b128 v[150:153], v158
	ds_read_b128 v[162:165], v158 offset:1024
	ds_read_b128 v[166:169], v158 offset:2048
	ds_read_b128 v[170:173], v158 offset:3072
	ds_read_b128 v[174:177], v159
	ds_read_b128 v[178:181], v159 offset:1024
	ds_read_b128 v[182:185], v159 offset:2048
	ds_read_b128 v[186:189], v159 offset:3072
	s_add_u32 s68, s34, 0xfff00080
	s_addc_u32 s69, s35, -1
	s_cmp_eq_u32 s67, 60
	s_cselect_b32 s87, s21, s69
	s_cselect_b32 s86, s27, s68
	s_cselect_b32 s85, s19, s66
	s_cselect_b32 s84, s31, s65
	s_add_i32 m0, s53, 0xc000
	ds_read_b128 v[190:193], v160
	ds_read_b128 v[194:197], v160 offset:1024
	ds_read_b128 v[198:201], v160 offset:2048
	ds_read_b128 v[202:205], v160 offset:3072
	ds_read_b128 v[206:209], v160 offset:4096
	ds_read_b128 v[210:213], v160 offset:5120
	ds_read_b128 v[214:217], v160 offset:6144
	ds_read_b128 v[218:221], v160 offset:7168
	global_load_lds_dwordx4 v140, s[34:35]
	s_add_i32 m0, s53, 0xe000
	s_nop 0
	global_load_lds_dwordx4 v142, s[34:35]
	s_waitcnt vmcnt(8) lgkmcnt(0)
	s_barrier
	v_mfma_f32_16x16x32_bf16 v[124:127], v[150:153], v[190:193], v[124:127]
	v_mfma_f32_16x16x32_bf16 v[120:123], v[166:169], v[190:193], v[120:123]
	v_mfma_f32_16x16x32_bf16 v[108:111], v[150:153], v[198:201], v[108:111]
	v_mfma_f32_16x16x32_bf16 v[104:107], v[166:169], v[198:201], v[104:107]
	v_mfma_f32_16x16x32_bf16 v[92:95], v[150:153], v[206:209], v[92:95]
	v_mfma_f32_16x16x32_bf16 v[88:91], v[166:169], v[206:209], v[88:91]
	v_mfma_f32_16x16x32_bf16 v[76:79], v[150:153], v[214:217], v[76:79]
	v_mfma_f32_16x16x32_bf16 v[72:75], v[166:169], v[214:217], v[72:75]
	v_mfma_f32_16x16x32_bf16 v[124:127], v[162:165], v[194:197], v[124:127]
	v_mfma_f32_16x16x32_bf16 v[120:123], v[170:173], v[194:197], v[120:123]
	v_mfma_f32_16x16x32_bf16 v[108:111], v[162:165], v[202:205], v[108:111]
	v_mfma_f32_16x16x32_bf16 v[104:107], v[170:173], v[202:205], v[104:107]
	v_mfma_f32_16x16x32_bf16 v[92:95], v[162:165], v[210:213], v[92:95]
	v_mfma_f32_16x16x32_bf16 v[88:91], v[170:173], v[210:213], v[88:91]
	v_mfma_f32_16x16x32_bf16 v[76:79], v[162:165], v[218:221], v[76:79]
	v_mfma_f32_16x16x32_bf16 v[72:75], v[170:173], v[218:221], v[72:75]
	v_mfma_f32_16x16x32_bf16 v[116:119], v[174:177], v[190:193], v[116:119]
	v_mfma_f32_16x16x32_bf16 v[112:115], v[182:185], v[190:193], v[112:115]
	v_mfma_f32_16x16x32_bf16 v[100:103], v[174:177], v[198:201], v[100:103]
	v_mfma_f32_16x16x32_bf16 v[96:99], v[182:185], v[198:201], v[96:99]
	v_mfma_f32_16x16x32_bf16 v[84:87], v[174:177], v[206:209], v[84:87]
	v_mfma_f32_16x16x32_bf16 v[80:83], v[182:185], v[206:209], v[80:83]
	v_mfma_f32_16x16x32_bf16 v[68:71], v[174:177], v[214:217], v[68:71]
	v_mfma_f32_16x16x32_bf16 v[64:67], v[182:185], v[214:217], v[64:67]
	v_mfma_f32_16x16x32_bf16 v[116:119], v[178:181], v[194:197], v[116:119]
	v_mfma_f32_16x16x32_bf16 v[112:115], v[186:189], v[194:197], v[112:115]
	v_mfma_f32_16x16x32_bf16 v[100:103], v[178:181], v[202:205], v[100:103]
	v_mfma_f32_16x16x32_bf16 v[96:99], v[186:189], v[202:205], v[96:99]
	v_mfma_f32_16x16x32_bf16 v[84:87], v[178:181], v[210:213], v[84:87]
	v_mfma_f32_16x16x32_bf16 v[80:83], v[186:189], v[210:213], v[80:83]
	v_mfma_f32_16x16x32_bf16 v[68:71], v[178:181], v[218:221], v[68:71]
	v_mfma_f32_16x16x32_bf16 v[64:67], v[186:189], v[218:221], v[64:67]
	s_barrier
	s_add_u32 s98, s84, s12
	s_addc_u32 s99, s85, s13
	s_add_u32 s100, s86, s12
	s_addc_u32 s101, s87, s13
	s_add_i32 s68, s62, s33
	s_mov_b32 m0, s68
	ds_read_b128 v[190:193], v160 offset:16384
	ds_read_b128 v[194:197], v160 offset:17408
	ds_read_b128 v[198:201], v160 offset:18432
	ds_read_b128 v[202:205], v160 offset:19456
	ds_read_b128 v[206:209], v160 offset:20480
	ds_read_b128 v[210:213], v160 offset:21504
	ds_read_b128 v[214:217], v160 offset:22528
	ds_read_b128 v[218:221], v160 offset:23552
	global_load_lds_dwordx4 v132, s[84:85]
	s_add_i32 m0, s68, 0x2000
	s_add_u32 s68, s84, 0x100000
	s_addc_u32 s69, s85, 0
	s_add_i32 s70, s63, s33
	global_load_lds_dwordx4 v128, s[84:85]
	s_mov_b32 m0, s70
	s_nop 0
	global_load_lds_dwordx4 v132, s[68:69]
	s_add_i32 m0, s70, 0x2000
	s_nop 0
	global_load_lds_dwordx4 v128, s[68:69]
	s_mov_b32 m0, s53
	s_nop 0
	global_load_lds_dwordx4 v134, s[86:87]
	s_mov_b32 m0, s54
	s_nop 0
	global_load_lds_dwordx4 v130, s[86:87]
	s_waitcnt vmcnt(8) lgkmcnt(0)
	s_barrier
	v_mfma_f32_16x16x32_bf16 v[60:63], v[150:153], v[190:193], v[60:63]
	v_mfma_f32_16x16x32_bf16 v[56:59], v[166:169], v[190:193], v[56:59]
	v_mfma_f32_16x16x32_bf16 v[44:47], v[150:153], v[198:201], v[44:47]
	v_mfma_f32_16x16x32_bf16 v[40:43], v[166:169], v[198:201], v[40:43]
	v_mfma_f32_16x16x32_bf16 v[28:31], v[150:153], v[206:209], v[28:31]
	v_mfma_f32_16x16x32_bf16 v[24:27], v[166:169], v[206:209], v[24:27]
	v_mfma_f32_16x16x32_bf16 v[12:15], v[150:153], v[214:217], v[12:15]
	v_mfma_f32_16x16x32_bf16 v[8:11], v[166:169], v[214:217], v[8:11]
	v_mfma_f32_16x16x32_bf16 v[60:63], v[162:165], v[194:197], v[60:63]
	v_mfma_f32_16x16x32_bf16 v[56:59], v[170:173], v[194:197], v[56:59]
	v_mfma_f32_16x16x32_bf16 v[44:47], v[162:165], v[202:205], v[44:47]
	v_mfma_f32_16x16x32_bf16 v[40:43], v[170:173], v[202:205], v[40:43]
	v_mfma_f32_16x16x32_bf16 v[28:31], v[162:165], v[210:213], v[28:31]
	v_mfma_f32_16x16x32_bf16 v[24:27], v[170:173], v[210:213], v[24:27]
	v_mfma_f32_16x16x32_bf16 v[12:15], v[162:165], v[218:221], v[12:15]
	v_mfma_f32_16x16x32_bf16 v[8:11], v[170:173], v[218:221], v[8:11]
	v_mfma_f32_16x16x32_bf16 v[52:55], v[174:177], v[190:193], v[52:55]
	v_mfma_f32_16x16x32_bf16 v[48:51], v[182:185], v[190:193], v[48:51]
	v_mfma_f32_16x16x32_bf16 v[36:39], v[174:177], v[198:201], v[36:39]
	v_mfma_f32_16x16x32_bf16 v[32:35], v[182:185], v[198:201], v[32:35]
	v_mfma_f32_16x16x32_bf16 v[20:23], v[174:177], v[206:209], v[20:23]
	v_mfma_f32_16x16x32_bf16 v[16:19], v[182:185], v[206:209], v[16:19]
	v_mfma_f32_16x16x32_bf16 v[4:7], v[174:177], v[214:217], v[4:7]
	v_mfma_f32_16x16x32_bf16 v[0:3], v[182:185], v[214:217], v[0:3]
	v_mfma_f32_16x16x32_bf16 v[52:55], v[178:181], v[194:197], v[52:55]
	v_mfma_f32_16x16x32_bf16 v[48:51], v[186:189], v[194:197], v[48:51]
	v_mfma_f32_16x16x32_bf16 v[36:39], v[178:181], v[202:205], v[36:39]
	v_mfma_f32_16x16x32_bf16 v[32:35], v[186:189], v[202:205], v[32:35]
	v_mfma_f32_16x16x32_bf16 v[20:23], v[178:181], v[210:213], v[20:23]
	v_mfma_f32_16x16x32_bf16 v[16:19], v[186:189], v[210:213], v[16:19]
	v_mfma_f32_16x16x32_bf16 v[4:7], v[178:181], v[218:221], v[4:7]
	v_mfma_f32_16x16x32_bf16 v[0:3], v[186:189], v[218:221], v[0:3]
	s_barrier
; #define PG8_STAGE(bufoff, gbase, voff) do { _Pragma("unroll") for (int _i = 0; _i < 2; ++_i) \
;         __builtin_amdgcn_global_load_lds((const unsigned*)((const char*)(gbase) + (voff)[_i]), (PG8_LAS unsigned*)(lds + (bufoff) + ldsw + _i * 8192), 16, 0, 0); } while (0)
; #define PG8_LDA(dst, b, h) do { _Pragma("unroll") for (int m = 0; m < 4; ++m) _Pragma("unroll") for (int k = 0; k < 2; ++k) dst[m][k] = *(const PG8_LAS bf16x8*)(lds + PG8_SA(b, h) + aoff + m * 2048 + k * 1024); } while (0)
; #define PG8_LDB(dst, b, h) do { _Pragma("unroll") for (int n = 0; n < 2; ++n) _Pragma("unroll") for (int k = 0; k < 2; ++k) dst[n][k] = *(const PG8_LAS bf16x8*)(lds + PG8_SB(b, h) + boff + n * 2048 + k * 1024); } while (0)
; #define PG8_MMA(ai, bj, At, Bt) do { __builtin_amdgcn_s_setprio(1); _Pragma("unroll") for (int m = 0; m < 4; ++m) _Pragma("unroll") for (int n = 0; n < 2; ++n) _Pragma("unroll") for (int k = 0; k < 2; ++k) \
;         acc[ai][bj][m][n] = __builtin_amdgcn_mfma_f32_16x16x32_bf16(Bt[n][k], At[m][k], acc[ai][bj][m][n], 0, 0, 0); __builtin_amdgcn_s_setprio(0); } while (0)
; #define PG8_WAIT_V(n) asm volatile("s_waitcnt vmcnt(" #n ")" ::: "memory")
; #define PG8_WAIT_L(n) asm volatile("s_waitcnt lgkmcnt(" #n ")" ::: "memory")
; #define PG8_BAR __builtin_amdgcn_s_barrier()
; template <class Epi, class Sched, bool ALIGN_EPI = false, bool SP2 = false>
; __device__ __forceinline__ void gemm_phase(PG8_LAS unsigned char* lds, const Gemm g, const Sched& S, const Epi& E) {
;     ...
;         for (int t = 0; t < nt; t += 2) {
;             const bool last = (t == nt - 2);
;             const char* a1 = cA + (size_t)(t + 1) * kstepA;
;             const char* a2 = last ? nA : cA + (size_t)(t + 2) * kstepA; const char* b2 = last ? nB : cB + (size_t)(t + 2) * kstep;
;             const char* a3 = a2 + kstepA; const char* b3 = b2 + kstep;
;     ...
;             PG8_LDB(B0, 1, 0); PG8_LDB(B1, 1, 1); PG8_SCHED; PG8_LDA(At, 1, 0); PG8_STAGE(PG8_SA(0, 1), a2 + hstepA, voffA);
;             PG8_WAIT_V(8); PG8_WAIT_L(0); PG8_BAR; PG8_MMA(0, 0, At, B0); PG8_MMA(0, 1, At, B1); PG8_BAR; PG8_SCHED;
;             PG8_LDA(At, 1, 1); PG8_STAGE(PG8_SB(1, 0), b3, voffB); PG8_STAGE(PG8_SB(1, 1), b3 + hstep, voffB); PG8_STAGE(PG8_SA(1, 0), a3, voffA);
;             PG8_WAIT_V(8); PG8_WAIT_L(0); PG8_BAR; PG8_MMA(1, 0, At, B0); PG8_MMA(1, 1, At, B1); PG8_BAR; PG8_SCHED;
	s_add_i32 s70, 0, 0x18000
	s_add_i32 s71, 0, 0x1c000
	ds_read_b128 v[150:153], v154
	ds_read_b128 v[162:165], v154 offset:1024
	ds_read_b128 v[166:169], v154 offset:2048
	ds_read_b128 v[170:173], v154 offset:3072
	ds_read_b128 v[174:177], v155
	ds_read_b128 v[178:181], v155 offset:1024
	ds_read_b128 v[182:185], v155 offset:2048
	ds_read_b128 v[186:189], v155 offset:3072
	s_add_u32 s68, s86, 0x100000
	s_addc_u32 s69, s87, 0
	s_mov_b32 m0, s55
	ds_read_b128 v[190:193], v160 offset:32768
	ds_read_b128 v[194:197], v160 offset:33792
	ds_read_b128 v[198:201], v160 offset:34816
	ds_read_b128 v[202:205], v160 offset:35840
	ds_read_b128 v[206:209], v160 offset:36864
	ds_read_b128 v[210:213], v160 offset:37888
	ds_read_b128 v[214:217], v160 offset:38912
	ds_read_b128 v[218:221], v160 offset:39936
	global_load_lds_dwordx4 v134, s[68:69]
	s_mov_b32 m0, s56
	s_nop 0
	global_load_lds_dwordx4 v130, s[68:69]
	s_waitcnt vmcnt(8) lgkmcnt(0)
	s_barrier
	v_mfma_f32_16x16x32_bf16 v[124:127], v[150:153], v[190:193], v[124:127]
	v_mfma_f32_16x16x32_bf16 v[120:123], v[166:169], v[190:193], v[120:123]
	v_mfma_f32_16x16x32_bf16 v[108:111], v[150:153], v[198:201], v[108:111]
	v_mfma_f32_16x16x32_bf16 v[104:107], v[166:169], v[198:201], v[104:107]
	v_mfma_f32_16x16x32_bf16 v[92:95], v[150:153], v[206:209], v[92:95]
	v_mfma_f32_16x16x32_bf16 v[88:91], v[166:169], v[206:209], v[88:91]
	v_mfma_f32_16x16x32_bf16 v[76:79], v[150:153], v[214:217], v[76:79]
	v_mfma_f32_16x16x32_bf16 v[72:75], v[166:169], v[214:217], v[72:75]
	v_mfma_f32_16x16x32_bf16 v[124:127], v[162:165], v[194:197], v[124:127]
	v_mfma_f32_16x16x32_bf16 v[120:123], v[170:173], v[194:197], v[120:123]
	v_mfma_f32_16x16x32_bf16 v[108:111], v[162:165], v[202:205], v[108:111]
	v_mfma_f32_16x16x32_bf16 v[104:107], v[170:173], v[202:205], v[104:107]
	v_mfma_f32_16x16x32_bf16 v[92:95], v[162:165], v[210:213], v[92:95]
	v_mfma_f32_16x16x32_bf16 v[88:91], v[170:173], v[210:213], v[88:91]
	v_mfma_f32_16x16x32_bf16 v[76:79], v[162:165], v[218:221], v[76:79]
	v_mfma_f32_16x16x32_bf16 v[72:75], v[170:173], v[218:221], v[72:75]
	v_mfma_f32_16x16x32_bf16 v[116:119], v[174:177], v[190:193], v[116:119]
	v_mfma_f32_16x16x32_bf16 v[112:115], v[182:185], v[190:193], v[112:115]
	v_mfma_f32_16x16x32_bf16 v[100:103], v[174:177], v[198:201], v[100:103]
	v_mfma_f32_16x16x32_bf16 v[96:99], v[182:185], v[198:201], v[96:99]
	v_mfma_f32_16x16x32_bf16 v[84:87], v[174:177], v[206:209], v[84:87]
	v_mfma_f32_16x16x32_bf16 v[80:83], v[182:185], v[206:209], v[80:83]
	v_mfma_f32_16x16x32_bf16 v[68:71], v[174:177], v[214:217], v[68:71]
	v_mfma_f32_16x16x32_bf16 v[64:67], v[182:185], v[214:217], v[64:67]
	v_mfma_f32_16x16x32_bf16 v[116:119], v[178:181], v[194:197], v[116:119]
	v_mfma_f32_16x16x32_bf16 v[112:115], v[186:189], v[194:197], v[112:115]
	v_mfma_f32_16x16x32_bf16 v[100:103], v[178:181], v[202:205], v[100:103]
	v_mfma_f32_16x16x32_bf16 v[96:99], v[186:189], v[202:205], v[96:99]
	v_mfma_f32_16x16x32_bf16 v[84:87], v[178:181], v[210:213], v[84:87]
	v_mfma_f32_16x16x32_bf16 v[80:83], v[186:189], v[210:213], v[80:83]
	v_mfma_f32_16x16x32_bf16 v[68:71], v[178:181], v[218:221], v[68:71]
	v_mfma_f32_16x16x32_bf16 v[64:67], v[186:189], v[218:221], v[64:67]
	s_barrier
	s_add_i32 s68, s70, s33
	s_mov_b32 m0, s68
	ds_read_b128 v[190:193], v160 offset:49152
	ds_read_b128 v[194:197], v160 offset:50176
	ds_read_b128 v[198:201], v160 offset:51200
	ds_read_b128 v[202:205], v160 offset:52224
	ds_read_b128 v[206:209], v160 offset:53248
	ds_read_b128 v[210:213], v160 offset:54272
	ds_read_b128 v[214:217], v160 offset:55296
	ds_read_b128 v[218:221], v160 offset:56320
	global_load_lds_dwordx4 v132, s[98:99]
	s_add_i32 m0, s68, 0x2000
	s_add_u32 s68, s84, 0x100080
	s_addc_u32 s69, s85, 0
	s_add_i32 s70, s71, s33
	global_load_lds_dwordx4 v128, s[98:99]
	s_mov_b32 m0, s70
	s_nop 0
	global_load_lds_dwordx4 v132, s[68:69]
	s_add_i32 m0, s70, 0x2000
	s_nop 0
	global_load_lds_dwordx4 v128, s[68:69]
	s_mov_b32 m0, s60
	s_nop 0
	global_load_lds_dwordx4 v134, s[100:101]
	s_mov_b32 m0, s61
	s_nop 0
	global_load_lds_dwordx4 v130, s[100:101]
	s_add_i32 s67, s67, 2
	s_add_u32 s34, s34, 0x100
	s_addc_u32 s35, s35, 0
	s_add_u32 s65, s65, 0x100
	s_addc_u32 s66, s66, 0
	s_cmp_gt_u32 s67, 61
	s_waitcnt vmcnt(8) lgkmcnt(0)
	s_barrier
	v_mfma_f32_16x16x32_bf16 v[60:63], v[150:153], v[190:193], v[60:63]
	v_mfma_f32_16x16x32_bf16 v[56:59], v[166:169], v[190:193], v[56:59]
	v_mfma_f32_16x16x32_bf16 v[44:47], v[150:153], v[198:201], v[44:47]
	v_mfma_f32_16x16x32_bf16 v[40:43], v[166:169], v[198:201], v[40:43]
	v_mfma_f32_16x16x32_bf16 v[28:31], v[150:153], v[206:209], v[28:31]
	v_mfma_f32_16x16x32_bf16 v[24:27], v[166:169], v[206:209], v[24:27]
	v_mfma_f32_16x16x32_bf16 v[12:15], v[150:153], v[214:217], v[12:15]
	v_mfma_f32_16x16x32_bf16 v[8:11], v[166:169], v[214:217], v[8:11]
	v_mfma_f32_16x16x32_bf16 v[60:63], v[162:165], v[194:197], v[60:63]
	v_mfma_f32_16x16x32_bf16 v[56:59], v[170:173], v[194:197], v[56:59]
	v_mfma_f32_16x16x32_bf16 v[44:47], v[162:165], v[202:205], v[44:47]
	v_mfma_f32_16x16x32_bf16 v[40:43], v[170:173], v[202:205], v[40:43]
	v_mfma_f32_16x16x32_bf16 v[28:31], v[162:165], v[210:213], v[28:31]
	v_mfma_f32_16x16x32_bf16 v[24:27], v[170:173], v[210:213], v[24:27]
	v_mfma_f32_16x16x32_bf16 v[12:15], v[162:165], v[218:221], v[12:15]
	v_mfma_f32_16x16x32_bf16 v[8:11], v[170:173], v[218:221], v[8:11]
	v_mfma_f32_16x16x32_bf16 v[52:55], v[174:177], v[190:193], v[52:55]
	v_mfma_f32_16x16x32_bf16 v[48:51], v[182:185], v[190:193], v[48:51]
	v_mfma_f32_16x16x32_bf16 v[36:39], v[174:177], v[198:201], v[36:39]
	v_mfma_f32_16x16x32_bf16 v[32:35], v[182:185], v[198:201], v[32:35]
	v_mfma_f32_16x16x32_bf16 v[20:23], v[174:177], v[206:209], v[20:23]
	v_mfma_f32_16x16x32_bf16 v[16:19], v[182:185], v[206:209], v[16:19]
	v_mfma_f32_16x16x32_bf16 v[4:7], v[174:177], v[214:217], v[4:7]
	v_mfma_f32_16x16x32_bf16 v[0:3], v[182:185], v[214:217], v[0:3]
	v_mfma_f32_16x16x32_bf16 v[52:55], v[178:181], v[194:197], v[52:55]
	v_mfma_f32_16x16x32_bf16 v[48:51], v[186:189], v[194:197], v[48:51]
	v_mfma_f32_16x16x32_bf16 v[36:39], v[178:181], v[202:205], v[36:39]
	v_mfma_f32_16x16x32_bf16 v[32:35], v[186:189], v[202:205], v[32:35]
	v_mfma_f32_16x16x32_bf16 v[20:23], v[178:181], v[210:213], v[20:23]
	v_mfma_f32_16x16x32_bf16 v[16:19], v[186:189], v[210:213], v[16:19]
	v_mfma_f32_16x16x32_bf16 v[4:7], v[178:181], v[218:221], v[4:7]
	v_mfma_f32_16x16x32_bf16 v[0:3], v[186:189], v[218:221], v[0:3]
	s_barrier
	s_cbranch_scc0 .LBB0_115
	s_and_b64 vcc, exec, s[14:15]
	s_cbranch_vccz .LBB0_118
	s_barrier

; #define PG8_STAGE(bufoff, gbase, voff) do { _Pragma("unroll") for (int _i = 0; _i < 2; ++_i) \
;         __builtin_amdgcn_global_load_lds((const unsigned*)((const char*)(gbase) + (voff)[_i]), (PG8_LAS unsigned*)(lds + (bufoff) + ldsw + _i * 8192), 16, 0, 0); } while (0)
; #define PG8_LDA(dst, b, h) do { _Pragma("unroll") for (int m = 0; m < 4; ++m) _Pragma("unroll") for (int k = 0; k < 2; ++k) dst[m][k] = *(const PG8_LAS bf16x8*)(lds + PG8_SA(b, h) + aoff + m * 2048 + k * 1024); } while (0)
; #define PG8_LDB(dst, b, h) do { _Pragma("unroll") for (int n = 0; n < 2; ++n) _Pragma("unroll") for (int k = 0; k < 2; ++k) dst[n][k] = *(const PG8_LAS bf16x8*)(lds + PG8_SB(b, h) + boff + n * 2048 + k * 1024); } while (0)
; #define PG8_WAIT_V(n) asm volatile("s_waitcnt vmcnt(" #n ")" ::: "memory")
; #define PG8_WAIT_L(n) asm volatile("s_waitcnt lgkmcnt(" #n ")" ::: "memory")
; #define PG8_BAR __builtin_amdgcn_s_barrier()
; #define PG8_SCHED __builtin_amdgcn_sched_barrier(0)
; template <class Epi, class Sched, bool ALIGN_EPI = false, bool SP2 = false>
; __device__ __forceinline__ void gemm_phase(PG8_LAS unsigned char* lds, const Gemm g, const Sched& S, const Epi& E) {
;     ...
;         const char* nA = has_next ? (const char*)g.A + (size_t)nxt.pm * tstep : cA; const char* nB = has_next ? (const char*)g.Bt + (size_t)nxt.pn * tstep : cB;
;         for (int t = 0; t < nt; t += 2) {
;             const bool last = (t == nt - 2);
;             const char* a1 = cA + (size_t)(t + 1) * kstepA;
;             const char* a2 = last ? nA : cA + (size_t)(t + 2) * kstepA; const char* b2 = last ? nB : cB + (size_t)(t + 2) * kstep;
;             const char* a3 = a2 + kstepA; const char* b3 = b2 + kstep;
;             if (last && has_next) S.a_ready(nxt);
;             if constexpr (SP2) {
;             PG8_LDB(B0, 0, 0); PG8_LDB(B1, 0, 1); PG8_SCHED; PG8_LDA(At, 0, 0); PG8_STAGE(PG8_SA(1, 1), a1 + hstepA, voffA);
;             PG8_WAIT_V(8); PG8_WAIT_L(0); PG8_BAR; PG8_MMA(0, 0, At, B0); PG8_MMA(0, 1, At, B1); PG8_BAR; PG8_SCHED;
;             PG8_LDA(At, 0, 1); PG8_STAGE(PG8_SB(0, 0), b2, voffB); PG8_STAGE(PG8_SB(0, 1), b2 + hstep, voffB); PG8_STAGE(PG8_SA(0, 0), a2, voffA);
;             PG8_WAIT_V(8); PG8_WAIT_L(0); PG8_BAR; PG8_MMA(1, 0, At, B0); PG8_MMA(1, 1, At, B1); PG8_BAR; PG8_SCHED;
.LBB0_1198:
	ds_read_b128 v[144:147], v153
	ds_read_b128 v[158:161], v153 offset:1024
	ds_read_b128 v[162:165], v153 offset:2048
	ds_read_b128 v[166:169], v153 offset:3072
	ds_read_b128 v[170:173], v154
	ds_read_b128 v[174:177], v154 offset:1024
	ds_read_b128 v[178:181], v154 offset:2048
	ds_read_b128 v[182:185], v154 offset:3072
	s_add_u32 s38, s34, 0xfff00080
	s_addc_u32 s39, s35, -1
	s_cmp_eq_u32 s65, 60
	s_cselect_b32 s41, s21, s39
	s_cselect_b32 s40, s27, s38
	s_cselect_b32 s39, s19, s64
	s_cselect_b32 s38, s62, s63
	s_add_i32 m0, s31, 0xc000
	ds_read_b128 v[186:189], v155
	ds_read_b128 v[190:193], v155 offset:1024
	ds_read_b128 v[194:197], v155 offset:2048
	ds_read_b128 v[198:201], v155 offset:3072
	ds_read_b128 v[202:205], v155 offset:4096
	ds_read_b128 v[206:209], v155 offset:5120
	ds_read_b128 v[210:213], v155 offset:6144
	ds_read_b128 v[214:217], v155 offset:7168
	global_load_lds_dwordx4 v136, s[34:35]
	s_add_i32 m0, s31, 0xe000
	s_nop 0
	global_load_lds_dwordx4 v138, s[34:35]
	s_waitcnt vmcnt(8) lgkmcnt(0)
	s_barrier
	v_mfma_f32_16x16x32_bf16 v[124:127], v[144:147], v[186:189], v[124:127]
	v_mfma_f32_16x16x32_bf16 v[120:123], v[162:165], v[186:189], v[120:123]
	v_mfma_f32_16x16x32_bf16 v[108:111], v[144:147], v[194:197], v[108:111]
	v_mfma_f32_16x16x32_bf16 v[48:51], v[162:165], v[194:197], v[48:51]
	v_mfma_f32_16x16x32_bf16 v[100:103], v[144:147], v[202:205], v[100:103]
	v_mfma_f32_16x16x32_bf16 v[64:67], v[162:165], v[202:205], v[64:67]
	v_mfma_f32_16x16x32_bf16 v[92:95], v[144:147], v[210:213], v[92:95]
	v_mfma_f32_16x16x32_bf16 v[80:83], v[162:165], v[210:213], v[80:83]
	v_mfma_f32_16x16x32_bf16 v[124:127], v[158:161], v[190:193], v[124:127]
	v_mfma_f32_16x16x32_bf16 v[120:123], v[166:169], v[190:193], v[120:123]
	v_mfma_f32_16x16x32_bf16 v[108:111], v[158:161], v[198:201], v[108:111]
	v_mfma_f32_16x16x32_bf16 v[48:51], v[166:169], v[198:201], v[48:51]
	v_mfma_f32_16x16x32_bf16 v[100:103], v[158:161], v[206:209], v[100:103]
	v_mfma_f32_16x16x32_bf16 v[64:67], v[166:169], v[206:209], v[64:67]
	v_mfma_f32_16x16x32_bf16 v[92:95], v[158:161], v[214:217], v[92:95]
	v_mfma_f32_16x16x32_bf16 v[80:83], v[166:169], v[214:217], v[80:83]
	v_mfma_f32_16x16x32_bf16 v[116:119], v[170:173], v[186:189], v[116:119]
	v_mfma_f32_16x16x32_bf16 v[112:115], v[178:181], v[186:189], v[112:115]
	v_mfma_f32_16x16x32_bf16 v[104:107], v[170:173], v[194:197], v[104:107]
	v_mfma_f32_16x16x32_bf16 v[52:55], v[178:181], v[194:197], v[52:55]
	v_mfma_f32_16x16x32_bf16 v[96:99], v[170:173], v[202:205], v[96:99]
	v_mfma_f32_16x16x32_bf16 v[76:79], v[178:181], v[202:205], v[76:79]
	v_mfma_f32_16x16x32_bf16 v[88:91], v[170:173], v[210:213], v[88:91]
	v_mfma_f32_16x16x32_bf16 v[84:87], v[178:181], v[210:213], v[84:87]
	v_mfma_f32_16x16x32_bf16 v[116:119], v[174:177], v[190:193], v[116:119]
	v_mfma_f32_16x16x32_bf16 v[112:115], v[182:185], v[190:193], v[112:115]
	v_mfma_f32_16x16x32_bf16 v[104:107], v[174:177], v[198:201], v[104:107]
	v_mfma_f32_16x16x32_bf16 v[52:55], v[182:185], v[198:201], v[52:55]
	v_mfma_f32_16x16x32_bf16 v[96:99], v[174:177], v[206:209], v[96:99]
	v_mfma_f32_16x16x32_bf16 v[76:79], v[182:185], v[206:209], v[76:79]
	v_mfma_f32_16x16x32_bf16 v[88:91], v[174:177], v[214:217], v[88:91]
	v_mfma_f32_16x16x32_bf16 v[84:87], v[182:185], v[214:217], v[84:87]
	s_barrier
	s_add_u32 s98, s38, s14
	s_addc_u32 s99, s39, s15
	s_add_u32 s100, s40, s14
	s_addc_u32 s101, s41, s15
	s_add_i32 s66, s60, s33
	s_mov_b32 m0, s66
	ds_read_b128 v[186:189], v155 offset:16384
	ds_read_b128 v[190:193], v155 offset:17408
	ds_read_b128 v[194:197], v155 offset:18432
	ds_read_b128 v[198:201], v155 offset:19456
	ds_read_b128 v[202:205], v155 offset:20480
	ds_read_b128 v[206:209], v155 offset:21504
	ds_read_b128 v[210:213], v155 offset:22528
	ds_read_b128 v[214:217], v155 offset:23552
	global_load_lds_dwordx4 v130, s[38:39]
	s_add_i32 m0, s66, 0x2000
	s_add_u32 s66, s38, 0x100000
	s_addc_u32 s67, s39, 0
	s_add_i32 s68, s61, s33
	global_load_lds_dwordx4 v134, s[38:39]
	s_mov_b32 m0, s68
	s_nop 0
	global_load_lds_dwordx4 v130, s[66:67]
	s_add_i32 m0, s68, 0x2000
	s_nop 0
	global_load_lds_dwordx4 v134, s[66:67]
	s_mov_b32 m0, s31
	s_nop 0
	global_load_lds_dwordx4 v128, s[40:41]
	s_mov_b32 m0, s52
	s_nop 0
	global_load_lds_dwordx4 v132, s[40:41]
	s_waitcnt vmcnt(8) lgkmcnt(0)
	s_barrier
	v_mfma_f32_16x16x32_bf16 v[72:75], v[144:147], v[186:189], v[72:75]
	v_mfma_f32_16x16x32_bf16 v[68:71], v[162:165], v[186:189], v[68:71]
	v_mfma_f32_16x16x32_bf16 v[44:47], v[144:147], v[194:197], v[44:47]
	v_mfma_f32_16x16x32_bf16 v[40:43], v[162:165], v[194:197], v[40:43]
	v_mfma_f32_16x16x32_bf16 v[28:31], v[144:147], v[202:205], v[28:31]
	v_mfma_f32_16x16x32_bf16 v[24:27], v[162:165], v[202:205], v[24:27]
	v_mfma_f32_16x16x32_bf16 v[12:15], v[144:147], v[210:213], v[12:15]
	v_mfma_f32_16x16x32_bf16 v[8:11], v[162:165], v[210:213], v[8:11]
	v_mfma_f32_16x16x32_bf16 v[72:75], v[158:161], v[190:193], v[72:75]
	v_mfma_f32_16x16x32_bf16 v[68:71], v[166:169], v[190:193], v[68:71]
	v_mfma_f32_16x16x32_bf16 v[44:47], v[158:161], v[198:201], v[44:47]
	v_mfma_f32_16x16x32_bf16 v[40:43], v[166:169], v[198:201], v[40:43]
	v_mfma_f32_16x16x32_bf16 v[28:31], v[158:161], v[206:209], v[28:31]
	v_mfma_f32_16x16x32_bf16 v[24:27], v[166:169], v[206:209], v[24:27]
	v_mfma_f32_16x16x32_bf16 v[12:15], v[158:161], v[214:217], v[12:15]
	v_mfma_f32_16x16x32_bf16 v[8:11], v[166:169], v[214:217], v[8:11]
	v_mfma_f32_16x16x32_bf16 v[60:63], v[170:173], v[186:189], v[60:63]
	v_mfma_f32_16x16x32_bf16 v[56:59], v[178:181], v[186:189], v[56:59]
	v_mfma_f32_16x16x32_bf16 v[36:39], v[170:173], v[194:197], v[36:39]
	v_mfma_f32_16x16x32_bf16 v[32:35], v[178:181], v[194:197], v[32:35]
	v_mfma_f32_16x16x32_bf16 v[20:23], v[170:173], v[202:205], v[20:23]
	v_mfma_f32_16x16x32_bf16 v[16:19], v[178:181], v[202:205], v[16:19]
	v_mfma_f32_16x16x32_bf16 v[4:7], v[170:173], v[210:213], v[4:7]
	v_mfma_f32_16x16x32_bf16 v[0:3], v[178:181], v[210:213], v[0:3]
	v_mfma_f32_16x16x32_bf16 v[60:63], v[174:177], v[190:193], v[60:63]
	v_mfma_f32_16x16x32_bf16 v[56:59], v[182:185], v[190:193], v[56:59]
	v_mfma_f32_16x16x32_bf16 v[36:39], v[174:177], v[198:201], v[36:39]
	v_mfma_f32_16x16x32_bf16 v[32:35], v[182:185], v[198:201], v[32:35]
	v_mfma_f32_16x16x32_bf16 v[20:23], v[174:177], v[206:209], v[20:23]
	v_mfma_f32_16x16x32_bf16 v[16:19], v[182:185], v[206:209], v[16:19]
	v_mfma_f32_16x16x32_bf16 v[4:7], v[174:177], v[214:217], v[4:7]
	v_mfma_f32_16x16x32_bf16 v[0:3], v[182:185], v[214:217], v[0:3]
	s_barrier
; #define PG8_STAGE(bufoff, gbase, voff) do { _Pragma("unroll") for (int _i = 0; _i < 2; ++_i) \
;         __builtin_amdgcn_global_load_lds((const unsigned*)((const char*)(gbase) + (voff)[_i]), (PG8_LAS unsigned*)(lds + (bufoff) + ldsw + _i * 8192), 16, 0, 0); } while (0)
; #define PG8_LDA(dst, b, h) do { _Pragma("unroll") for (int m = 0; m < 4; ++m) _Pragma("unroll") for (int k = 0; k < 2; ++k) dst[m][k] = *(const PG8_LAS bf16x8*)(lds + PG8_SA(b, h) + aoff + m * 2048 + k * 1024); } while (0)
; #define PG8_LDB(dst, b, h) do { _Pragma("unroll") for (int n = 0; n < 2; ++n) _Pragma("unroll") for (int k = 0; k < 2; ++k) dst[n][k] = *(const PG8_LAS bf16x8*)(lds + PG8_SB(b, h) + boff + n * 2048 + k * 1024); } while (0)
; #define PG8_MMA(ai, bj, At, Bt) do { __builtin_amdgcn_s_setprio(1); _Pragma("unroll") for (int m = 0; m < 4; ++m) _Pragma("unroll") for (int n = 0; n < 2; ++n) _Pragma("unroll") for (int k = 0; k < 2; ++k) \
;         acc[ai][bj][m][n] = __builtin_amdgcn_mfma_f32_16x16x32_bf16(Bt[n][k], At[m][k], acc[ai][bj][m][n], 0, 0, 0); __builtin_amdgcn_s_setprio(0); } while (0)
; #define PG8_WAIT_V(n) asm volatile("s_waitcnt vmcnt(" #n ")" ::: "memory")
; #define PG8_WAIT_L(n) asm volatile("s_waitcnt lgkmcnt(" #n ")" ::: "memory")
; #define PG8_BAR __builtin_amdgcn_s_barrier()
; template <class Epi, class Sched, bool ALIGN_EPI = false, bool SP2 = false>
; __device__ __forceinline__ void gemm_phase(PG8_LAS unsigned char* lds, const Gemm g, const Sched& S, const Epi& E) {
;     ...
;         for (int t = 0; t < nt; t += 2) {
;             const bool last = (t == nt - 2);
;             const char* a1 = cA + (size_t)(t + 1) * kstepA;
;             const char* a2 = last ? nA : cA + (size_t)(t + 2) * kstepA; const char* b2 = last ? nB : cB + (size_t)(t + 2) * kstep;
;             const char* a3 = a2 + kstepA; const char* b3 = b2 + kstep;
;     ...
;             PG8_LDB(B0, 1, 0); PG8_LDB(B1, 1, 1); PG8_SCHED; PG8_LDA(At, 1, 0); PG8_STAGE(PG8_SA(0, 1), a2 + hstepA, voffA);
;             PG8_WAIT_V(8); PG8_WAIT_L(0); PG8_BAR; PG8_MMA(0, 0, At, B0); PG8_MMA(0, 1, At, B1); PG8_BAR; PG8_SCHED;
;             PG8_LDA(At, 1, 1); PG8_STAGE(PG8_SB(1, 0), b3, voffB); PG8_STAGE(PG8_SB(1, 1), b3 + hstep, voffB); PG8_STAGE(PG8_SA(1, 0), a3, voffA);
;             PG8_WAIT_V(8); PG8_WAIT_L(0); PG8_BAR; PG8_MMA(1, 0, At, B0); PG8_MMA(1, 1, At, B1); PG8_BAR; PG8_SCHED;
	s_add_i32 s66, 0, 0x18000
	s_add_i32 s67, 0, 0x1c000
	ds_read_b128 v[144:147], v148
	ds_read_b128 v[158:161], v148 offset:1024
	ds_read_b128 v[162:165], v148 offset:2048
	ds_read_b128 v[166:169], v148 offset:3072
	ds_read_b128 v[170:173], v149
	ds_read_b128 v[174:177], v149 offset:1024
	ds_read_b128 v[178:181], v149 offset:2048
	ds_read_b128 v[182:185], v149 offset:3072
	s_add_u32 s40, s40, 0x100000
	s_addc_u32 s41, s41, 0
	s_mov_b32 m0, s53
	ds_read_b128 v[186:189], v155 offset:32768
	ds_read_b128 v[190:193], v155 offset:33792
	ds_read_b128 v[194:197], v155 offset:34816
	ds_read_b128 v[198:201], v155 offset:35840
	ds_read_b128 v[202:205], v155 offset:36864
	ds_read_b128 v[206:209], v155 offset:37888
	ds_read_b128 v[210:213], v155 offset:38912
	ds_read_b128 v[214:217], v155 offset:39936
	global_load_lds_dwordx4 v128, s[40:41]
	s_mov_b32 m0, s54
	s_nop 0
	global_load_lds_dwordx4 v132, s[40:41]
	s_waitcnt vmcnt(8) lgkmcnt(0)
	s_barrier
	v_mfma_f32_16x16x32_bf16 v[124:127], v[144:147], v[186:189], v[124:127]
	v_mfma_f32_16x16x32_bf16 v[120:123], v[162:165], v[186:189], v[120:123]
	v_mfma_f32_16x16x32_bf16 v[108:111], v[144:147], v[194:197], v[108:111]
	v_mfma_f32_16x16x32_bf16 v[48:51], v[162:165], v[194:197], v[48:51]
	v_mfma_f32_16x16x32_bf16 v[100:103], v[144:147], v[202:205], v[100:103]
	v_mfma_f32_16x16x32_bf16 v[64:67], v[162:165], v[202:205], v[64:67]
	v_mfma_f32_16x16x32_bf16 v[92:95], v[144:147], v[210:213], v[92:95]
	v_mfma_f32_16x16x32_bf16 v[80:83], v[162:165], v[210:213], v[80:83]
	v_mfma_f32_16x16x32_bf16 v[124:127], v[158:161], v[190:193], v[124:127]
	v_mfma_f32_16x16x32_bf16 v[120:123], v[166:169], v[190:193], v[120:123]
	v_mfma_f32_16x16x32_bf16 v[108:111], v[158:161], v[198:201], v[108:111]
	v_mfma_f32_16x16x32_bf16 v[48:51], v[166:169], v[198:201], v[48:51]
	v_mfma_f32_16x16x32_bf16 v[100:103], v[158:161], v[206:209], v[100:103]
	v_mfma_f32_16x16x32_bf16 v[64:67], v[166:169], v[206:209], v[64:67]
	v_mfma_f32_16x16x32_bf16 v[92:95], v[158:161], v[214:217], v[92:95]
	v_mfma_f32_16x16x32_bf16 v[80:83], v[166:169], v[214:217], v[80:83]
	v_mfma_f32_16x16x32_bf16 v[116:119], v[170:173], v[186:189], v[116:119]
	v_mfma_f32_16x16x32_bf16 v[112:115], v[178:181], v[186:189], v[112:115]
	v_mfma_f32_16x16x32_bf16 v[104:107], v[170:173], v[194:197], v[104:107]
	v_mfma_f32_16x16x32_bf16 v[52:55], v[178:181], v[194:197], v[52:55]
	v_mfma_f32_16x16x32_bf16 v[96:99], v[170:173], v[202:205], v[96:99]
	v_mfma_f32_16x16x32_bf16 v[76:79], v[178:181], v[202:205], v[76:79]
	v_mfma_f32_16x16x32_bf16 v[88:91], v[170:173], v[210:213], v[88:91]
	v_mfma_f32_16x16x32_bf16 v[84:87], v[178:181], v[210:213], v[84:87]
	v_mfma_f32_16x16x32_bf16 v[116:119], v[174:177], v[190:193], v[116:119]
	v_mfma_f32_16x16x32_bf16 v[112:115], v[182:185], v[190:193], v[112:115]
	v_mfma_f32_16x16x32_bf16 v[104:107], v[174:177], v[198:201], v[104:107]
	v_mfma_f32_16x16x32_bf16 v[52:55], v[182:185], v[198:201], v[52:55]
	v_mfma_f32_16x16x32_bf16 v[96:99], v[174:177], v[206:209], v[96:99]
	v_mfma_f32_16x16x32_bf16 v[76:79], v[182:185], v[206:209], v[76:79]
	v_mfma_f32_16x16x32_bf16 v[88:91], v[174:177], v[214:217], v[88:91]
	v_mfma_f32_16x16x32_bf16 v[84:87], v[182:185], v[214:217], v[84:87]
	s_barrier
	s_add_i32 s40, s66, s33
	s_mov_b32 m0, s40
	ds_read_b128 v[186:189], v155 offset:49152
	ds_read_b128 v[190:193], v155 offset:50176
	ds_read_b128 v[194:197], v155 offset:51200
	ds_read_b128 v[198:201], v155 offset:52224
	ds_read_b128 v[202:205], v155 offset:53248
	ds_read_b128 v[206:209], v155 offset:54272
	ds_read_b128 v[210:213], v155 offset:55296
	ds_read_b128 v[214:217], v155 offset:56320
	global_load_lds_dwordx4 v130, s[98:99]
	s_add_i32 m0, s40, 0x2000
	s_add_u32 s38, s38, 0x100080
	s_addc_u32 s39, s39, 0
	s_add_i32 s40, s67, s33
	global_load_lds_dwordx4 v134, s[98:99]
	s_mov_b32 m0, s40
	s_nop 0
	global_load_lds_dwordx4 v130, s[38:39]
	s_add_i32 m0, s40, 0x2000
	s_nop 0
	global_load_lds_dwordx4 v134, s[38:39]
	s_mov_b32 m0, s56
	s_nop 0
	global_load_lds_dwordx4 v128, s[100:101]
	s_mov_b32 m0, s57
	s_nop 0
	global_load_lds_dwordx4 v132, s[100:101]
	s_add_i32 s65, s65, 2
	s_add_u32 s34, s34, 0x100
	s_addc_u32 s35, s35, 0
	s_add_u32 s63, s63, 0x100
	s_addc_u32 s64, s64, 0
	s_cmp_gt_u32 s65, 61
	s_waitcnt vmcnt(8) lgkmcnt(0)
	s_barrier
	v_mfma_f32_16x16x32_bf16 v[72:75], v[144:147], v[186:189], v[72:75]
	v_mfma_f32_16x16x32_bf16 v[68:71], v[162:165], v[186:189], v[68:71]
	v_mfma_f32_16x16x32_bf16 v[44:47], v[144:147], v[194:197], v[44:47]
	v_mfma_f32_16x16x32_bf16 v[40:43], v[162:165], v[194:197], v[40:43]
	v_mfma_f32_16x16x32_bf16 v[28:31], v[144:147], v[202:205], v[28:31]
	v_mfma_f32_16x16x32_bf16 v[24:27], v[162:165], v[202:205], v[24:27]
	v_mfma_f32_16x16x32_bf16 v[12:15], v[144:147], v[210:213], v[12:15]
	v_mfma_f32_16x16x32_bf16 v[8:11], v[162:165], v[210:213], v[8:11]
	v_mfma_f32_16x16x32_bf16 v[72:75], v[158:161], v[190:193], v[72:75]
	v_mfma_f32_16x16x32_bf16 v[68:71], v[166:169], v[190:193], v[68:71]
	v_mfma_f32_16x16x32_bf16 v[44:47], v[158:161], v[198:201], v[44:47]
	v_mfma_f32_16x16x32_bf16 v[40:43], v[166:169], v[198:201], v[40:43]
	v_mfma_f32_16x16x32_bf16 v[28:31], v[158:161], v[206:209], v[28:31]
	v_mfma_f32_16x16x32_bf16 v[24:27], v[166:169], v[206:209], v[24:27]
	v_mfma_f32_16x16x32_bf16 v[12:15], v[158:161], v[214:217], v[12:15]
	v_mfma_f32_16x16x32_bf16 v[8:11], v[166:169], v[214:217], v[8:11]
	v_mfma_f32_16x16x32_bf16 v[60:63], v[170:173], v[186:189], v[60:63]
	v_mfma_f32_16x16x32_bf16 v[56:59], v[178:181], v[186:189], v[56:59]
	v_mfma_f32_16x16x32_bf16 v[36:39], v[170:173], v[194:197], v[36:39]
	v_mfma_f32_16x16x32_bf16 v[32:35], v[178:181], v[194:197], v[32:35]
	v_mfma_f32_16x16x32_bf16 v[20:23], v[170:173], v[202:205], v[20:23]
	v_mfma_f32_16x16x32_bf16 v[16:19], v[178:181], v[202:205], v[16:19]
	v_mfma_f32_16x16x32_bf16 v[4:7], v[170:173], v[210:213], v[4:7]
	v_mfma_f32_16x16x32_bf16 v[0:3], v[178:181], v[210:213], v[0:3]
	v_mfma_f32_16x16x32_bf16 v[60:63], v[174:177], v[190:193], v[60:63]
	v_mfma_f32_16x16x32_bf16 v[56:59], v[182:185], v[190:193], v[56:59]
	v_mfma_f32_16x16x32_bf16 v[36:39], v[174:177], v[198:201], v[36:39]
	v_mfma_f32_16x16x32_bf16 v[32:35], v[182:185], v[198:201], v[32:35]
	v_mfma_f32_16x16x32_bf16 v[20:23], v[174:177], v[206:209], v[20:23]
	v_mfma_f32_16x16x32_bf16 v[16:19], v[182:185], v[206:209], v[16:19]
	v_mfma_f32_16x16x32_bf16 v[4:7], v[174:177], v[214:217], v[4:7]
	v_mfma_f32_16x16x32_bf16 v[0:3], v[182:185], v[214:217], v[0:3]
	s_barrier
	s_cbranch_scc0 .LBB0_1198
	s_and_b64 vcc, exec, s[16:17]
	s_cbranch_vccz .LBB0_1201
	s_barrier

; #define PG8_STAGE(bufoff, gbase, voff) do { _Pragma("unroll") for (int _i = 0; _i < 2; ++_i) \
;         __builtin_amdgcn_global_load_lds((const unsigned*)((const char*)(gbase) + (voff)[_i]), (PG8_LAS unsigned*)(lds + (bufoff) + ldsw + _i * 8192), 16, 0, 0); } while (0)
; #define PG8_LDA(dst, b, h) do { _Pragma("unroll") for (int m = 0; m < 4; ++m) _Pragma("unroll") for (int k = 0; k < 2; ++k) dst[m][k] = *(const PG8_LAS bf16x8*)(lds + PG8_SA(b, h) + aoff + m * 2048 + k * 1024); } while (0)
; #define PG8_LDB(dst, b, h) do { _Pragma("unroll") for (int n = 0; n < 2; ++n) _Pragma("unroll") for (int k = 0; k < 2; ++k) dst[n][k] = *(const PG8_LAS bf16x8*)(lds + PG8_SB(b, h) + boff + n * 2048 + k * 1024); } while (0)
; #define PG8_WAIT_V(n) asm volatile("s_waitcnt vmcnt(" #n ")" ::: "memory")
; #define PG8_WAIT_L(n) asm volatile("s_waitcnt lgkmcnt(" #n ")" ::: "memory")
; #define PG8_BAR __builtin_amdgcn_s_barrier()
; #define PG8_SCHED __builtin_amdgcn_sched_barrier(0)
; template <class Epi, class Sched, bool ALIGN_EPI = false, bool SP2 = false>
; __device__ __forceinline__ void gemm_phase(PG8_LAS unsigned char* lds, const Gemm g, const Sched& S, const Epi& E) {
;     ...
;         const char* nA = has_next ? (const char*)g.A + (size_t)nxt.pm * tstep : cA; const char* nB = has_next ? (const char*)g.Bt + (size_t)nxt.pn * tstep : cB;
;         for (int t = 0; t < nt; t += 2) {
;             const bool last = (t == nt - 2);
;             const char* a1 = cA + (size_t)(t + 1) * kstepA;
;             const char* a2 = last ? nA : cA + (size_t)(t + 2) * kstepA; const char* b2 = last ? nB : cB + (size_t)(t + 2) * kstep;
;             const char* a3 = a2 + kstepA; const char* b3 = b2 + kstep;
;             if (last && has_next) S.a_ready(nxt);
;             if constexpr (SP2) {
;             PG8_LDB(B0, 0, 0); PG8_LDB(B1, 0, 1); PG8_SCHED; PG8_LDA(At, 0, 0); PG8_STAGE(PG8_SA(1, 1), a1 + hstepA, voffA);
;             PG8_WAIT_V(8); PG8_WAIT_L(0); PG8_BAR; PG8_MMA(0, 0, At, B0); PG8_MMA(0, 1, At, B1); PG8_BAR; PG8_SCHED;
;             PG8_LDA(At, 0, 1); PG8_STAGE(PG8_SB(0, 0), b2, voffB); PG8_STAGE(PG8_SB(0, 1), b2 + hstep, voffB); PG8_STAGE(PG8_SA(0, 0), a2, voffA);
;             PG8_WAIT_V(8); PG8_WAIT_L(0); PG8_BAR; PG8_MMA(1, 0, At, B0); PG8_MMA(1, 1, At, B1); PG8_BAR; PG8_SCHED;
.LBB0_1310:
	ds_read_b128 v[128:131], v236
	ds_read_b128 v[132:135], v236 offset:1024
	ds_read_b128 v[136:139], v236 offset:2048
	ds_read_b128 v[140:143], v236 offset:3072
	ds_read_b128 v[144:147], v237
	ds_read_b128 v[148:151], v237 offset:1024
	ds_read_b128 v[152:155], v237 offset:2048
	ds_read_b128 v[156:159], v237 offset:3072
	s_add_u32 s96, s94, 0x100
	s_addc_u32 s97, s95, 0
	s_cmp_eq_u32 s71, 60
	s_cselect_b32 s7, s41, s97
	s_cselect_b32 s6, s52, s96
	s_cselect_b32 vcc_hi, s39, s70
	s_cselect_b32 vcc_lo, s53, s69
	v_lshl_add_u64 v[164:165], s[94:95], 0, v[178:179]
	s_add_i32 m0, s56, 0xc000
	ds_read_b128 v[160:163], v238
	ds_read_b128 v[186:189], v238 offset:1024
	ds_read_b128 v[190:193], v238 offset:2048
	ds_read_b128 v[194:197], v238 offset:3072
	ds_read_b128 v[198:201], v238 offset:4096
	ds_read_b128 v[202:205], v238 offset:5120
	ds_read_b128 v[206:209], v238 offset:6144
	ds_read_b128 v[210:213], v238 offset:7168
	global_load_lds_dwordx4 v[164:165], off
	v_lshl_add_u64 v[164:165], s[94:95], 0, v[180:181]
	s_add_i32 m0, s56, 0xe000
	s_nop 0
	global_load_lds_dwordx4 v[164:165], off
	s_waitcnt vmcnt(8) lgkmcnt(0)
	s_barrier
	v_mfma_f32_16x16x32_bf16 v[124:127], v[128:131], v[160:163], v[124:127]
	v_mfma_f32_16x16x32_bf16 v[120:123], v[136:139], v[160:163], v[120:123]
	v_mfma_f32_16x16x32_bf16 v[108:111], v[128:131], v[190:193], v[108:111]
	v_mfma_f32_16x16x32_bf16 v[104:107], v[136:139], v[190:193], v[104:107]
	v_mfma_f32_16x16x32_bf16 v[92:95], v[128:131], v[198:201], v[92:95]
	v_mfma_f32_16x16x32_bf16 v[88:91], v[136:139], v[198:201], v[88:91]
	v_mfma_f32_16x16x32_bf16 v[76:79], v[128:131], v[206:209], v[76:79]
	v_mfma_f32_16x16x32_bf16 v[72:75], v[136:139], v[206:209], v[72:75]
	v_mfma_f32_16x16x32_bf16 v[124:127], v[132:135], v[186:189], v[124:127]
	v_mfma_f32_16x16x32_bf16 v[120:123], v[140:143], v[186:189], v[120:123]
	v_mfma_f32_16x16x32_bf16 v[108:111], v[132:135], v[194:197], v[108:111]
	v_mfma_f32_16x16x32_bf16 v[104:107], v[140:143], v[194:197], v[104:107]
	v_mfma_f32_16x16x32_bf16 v[92:95], v[132:135], v[202:205], v[92:95]
	v_mfma_f32_16x16x32_bf16 v[88:91], v[140:143], v[202:205], v[88:91]
	v_mfma_f32_16x16x32_bf16 v[76:79], v[132:135], v[210:213], v[76:79]
	v_mfma_f32_16x16x32_bf16 v[72:75], v[140:143], v[210:213], v[72:75]
	v_mfma_f32_16x16x32_bf16 v[116:119], v[144:147], v[160:163], v[116:119]
	v_mfma_f32_16x16x32_bf16 v[112:115], v[152:155], v[160:163], v[112:115]
	v_mfma_f32_16x16x32_bf16 v[100:103], v[144:147], v[190:193], v[100:103]
	v_mfma_f32_16x16x32_bf16 v[96:99], v[152:155], v[190:193], v[96:99]
	v_mfma_f32_16x16x32_bf16 v[84:87], v[144:147], v[198:201], v[84:87]
	v_mfma_f32_16x16x32_bf16 v[80:83], v[152:155], v[198:201], v[80:83]
	v_mfma_f32_16x16x32_bf16 v[68:71], v[144:147], v[206:209], v[68:71]
	v_mfma_f32_16x16x32_bf16 v[64:67], v[152:155], v[206:209], v[64:67]
	v_mfma_f32_16x16x32_bf16 v[116:119], v[148:151], v[186:189], v[116:119]
	v_mfma_f32_16x16x32_bf16 v[112:115], v[156:159], v[186:189], v[112:115]
	v_mfma_f32_16x16x32_bf16 v[100:103], v[148:151], v[194:197], v[100:103]
	v_mfma_f32_16x16x32_bf16 v[96:99], v[156:159], v[194:197], v[96:99]
	v_mfma_f32_16x16x32_bf16 v[84:87], v[148:151], v[202:205], v[84:87]
	v_mfma_f32_16x16x32_bf16 v[80:83], v[156:159], v[202:205], v[80:83]
	v_mfma_f32_16x16x32_bf16 v[68:71], v[148:151], v[210:213], v[68:71]
	v_mfma_f32_16x16x32_bf16 v[64:67], v[156:159], v[210:213], v[64:67]
	s_barrier
	s_add_u32 s98, vcc_lo, s10
	s_addc_u32 s99, vcc_hi, s11
	s_add_u32 s100, s6, s10
	s_addc_u32 s101, s7, s11
	s_add_i32 s72, s65, s55
	s_mov_b32 m0, s72
	ds_read_b128 v[160:163], v238 offset:16384
	ds_read_b128 v[186:189], v238 offset:17408
	ds_read_b128 v[190:193], v238 offset:18432
	ds_read_b128 v[194:197], v238 offset:19456
	ds_read_b128 v[198:201], v238 offset:20480
	ds_read_b128 v[202:205], v238 offset:21504
	ds_read_b128 v[206:209], v238 offset:22528
	ds_read_b128 v[210:213], v238 offset:23552
	global_load_lds_dwordx4 v168, vcc
	s_add_i32 m0, s72, 0x2000
	s_add_u32 s72, vcc_lo, 0x100000
	s_addc_u32 s73, vcc_hi, 0
	s_add_i32 s74, s66, s55
	global_load_lds_dwordx4 v172, vcc
	s_mov_b32 m0, s74
	s_nop 0
	global_load_lds_dwordx4 v168, s[72:73]
	s_add_i32 m0, s74, 0x2000
	s_nop 0
	global_load_lds_dwordx4 v172, s[72:73]
	s_mov_b32 m0, s56
	s_nop 0
	global_load_lds_dwordx4 v166, s[6:7]
	s_mov_b32 m0, s57
	s_nop 0
	global_load_lds_dwordx4 v170, s[6:7]
	s_waitcnt vmcnt(8) lgkmcnt(0)
	s_barrier
	v_mfma_f32_16x16x32_bf16 v[60:63], v[128:131], v[160:163], v[60:63]
	v_mfma_f32_16x16x32_bf16 v[56:59], v[136:139], v[160:163], v[56:59]
	v_mfma_f32_16x16x32_bf16 v[44:47], v[128:131], v[190:193], v[44:47]
	v_mfma_f32_16x16x32_bf16 v[40:43], v[136:139], v[190:193], v[40:43]
	v_mfma_f32_16x16x32_bf16 v[28:31], v[128:131], v[198:201], v[28:31]
	v_mfma_f32_16x16x32_bf16 v[24:27], v[136:139], v[198:201], v[24:27]
	v_mfma_f32_16x16x32_bf16 v[12:15], v[128:131], v[206:209], v[12:15]
	v_mfma_f32_16x16x32_bf16 v[8:11], v[136:139], v[206:209], v[8:11]
	v_mfma_f32_16x16x32_bf16 v[60:63], v[132:135], v[186:189], v[60:63]
	v_mfma_f32_16x16x32_bf16 v[56:59], v[140:143], v[186:189], v[56:59]
	v_mfma_f32_16x16x32_bf16 v[44:47], v[132:135], v[194:197], v[44:47]
	v_mfma_f32_16x16x32_bf16 v[40:43], v[140:143], v[194:197], v[40:43]
	v_mfma_f32_16x16x32_bf16 v[28:31], v[132:135], v[202:205], v[28:31]
	v_mfma_f32_16x16x32_bf16 v[24:27], v[140:143], v[202:205], v[24:27]
	v_mfma_f32_16x16x32_bf16 v[12:15], v[132:135], v[210:213], v[12:15]
	v_mfma_f32_16x16x32_bf16 v[8:11], v[140:143], v[210:213], v[8:11]
	v_mfma_f32_16x16x32_bf16 v[52:55], v[144:147], v[160:163], v[52:55]
	v_mfma_f32_16x16x32_bf16 v[48:51], v[152:155], v[160:163], v[48:51]
	v_mfma_f32_16x16x32_bf16 v[36:39], v[144:147], v[190:193], v[36:39]
	v_mfma_f32_16x16x32_bf16 v[32:35], v[152:155], v[190:193], v[32:35]
	v_mfma_f32_16x16x32_bf16 v[20:23], v[144:147], v[198:201], v[20:23]
	v_mfma_f32_16x16x32_bf16 v[16:19], v[152:155], v[198:201], v[16:19]
	v_mfma_f32_16x16x32_bf16 v[4:7], v[144:147], v[206:209], v[4:7]
	v_mfma_f32_16x16x32_bf16 v[0:3], v[152:155], v[206:209], v[0:3]
	v_mfma_f32_16x16x32_bf16 v[52:55], v[148:151], v[186:189], v[52:55]
	v_mfma_f32_16x16x32_bf16 v[48:51], v[156:159], v[186:189], v[48:51]
	v_mfma_f32_16x16x32_bf16 v[36:39], v[148:151], v[194:197], v[36:39]
	v_mfma_f32_16x16x32_bf16 v[32:35], v[156:159], v[194:197], v[32:35]
	v_mfma_f32_16x16x32_bf16 v[20:23], v[148:151], v[202:205], v[20:23]
	v_mfma_f32_16x16x32_bf16 v[16:19], v[156:159], v[202:205], v[16:19]
	v_mfma_f32_16x16x32_bf16 v[4:7], v[148:151], v[210:213], v[4:7]
	v_mfma_f32_16x16x32_bf16 v[0:3], v[156:159], v[210:213], v[0:3]
	s_barrier
; #define PG8_STAGE(bufoff, gbase, voff) do { _Pragma("unroll") for (int _i = 0; _i < 2; ++_i) \
;         __builtin_amdgcn_global_load_lds((const unsigned*)((const char*)(gbase) + (voff)[_i]), (PG8_LAS unsigned*)(lds + (bufoff) + ldsw + _i * 8192), 16, 0, 0); } while (0)
; #define PG8_LDA(dst, b, h) do { _Pragma("unroll") for (int m = 0; m < 4; ++m) _Pragma("unroll") for (int k = 0; k < 2; ++k) dst[m][k] = *(const PG8_LAS bf16x8*)(lds + PG8_SA(b, h) + aoff + m * 2048 + k * 1024); } while (0)
; #define PG8_LDB(dst, b, h) do { _Pragma("unroll") for (int n = 0; n < 2; ++n) _Pragma("unroll") for (int k = 0; k < 2; ++k) dst[n][k] = *(const PG8_LAS bf16x8*)(lds + PG8_SB(b, h) + boff + n * 2048 + k * 1024); } while (0)
; #define PG8_MMA(ai, bj, At, Bt) do { __builtin_amdgcn_s_setprio(1); _Pragma("unroll") for (int m = 0; m < 4; ++m) _Pragma("unroll") for (int n = 0; n < 2; ++n) _Pragma("unroll") for (int k = 0; k < 2; ++k) \
;         acc[ai][bj][m][n] = __builtin_amdgcn_mfma_f32_16x16x32_bf16(Bt[n][k], At[m][k], acc[ai][bj][m][n], 0, 0, 0); __builtin_amdgcn_s_setprio(0); } while (0)
; #define PG8_WAIT_V(n) asm volatile("s_waitcnt vmcnt(" #n ")" ::: "memory")
; #define PG8_WAIT_L(n) asm volatile("s_waitcnt lgkmcnt(" #n ")" ::: "memory")
; #define PG8_BAR __builtin_amdgcn_s_barrier()
; template <class Epi, class Sched, bool ALIGN_EPI = false, bool SP2 = false>
; __device__ __forceinline__ void gemm_phase(PG8_LAS unsigned char* lds, const Gemm g, const Sched& S, const Epi& E) {
;     ...
;         for (int t = 0; t < nt; t += 2) {
;             const bool last = (t == nt - 2);
;             const char* a1 = cA + (size_t)(t + 1) * kstepA;
;             const char* a2 = last ? nA : cA + (size_t)(t + 2) * kstepA; const char* b2 = last ? nB : cB + (size_t)(t + 2) * kstep;
;             const char* a3 = a2 + kstepA; const char* b3 = b2 + kstep;
;     ...
;             PG8_LDB(B0, 1, 0); PG8_LDB(B1, 1, 1); PG8_SCHED; PG8_LDA(At, 1, 0); PG8_STAGE(PG8_SA(0, 1), a2 + hstepA, voffA);
;             PG8_WAIT_V(8); PG8_WAIT_L(0); PG8_BAR; PG8_MMA(0, 0, At, B0); PG8_MMA(0, 1, At, B1); PG8_BAR; PG8_SCHED;
;             PG8_LDA(At, 1, 1); PG8_STAGE(PG8_SB(1, 0), b3, voffB); PG8_STAGE(PG8_SB(1, 1), b3 + hstep, voffB); PG8_STAGE(PG8_SA(1, 0), a3, voffA);
;             PG8_WAIT_V(8); PG8_WAIT_L(0); PG8_BAR; PG8_MMA(1, 0, At, B0); PG8_MMA(1, 1, At, B1); PG8_BAR; PG8_SCHED;
	s_add_i32 s72, 0, 0x18000
	s_add_i32 s73, 0, 0x1c000
	ds_read_b128 v[128:131], v214
	ds_read_b128 v[132:135], v214 offset:1024
	ds_read_b128 v[136:139], v214 offset:2048
	ds_read_b128 v[140:143], v214 offset:3072
	ds_read_b128 v[144:147], v215
	ds_read_b128 v[148:151], v215 offset:1024
	ds_read_b128 v[152:155], v215 offset:2048
	ds_read_b128 v[156:159], v215 offset:3072
	s_add_u32 s6, s6, 0x100000
	s_addc_u32 s7, s7, 0
	s_mov_b32 m0, s58
	ds_read_b128 v[160:163], v238 offset:32768
	ds_read_b128 v[186:189], v238 offset:33792
	ds_read_b128 v[190:193], v238 offset:34816
	ds_read_b128 v[194:197], v238 offset:35840
	ds_read_b128 v[198:201], v238 offset:36864
	ds_read_b128 v[202:205], v238 offset:37888
	ds_read_b128 v[206:209], v238 offset:38912
	ds_read_b128 v[210:213], v238 offset:39936
	global_load_lds_dwordx4 v166, s[6:7]
	s_mov_b32 m0, s59
	s_nop 0
	global_load_lds_dwordx4 v170, s[6:7]
	s_waitcnt vmcnt(8) lgkmcnt(0)
	s_barrier
	v_mfma_f32_16x16x32_bf16 v[124:127], v[128:131], v[160:163], v[124:127]
	v_mfma_f32_16x16x32_bf16 v[120:123], v[136:139], v[160:163], v[120:123]
	v_mfma_f32_16x16x32_bf16 v[108:111], v[128:131], v[190:193], v[108:111]
	v_mfma_f32_16x16x32_bf16 v[104:107], v[136:139], v[190:193], v[104:107]
	v_mfma_f32_16x16x32_bf16 v[92:95], v[128:131], v[198:201], v[92:95]
	v_mfma_f32_16x16x32_bf16 v[88:91], v[136:139], v[198:201], v[88:91]
	v_mfma_f32_16x16x32_bf16 v[76:79], v[128:131], v[206:209], v[76:79]
	v_mfma_f32_16x16x32_bf16 v[72:75], v[136:139], v[206:209], v[72:75]
	v_mfma_f32_16x16x32_bf16 v[124:127], v[132:135], v[186:189], v[124:127]
	v_mfma_f32_16x16x32_bf16 v[120:123], v[140:143], v[186:189], v[120:123]
	v_mfma_f32_16x16x32_bf16 v[108:111], v[132:135], v[194:197], v[108:111]
	v_mfma_f32_16x16x32_bf16 v[104:107], v[140:143], v[194:197], v[104:107]
	v_mfma_f32_16x16x32_bf16 v[92:95], v[132:135], v[202:205], v[92:95]
	v_mfma_f32_16x16x32_bf16 v[88:91], v[140:143], v[202:205], v[88:91]
	v_mfma_f32_16x16x32_bf16 v[76:79], v[132:135], v[210:213], v[76:79]
	v_mfma_f32_16x16x32_bf16 v[72:75], v[140:143], v[210:213], v[72:75]
	v_mfma_f32_16x16x32_bf16 v[116:119], v[144:147], v[160:163], v[116:119]
	v_mfma_f32_16x16x32_bf16 v[112:115], v[152:155], v[160:163], v[112:115]
	v_mfma_f32_16x16x32_bf16 v[100:103], v[144:147], v[190:193], v[100:103]
	v_mfma_f32_16x16x32_bf16 v[96:99], v[152:155], v[190:193], v[96:99]
	v_mfma_f32_16x16x32_bf16 v[84:87], v[144:147], v[198:201], v[84:87]
	v_mfma_f32_16x16x32_bf16 v[80:83], v[152:155], v[198:201], v[80:83]
	v_mfma_f32_16x16x32_bf16 v[68:71], v[144:147], v[206:209], v[68:71]
	v_mfma_f32_16x16x32_bf16 v[64:67], v[152:155], v[206:209], v[64:67]
	v_mfma_f32_16x16x32_bf16 v[116:119], v[148:151], v[186:189], v[116:119]
	v_mfma_f32_16x16x32_bf16 v[112:115], v[156:159], v[186:189], v[112:115]
	v_mfma_f32_16x16x32_bf16 v[100:103], v[148:151], v[194:197], v[100:103]
	v_mfma_f32_16x16x32_bf16 v[96:99], v[156:159], v[194:197], v[96:99]
	v_mfma_f32_16x16x32_bf16 v[84:87], v[148:151], v[202:205], v[84:87]
	v_mfma_f32_16x16x32_bf16 v[80:83], v[156:159], v[202:205], v[80:83]
	v_mfma_f32_16x16x32_bf16 v[68:71], v[148:151], v[210:213], v[68:71]
	v_mfma_f32_16x16x32_bf16 v[64:67], v[156:159], v[210:213], v[64:67]
	s_barrier
	s_add_i32 s6, s72, s55
	s_mov_b32 m0, s6
	ds_read_b128 v[160:163], v238 offset:49152
	ds_read_b128 v[186:189], v238 offset:50176
	ds_read_b128 v[190:193], v238 offset:51200
	ds_read_b128 v[194:197], v238 offset:52224
	ds_read_b128 v[198:201], v238 offset:53248
	ds_read_b128 v[202:205], v238 offset:54272
	ds_read_b128 v[206:209], v238 offset:55296
	ds_read_b128 v[210:213], v238 offset:56320
	global_load_lds_dwordx4 v168, s[98:99]
	s_add_i32 m0, s6, 0x2000
	s_add_u32 s6, vcc_lo, 0x100080
	s_addc_u32 s7, vcc_hi, 0
	s_add_i32 s72, s73, s55
	global_load_lds_dwordx4 v172, s[98:99]
	s_mov_b32 m0, s72
	s_nop 0
	global_load_lds_dwordx4 v168, s[6:7]
	s_add_i32 m0, s72, 0x2000
	s_nop 0
	global_load_lds_dwordx4 v172, s[6:7]
	s_mov_b32 m0, s63
	s_nop 0
	global_load_lds_dwordx4 v166, s[100:101]
	s_mov_b32 m0, s64
	s_nop 0
	global_load_lds_dwordx4 v170, s[100:101]
	s_add_i32 s71, s71, 2
	s_add_u32 s69, s69, 0x100
	s_addc_u32 s70, s70, 0
	s_cmp_gt_u32 s71, 61
	s_mov_b64 s[94:95], s[96:97]
	s_waitcnt vmcnt(8) lgkmcnt(0)
	s_barrier
	v_mfma_f32_16x16x32_bf16 v[60:63], v[128:131], v[160:163], v[60:63]
	v_mfma_f32_16x16x32_bf16 v[56:59], v[136:139], v[160:163], v[56:59]
	v_mfma_f32_16x16x32_bf16 v[44:47], v[128:131], v[190:193], v[44:47]
	v_mfma_f32_16x16x32_bf16 v[40:43], v[136:139], v[190:193], v[40:43]
	v_mfma_f32_16x16x32_bf16 v[28:31], v[128:131], v[198:201], v[28:31]
	v_mfma_f32_16x16x32_bf16 v[24:27], v[136:139], v[198:201], v[24:27]
	v_mfma_f32_16x16x32_bf16 v[12:15], v[128:131], v[206:209], v[12:15]
	v_mfma_f32_16x16x32_bf16 v[8:11], v[136:139], v[206:209], v[8:11]
	v_mfma_f32_16x16x32_bf16 v[60:63], v[132:135], v[186:189], v[60:63]
	v_mfma_f32_16x16x32_bf16 v[56:59], v[140:143], v[186:189], v[56:59]
	v_mfma_f32_16x16x32_bf16 v[44:47], v[132:135], v[194:197], v[44:47]
	v_mfma_f32_16x16x32_bf16 v[40:43], v[140:143], v[194:197], v[40:43]
	v_mfma_f32_16x16x32_bf16 v[28:31], v[132:135], v[202:205], v[28:31]
	v_mfma_f32_16x16x32_bf16 v[24:27], v[140:143], v[202:205], v[24:27]
	v_mfma_f32_16x16x32_bf16 v[12:15], v[132:135], v[210:213], v[12:15]
	v_mfma_f32_16x16x32_bf16 v[8:11], v[140:143], v[210:213], v[8:11]
	v_mfma_f32_16x16x32_bf16 v[52:55], v[144:147], v[160:163], v[52:55]
	v_mfma_f32_16x16x32_bf16 v[48:51], v[152:155], v[160:163], v[48:51]
	v_mfma_f32_16x16x32_bf16 v[36:39], v[144:147], v[190:193], v[36:39]
	v_mfma_f32_16x16x32_bf16 v[32:35], v[152:155], v[190:193], v[32:35]
	v_mfma_f32_16x16x32_bf16 v[20:23], v[144:147], v[198:201], v[20:23]
	v_mfma_f32_16x16x32_bf16 v[16:19], v[152:155], v[198:201], v[16:19]
	v_mfma_f32_16x16x32_bf16 v[4:7], v[144:147], v[206:209], v[4:7]
	v_mfma_f32_16x16x32_bf16 v[0:3], v[152:155], v[206:209], v[0:3]
	v_mfma_f32_16x16x32_bf16 v[52:55], v[148:151], v[186:189], v[52:55]
	v_mfma_f32_16x16x32_bf16 v[48:51], v[156:159], v[186:189], v[48:51]
	v_mfma_f32_16x16x32_bf16 v[36:39], v[148:151], v[194:197], v[36:39]
	v_mfma_f32_16x16x32_bf16 v[32:35], v[156:159], v[194:197], v[32:35]
	v_mfma_f32_16x16x32_bf16 v[20:23], v[148:151], v[202:205], v[20:23]
	v_mfma_f32_16x16x32_bf16 v[16:19], v[156:159], v[202:205], v[16:19]
	v_mfma_f32_16x16x32_bf16 v[4:7], v[148:151], v[210:213], v[4:7]
	v_mfma_f32_16x16x32_bf16 v[0:3], v[156:159], v[210:213], v[0:3]
	s_barrier
	s_cbranch_scc0 .LBB0_1310
	s_and_b64 vcc, exec, s[12:13]
	s_cbranch_vccz .LBB0_1313
	s_barrier

; #define PG8_STAGE(bufoff, gbase, voff) do { _Pragma("unroll") for (int _i = 0; _i < 2; ++_i) \
;         __builtin_amdgcn_global_load_lds((const unsigned*)((const char*)(gbase) + (voff)[_i]), (PG8_LAS unsigned*)(lds + (bufoff) + ldsw + _i * 8192), 16, 0, 0); } while (0)
; #define PG8_LDA(dst, b, h) do { _Pragma("unroll") for (int m = 0; m < 4; ++m) _Pragma("unroll") for (int k = 0; k < 2; ++k) dst[m][k] = *(const PG8_LAS bf16x8*)(lds + PG8_SA(b, h) + aoff + m * 2048 + k * 1024); } while (0)
; #define PG8_LDB(dst, b, h) do { _Pragma("unroll") for (int n = 0; n < 2; ++n) _Pragma("unroll") for (int k = 0; k < 2; ++k) dst[n][k] = *(const PG8_LAS bf16x8*)(lds + PG8_SB(b, h) + boff + n * 2048 + k * 1024); } while (0)
; #define PG8_WAIT_V(n) asm volatile("s_waitcnt vmcnt(" #n ")" ::: "memory")
; #define PG8_WAIT_L(n) asm volatile("s_waitcnt lgkmcnt(" #n ")" ::: "memory")
; #define PG8_BAR __builtin_amdgcn_s_barrier()
; #define PG8_SCHED __builtin_amdgcn_sched_barrier(0)
; template <class Epi, class Sched, bool ALIGN_EPI = false, bool SP2 = false>
; __device__ __forceinline__ void gemm_phase(PG8_LAS unsigned char* lds, const Gemm g, const Sched& S, const Epi& E) {
;     ...
;         const char* nA = has_next ? (const char*)g.A + (size_t)nxt.pm * tstep : cA; const char* nB = has_next ? (const char*)g.Bt + (size_t)nxt.pn * tstep : cB;
;         for (int t = 0; t < nt; t += 2) {
;             const bool last = (t == nt - 2);
;             const char* a1 = cA + (size_t)(t + 1) * kstepA;
;             const char* a2 = last ? nA : cA + (size_t)(t + 2) * kstepA; const char* b2 = last ? nB : cB + (size_t)(t + 2) * kstep;
;             const char* a3 = a2 + kstepA; const char* b3 = b2 + kstep;
;             if (last && has_next) S.a_ready(nxt);
;             if constexpr (SP2) {
;             PG8_LDB(B0, 0, 0); PG8_LDB(B1, 0, 1); PG8_SCHED; PG8_LDA(At, 0, 0); PG8_STAGE(PG8_SA(1, 1), a1 + hstepA, voffA);
;             PG8_WAIT_V(8); PG8_WAIT_L(0); PG8_BAR; PG8_MMA(0, 0, At, B0); PG8_MMA(0, 1, At, B1); PG8_BAR; PG8_SCHED;
;             PG8_LDA(At, 0, 1); PG8_STAGE(PG8_SB(0, 0), b2, voffB); PG8_STAGE(PG8_SB(0, 1), b2 + hstep, voffB); PG8_STAGE(PG8_SA(0, 0), a2, voffA);
;             PG8_WAIT_V(8); PG8_WAIT_L(0); PG8_BAR; PG8_MMA(1, 0, At, B0); PG8_MMA(1, 1, At, B1); PG8_BAR; PG8_SCHED;
.LBB0_1515:
	ds_read_b128 v[144:147], v153
	ds_read_b128 v[158:161], v153 offset:1024
	ds_read_b128 v[162:165], v153 offset:2048
	ds_read_b128 v[166:169], v153 offset:3072
	ds_read_b128 v[170:173], v154
	ds_read_b128 v[174:177], v154 offset:1024
	ds_read_b128 v[178:181], v154 offset:2048
	ds_read_b128 v[182:185], v154 offset:3072
	s_add_u32 s24, s22, 0x4000
	s_addc_u32 s25, s23, 0
	s_cmpk_eq_i32 s63, 0xa8
	s_cselect_b32 s30, s6, s24
	s_cselect_b32 s31, s7, s25
	s_cselect_b32 s26, s20, s61
	s_cselect_b32 s27, s21, s62
	s_add_u32 s24, s30, 0x8000
	s_addc_u32 s25, s31, 0
	s_add_i32 m0, s34, 0xc000
	ds_read_b128 v[186:189], v155
	ds_read_b128 v[190:193], v155 offset:1024
	ds_read_b128 v[194:197], v155 offset:2048
	ds_read_b128 v[198:201], v155 offset:3072
	ds_read_b128 v[202:205], v155 offset:4096
	ds_read_b128 v[206:209], v155 offset:5120
	ds_read_b128 v[210:213], v155 offset:6144
	ds_read_b128 v[214:217], v155 offset:7168
	global_load_lds_dwordx4 v136, s[22:23]
	s_add_i32 m0, s34, 0xe000
	s_nop 0
	global_load_lds_dwordx4 v138, s[22:23]
	s_waitcnt vmcnt(8) lgkmcnt(0)
	s_barrier
	v_mfma_f32_16x16x32_bf16 v[124:127], v[144:147], v[186:189], v[124:127]
	v_mfma_f32_16x16x32_bf16 v[120:123], v[162:165], v[186:189], v[120:123]
	v_mfma_f32_16x16x32_bf16 v[108:111], v[144:147], v[194:197], v[108:111]
	v_mfma_f32_16x16x32_bf16 v[48:51], v[162:165], v[194:197], v[48:51]
	v_mfma_f32_16x16x32_bf16 v[100:103], v[144:147], v[202:205], v[100:103]
	v_mfma_f32_16x16x32_bf16 v[64:67], v[162:165], v[202:205], v[64:67]
	v_mfma_f32_16x16x32_bf16 v[92:95], v[144:147], v[210:213], v[92:95]
	v_mfma_f32_16x16x32_bf16 v[80:83], v[162:165], v[210:213], v[80:83]
	v_mfma_f32_16x16x32_bf16 v[124:127], v[158:161], v[190:193], v[124:127]
	v_mfma_f32_16x16x32_bf16 v[120:123], v[166:169], v[190:193], v[120:123]
	v_mfma_f32_16x16x32_bf16 v[108:111], v[158:161], v[198:201], v[108:111]
	v_mfma_f32_16x16x32_bf16 v[48:51], v[166:169], v[198:201], v[48:51]
	v_mfma_f32_16x16x32_bf16 v[100:103], v[158:161], v[206:209], v[100:103]
	v_mfma_f32_16x16x32_bf16 v[64:67], v[166:169], v[206:209], v[64:67]
	v_mfma_f32_16x16x32_bf16 v[92:95], v[158:161], v[214:217], v[92:95]
	v_mfma_f32_16x16x32_bf16 v[80:83], v[166:169], v[214:217], v[80:83]
	v_mfma_f32_16x16x32_bf16 v[116:119], v[170:173], v[186:189], v[116:119]
	v_mfma_f32_16x16x32_bf16 v[112:115], v[178:181], v[186:189], v[112:115]
	v_mfma_f32_16x16x32_bf16 v[104:107], v[170:173], v[194:197], v[104:107]
	v_mfma_f32_16x16x32_bf16 v[52:55], v[178:181], v[194:197], v[52:55]
	v_mfma_f32_16x16x32_bf16 v[96:99], v[170:173], v[202:205], v[96:99]
	v_mfma_f32_16x16x32_bf16 v[76:79], v[178:181], v[202:205], v[76:79]
	v_mfma_f32_16x16x32_bf16 v[88:91], v[170:173], v[210:213], v[88:91]
	v_mfma_f32_16x16x32_bf16 v[84:87], v[178:181], v[210:213], v[84:87]
	v_mfma_f32_16x16x32_bf16 v[116:119], v[174:177], v[190:193], v[116:119]
	v_mfma_f32_16x16x32_bf16 v[112:115], v[182:185], v[190:193], v[112:115]
	v_mfma_f32_16x16x32_bf16 v[104:107], v[174:177], v[198:201], v[104:107]
	v_mfma_f32_16x16x32_bf16 v[52:55], v[182:185], v[198:201], v[52:55]
	v_mfma_f32_16x16x32_bf16 v[96:99], v[174:177], v[206:209], v[96:99]
	v_mfma_f32_16x16x32_bf16 v[76:79], v[182:185], v[206:209], v[76:79]
	v_mfma_f32_16x16x32_bf16 v[88:91], v[174:177], v[214:217], v[88:91]
	v_mfma_f32_16x16x32_bf16 v[84:87], v[182:185], v[214:217], v[84:87]
	s_barrier
	s_add_u32 s98, s26, s16
	s_addc_u32 s99, s27, s17
	s_add_i32 s64, s55, s33
	s_mov_b32 m0, s64
	ds_read_b128 v[186:189], v155 offset:16384
	ds_read_b128 v[190:193], v155 offset:17408
	ds_read_b128 v[194:197], v155 offset:18432
	ds_read_b128 v[198:201], v155 offset:19456
	ds_read_b128 v[202:205], v155 offset:20480
	ds_read_b128 v[206:209], v155 offset:21504
	ds_read_b128 v[210:213], v155 offset:22528
	ds_read_b128 v[214:217], v155 offset:23552
	global_load_lds_dwordx4 v130, s[26:27]
	s_add_i32 m0, s64, 0x2000
	s_add_u32 s64, s26, 0x2b0000
	s_addc_u32 s65, s27, 0
	s_add_i32 s66, s56, s33
	global_load_lds_dwordx4 v134, s[26:27]
	s_mov_b32 m0, s66
	s_nop 0
	global_load_lds_dwordx4 v130, s[64:65]
	s_add_i32 m0, s66, 0x2000
	s_nop 0
	global_load_lds_dwordx4 v134, s[64:65]
	s_mov_b32 m0, s34
	s_nop 0
	global_load_lds_dwordx4 v128, s[30:31]
	s_mov_b32 m0, s35
	s_nop 0
	global_load_lds_dwordx4 v132, s[30:31]
	s_waitcnt vmcnt(8) lgkmcnt(0)
	s_barrier
	v_mfma_f32_16x16x32_bf16 v[72:75], v[144:147], v[186:189], v[72:75]
	v_mfma_f32_16x16x32_bf16 v[68:71], v[162:165], v[186:189], v[68:71]
	v_mfma_f32_16x16x32_bf16 v[44:47], v[144:147], v[194:197], v[44:47]
	v_mfma_f32_16x16x32_bf16 v[40:43], v[162:165], v[194:197], v[40:43]
	v_mfma_f32_16x16x32_bf16 v[28:31], v[144:147], v[202:205], v[28:31]
	v_mfma_f32_16x16x32_bf16 v[24:27], v[162:165], v[202:205], v[24:27]
	v_mfma_f32_16x16x32_bf16 v[12:15], v[144:147], v[210:213], v[12:15]
	v_mfma_f32_16x16x32_bf16 v[8:11], v[162:165], v[210:213], v[8:11]
	v_mfma_f32_16x16x32_bf16 v[72:75], v[158:161], v[190:193], v[72:75]
	v_mfma_f32_16x16x32_bf16 v[68:71], v[166:169], v[190:193], v[68:71]
	v_mfma_f32_16x16x32_bf16 v[44:47], v[158:161], v[198:201], v[44:47]
	v_mfma_f32_16x16x32_bf16 v[40:43], v[166:169], v[198:201], v[40:43]
	v_mfma_f32_16x16x32_bf16 v[28:31], v[158:161], v[206:209], v[28:31]
	v_mfma_f32_16x16x32_bf16 v[24:27], v[166:169], v[206:209], v[24:27]
	v_mfma_f32_16x16x32_bf16 v[12:15], v[158:161], v[214:217], v[12:15]
	v_mfma_f32_16x16x32_bf16 v[8:11], v[166:169], v[214:217], v[8:11]
	v_mfma_f32_16x16x32_bf16 v[60:63], v[170:173], v[186:189], v[60:63]
	v_mfma_f32_16x16x32_bf16 v[56:59], v[178:181], v[186:189], v[56:59]
	v_mfma_f32_16x16x32_bf16 v[36:39], v[170:173], v[194:197], v[36:39]
	v_mfma_f32_16x16x32_bf16 v[32:35], v[178:181], v[194:197], v[32:35]
	v_mfma_f32_16x16x32_bf16 v[20:23], v[170:173], v[202:205], v[20:23]
	v_mfma_f32_16x16x32_bf16 v[16:19], v[178:181], v[202:205], v[16:19]
	v_mfma_f32_16x16x32_bf16 v[4:7], v[170:173], v[210:213], v[4:7]
	v_mfma_f32_16x16x32_bf16 v[0:3], v[178:181], v[210:213], v[0:3]
	v_mfma_f32_16x16x32_bf16 v[60:63], v[174:177], v[190:193], v[60:63]
	v_mfma_f32_16x16x32_bf16 v[56:59], v[182:185], v[190:193], v[56:59]
	v_mfma_f32_16x16x32_bf16 v[36:39], v[174:177], v[198:201], v[36:39]
	v_mfma_f32_16x16x32_bf16 v[32:35], v[182:185], v[198:201], v[32:35]
	v_mfma_f32_16x16x32_bf16 v[20:23], v[174:177], v[206:209], v[20:23]
	v_mfma_f32_16x16x32_bf16 v[16:19], v[182:185], v[206:209], v[16:19]
	v_mfma_f32_16x16x32_bf16 v[4:7], v[174:177], v[214:217], v[4:7]
	v_mfma_f32_16x16x32_bf16 v[0:3], v[182:185], v[214:217], v[0:3]
	s_barrier
; #define PG8_STAGE(bufoff, gbase, voff) do { _Pragma("unroll") for (int _i = 0; _i < 2; ++_i) \
;         __builtin_amdgcn_global_load_lds((const unsigned*)((const char*)(gbase) + (voff)[_i]), (PG8_LAS unsigned*)(lds + (bufoff) + ldsw + _i * 8192), 16, 0, 0); } while (0)
; #define PG8_LDA(dst, b, h) do { _Pragma("unroll") for (int m = 0; m < 4; ++m) _Pragma("unroll") for (int k = 0; k < 2; ++k) dst[m][k] = *(const PG8_LAS bf16x8*)(lds + PG8_SA(b, h) + aoff + m * 2048 + k * 1024); } while (0)
; #define PG8_LDB(dst, b, h) do { _Pragma("unroll") for (int n = 0; n < 2; ++n) _Pragma("unroll") for (int k = 0; k < 2; ++k) dst[n][k] = *(const PG8_LAS bf16x8*)(lds + PG8_SB(b, h) + boff + n * 2048 + k * 1024); } while (0)
; #define PG8_MMA(ai, bj, At, Bt) do { __builtin_amdgcn_s_setprio(1); _Pragma("unroll") for (int m = 0; m < 4; ++m) _Pragma("unroll") for (int n = 0; n < 2; ++n) _Pragma("unroll") for (int k = 0; k < 2; ++k) \
;         acc[ai][bj][m][n] = __builtin_amdgcn_mfma_f32_16x16x32_bf16(Bt[n][k], At[m][k], acc[ai][bj][m][n], 0, 0, 0); __builtin_amdgcn_s_setprio(0); } while (0)
; #define PG8_WAIT_V(n) asm volatile("s_waitcnt vmcnt(" #n ")" ::: "memory")
; #define PG8_WAIT_L(n) asm volatile("s_waitcnt lgkmcnt(" #n ")" ::: "memory")
; #define PG8_BAR __builtin_amdgcn_s_barrier()
; template <class Epi, class Sched, bool ALIGN_EPI = false, bool SP2 = false>
; __device__ __forceinline__ void gemm_phase(PG8_LAS unsigned char* lds, const Gemm g, const Sched& S, const Epi& E) {
;     ...
;         for (int t = 0; t < nt; t += 2) {
;             const bool last = (t == nt - 2);
;             const char* a1 = cA + (size_t)(t + 1) * kstepA;
;             const char* a2 = last ? nA : cA + (size_t)(t + 2) * kstepA; const char* b2 = last ? nB : cB + (size_t)(t + 2) * kstep;
;             const char* a3 = a2 + kstepA; const char* b3 = b2 + kstep;
;     ...
;             PG8_LDB(B0, 1, 0); PG8_LDB(B1, 1, 1); PG8_SCHED; PG8_LDA(At, 1, 0); PG8_STAGE(PG8_SA(0, 1), a2 + hstepA, voffA);
;             PG8_WAIT_V(8); PG8_WAIT_L(0); PG8_BAR; PG8_MMA(0, 0, At, B0); PG8_MMA(0, 1, At, B1); PG8_BAR; PG8_SCHED;
;             PG8_LDA(At, 1, 1); PG8_STAGE(PG8_SB(1, 0), b3, voffB); PG8_STAGE(PG8_SB(1, 1), b3 + hstep, voffB); PG8_STAGE(PG8_SA(1, 0), a3, voffA);
;             PG8_WAIT_V(8); PG8_WAIT_L(0); PG8_BAR; PG8_MMA(1, 0, At, B0); PG8_MMA(1, 1, At, B1); PG8_BAR; PG8_SCHED;
	s_add_i32 s64, 0, 0x18000
	s_add_i32 s65, 0, 0x1c000
	ds_read_b128 v[144:147], v148
	ds_read_b128 v[158:161], v148 offset:1024
	ds_read_b128 v[162:165], v148 offset:2048
	ds_read_b128 v[166:169], v148 offset:3072
	ds_read_b128 v[170:173], v149
	ds_read_b128 v[174:177], v149 offset:1024
	ds_read_b128 v[178:181], v149 offset:2048
	ds_read_b128 v[182:185], v149 offset:3072
	s_add_u32 s30, s30, 0x4000
	s_addc_u32 s31, s31, 0
	s_mov_b32 m0, s38
	ds_read_b128 v[186:189], v155 offset:32768
	ds_read_b128 v[190:193], v155 offset:33792
	ds_read_b128 v[194:197], v155 offset:34816
	ds_read_b128 v[198:201], v155 offset:35840
	ds_read_b128 v[202:205], v155 offset:36864
	ds_read_b128 v[206:209], v155 offset:37888
	ds_read_b128 v[210:213], v155 offset:38912
	ds_read_b128 v[214:217], v155 offset:39936
	global_load_lds_dwordx4 v128, s[30:31]
	s_mov_b32 m0, s39
	s_nop 0
	global_load_lds_dwordx4 v132, s[30:31]
	s_waitcnt vmcnt(8) lgkmcnt(0)
	s_barrier
	v_mfma_f32_16x16x32_bf16 v[124:127], v[144:147], v[186:189], v[124:127]
	v_mfma_f32_16x16x32_bf16 v[120:123], v[162:165], v[186:189], v[120:123]
	v_mfma_f32_16x16x32_bf16 v[108:111], v[144:147], v[194:197], v[108:111]
	v_mfma_f32_16x16x32_bf16 v[48:51], v[162:165], v[194:197], v[48:51]
	v_mfma_f32_16x16x32_bf16 v[100:103], v[144:147], v[202:205], v[100:103]
	v_mfma_f32_16x16x32_bf16 v[64:67], v[162:165], v[202:205], v[64:67]
	v_mfma_f32_16x16x32_bf16 v[92:95], v[144:147], v[210:213], v[92:95]
	v_mfma_f32_16x16x32_bf16 v[80:83], v[162:165], v[210:213], v[80:83]
	v_mfma_f32_16x16x32_bf16 v[124:127], v[158:161], v[190:193], v[124:127]
	v_mfma_f32_16x16x32_bf16 v[120:123], v[166:169], v[190:193], v[120:123]
	v_mfma_f32_16x16x32_bf16 v[108:111], v[158:161], v[198:201], v[108:111]
	v_mfma_f32_16x16x32_bf16 v[48:51], v[166:169], v[198:201], v[48:51]
	v_mfma_f32_16x16x32_bf16 v[100:103], v[158:161], v[206:209], v[100:103]
	v_mfma_f32_16x16x32_bf16 v[64:67], v[166:169], v[206:209], v[64:67]
	v_mfma_f32_16x16x32_bf16 v[92:95], v[158:161], v[214:217], v[92:95]
	v_mfma_f32_16x16x32_bf16 v[80:83], v[166:169], v[214:217], v[80:83]
	v_mfma_f32_16x16x32_bf16 v[116:119], v[170:173], v[186:189], v[116:119]
	v_mfma_f32_16x16x32_bf16 v[112:115], v[178:181], v[186:189], v[112:115]
	v_mfma_f32_16x16x32_bf16 v[104:107], v[170:173], v[194:197], v[104:107]
	v_mfma_f32_16x16x32_bf16 v[52:55], v[178:181], v[194:197], v[52:55]
	v_mfma_f32_16x16x32_bf16 v[96:99], v[170:173], v[202:205], v[96:99]
	v_mfma_f32_16x16x32_bf16 v[76:79], v[178:181], v[202:205], v[76:79]
	v_mfma_f32_16x16x32_bf16 v[88:91], v[170:173], v[210:213], v[88:91]
	v_mfma_f32_16x16x32_bf16 v[84:87], v[178:181], v[210:213], v[84:87]
	v_mfma_f32_16x16x32_bf16 v[116:119], v[174:177], v[190:193], v[116:119]
	v_mfma_f32_16x16x32_bf16 v[112:115], v[182:185], v[190:193], v[112:115]
	v_mfma_f32_16x16x32_bf16 v[104:107], v[174:177], v[198:201], v[104:107]
	v_mfma_f32_16x16x32_bf16 v[52:55], v[182:185], v[198:201], v[52:55]
	v_mfma_f32_16x16x32_bf16 v[96:99], v[174:177], v[206:209], v[96:99]
	v_mfma_f32_16x16x32_bf16 v[76:79], v[182:185], v[206:209], v[76:79]
	v_mfma_f32_16x16x32_bf16 v[88:91], v[174:177], v[214:217], v[88:91]
	v_mfma_f32_16x16x32_bf16 v[84:87], v[182:185], v[214:217], v[84:87]
	s_barrier
	s_add_i32 s30, s64, s33
	s_mov_b32 m0, s30
	ds_read_b128 v[186:189], v155 offset:49152
	ds_read_b128 v[190:193], v155 offset:50176
	ds_read_b128 v[194:197], v155 offset:51200
	ds_read_b128 v[198:201], v155 offset:52224
	ds_read_b128 v[202:205], v155 offset:53248
	ds_read_b128 v[206:209], v155 offset:54272
	ds_read_b128 v[210:213], v155 offset:55296
	ds_read_b128 v[214:217], v155 offset:56320
	global_load_lds_dwordx4 v130, s[98:99]
	s_add_i32 m0, s30, 0x2000
	s_add_u32 s26, s26, 0x2b0080
	s_addc_u32 s27, s27, 0
	s_add_i32 s30, s65, s33
	global_load_lds_dwordx4 v134, s[98:99]
	s_mov_b32 m0, s30
	s_nop 0
	global_load_lds_dwordx4 v130, s[26:27]
	s_add_i32 m0, s30, 0x2000
	s_nop 0
	global_load_lds_dwordx4 v134, s[26:27]
	s_mov_b32 m0, s41
	s_nop 0
	global_load_lds_dwordx4 v128, s[24:25]
	s_mov_b32 m0, s52
	s_nop 0
	global_load_lds_dwordx4 v132, s[24:25]
	s_add_i32 s63, s63, 2
	s_add_u32 s61, s61, 0x100
	s_addc_u32 s62, s62, 0
	s_add_u32 s22, s22, 0x10000
	s_addc_u32 s23, s23, 0
	s_cmpk_gt_u32 s63, 0xa9
	s_waitcnt vmcnt(8) lgkmcnt(0)
	s_barrier
	v_mfma_f32_16x16x32_bf16 v[72:75], v[144:147], v[186:189], v[72:75]
	v_mfma_f32_16x16x32_bf16 v[68:71], v[162:165], v[186:189], v[68:71]
	v_mfma_f32_16x16x32_bf16 v[44:47], v[144:147], v[194:197], v[44:47]
	v_mfma_f32_16x16x32_bf16 v[40:43], v[162:165], v[194:197], v[40:43]
	v_mfma_f32_16x16x32_bf16 v[28:31], v[144:147], v[202:205], v[28:31]
	v_mfma_f32_16x16x32_bf16 v[24:27], v[162:165], v[202:205], v[24:27]
	v_mfma_f32_16x16x32_bf16 v[12:15], v[144:147], v[210:213], v[12:15]
	v_mfma_f32_16x16x32_bf16 v[8:11], v[162:165], v[210:213], v[8:11]
	v_mfma_f32_16x16x32_bf16 v[72:75], v[158:161], v[190:193], v[72:75]
	v_mfma_f32_16x16x32_bf16 v[68:71], v[166:169], v[190:193], v[68:71]
	v_mfma_f32_16x16x32_bf16 v[44:47], v[158:161], v[198:201], v[44:47]
	v_mfma_f32_16x16x32_bf16 v[40:43], v[166:169], v[198:201], v[40:43]
	v_mfma_f32_16x16x32_bf16 v[28:31], v[158:161], v[206:209], v[28:31]
	v_mfma_f32_16x16x32_bf16 v[24:27], v[166:169], v[206:209], v[24:27]
	v_mfma_f32_16x16x32_bf16 v[12:15], v[158:161], v[214:217], v[12:15]
	v_mfma_f32_16x16x32_bf16 v[8:11], v[166:169], v[214:217], v[8:11]
	v_mfma_f32_16x16x32_bf16 v[60:63], v[170:173], v[186:189], v[60:63]
	v_mfma_f32_16x16x32_bf16 v[56:59], v[178:181], v[186:189], v[56:59]
	v_mfma_f32_16x16x32_bf16 v[36:39], v[170:173], v[194:197], v[36:39]
	v_mfma_f32_16x16x32_bf16 v[32:35], v[178:181], v[194:197], v[32:35]
	v_mfma_f32_16x16x32_bf16 v[20:23], v[170:173], v[202:205], v[20:23]
	v_mfma_f32_16x16x32_bf16 v[16:19], v[178:181], v[202:205], v[16:19]
	v_mfma_f32_16x16x32_bf16 v[4:7], v[170:173], v[210:213], v[4:7]
	v_mfma_f32_16x16x32_bf16 v[0:3], v[178:181], v[210:213], v[0:3]
	v_mfma_f32_16x16x32_bf16 v[60:63], v[174:177], v[190:193], v[60:63]
	v_mfma_f32_16x16x32_bf16 v[56:59], v[182:185], v[190:193], v[56:59]
	v_mfma_f32_16x16x32_bf16 v[36:39], v[174:177], v[198:201], v[36:39]
	v_mfma_f32_16x16x32_bf16 v[32:35], v[182:185], v[198:201], v[32:35]
	v_mfma_f32_16x16x32_bf16 v[20:23], v[174:177], v[206:209], v[20:23]
	v_mfma_f32_16x16x32_bf16 v[16:19], v[182:185], v[206:209], v[16:19]
	v_mfma_f32_16x16x32_bf16 v[4:7], v[174:177], v[214:217], v[4:7]
	v_mfma_f32_16x16x32_bf16 v[0:3], v[182:185], v[214:217], v[0:3]
	s_barrier
	s_cbranch_scc0 .LBB0_1515
	s_and_b64 vcc, exec, s[18:19]
	s_cbranch_vccz .LBB0_1518
	s_barrier

; #define PG8_STAGE(bufoff, gbase, voff) do { _Pragma("unroll") for (int _i = 0; _i < 2; ++_i) \
;         __builtin_amdgcn_global_load_lds((const unsigned*)((const char*)(gbase) + (voff)[_i]), (PG8_LAS unsigned*)(lds + (bufoff) + ldsw + _i * 8192), 16, 0, 0); } while (0)
; #define PG8_LDA(dst, b, h) do { _Pragma("unroll") for (int m = 0; m < 4; ++m) _Pragma("unroll") for (int k = 0; k < 2; ++k) dst[m][k] = *(const PG8_LAS bf16x8*)(lds + PG8_SA(b, h) + aoff + m * 2048 + k * 1024); } while (0)
; #define PG8_LDB(dst, b, h) do { _Pragma("unroll") for (int n = 0; n < 2; ++n) _Pragma("unroll") for (int k = 0; k < 2; ++k) dst[n][k] = *(const PG8_LAS bf16x8*)(lds + PG8_SB(b, h) + boff + n * 2048 + k * 1024); } while (0)
; #define PG8_WAIT_V(n) asm volatile("s_waitcnt vmcnt(" #n ")" ::: "memory")
; #define PG8_WAIT_L(n) asm volatile("s_waitcnt lgkmcnt(" #n ")" ::: "memory")
; #define PG8_BAR __builtin_amdgcn_s_barrier()
; #define PG8_SCHED __builtin_amdgcn_sched_barrier(0)
; template <class Epi, class Sched, bool ALIGN_EPI = false, bool SP2 = false>
; __device__ __forceinline__ void gemm_phase(PG8_LAS unsigned char* lds, const Gemm g, const Sched& S, const Epi& E) {
;     ...
;         const char* nA = has_next ? (const char*)g.A + (size_t)nxt.pm * tstep : cA; const char* nB = has_next ? (const char*)g.Bt + (size_t)nxt.pn * tstep : cB;
;         for (int t = 0; t < nt; t += 2) {
;             const bool last = (t == nt - 2);
;             const char* a1 = cA + (size_t)(t + 1) * kstepA;
;             const char* a2 = last ? nA : cA + (size_t)(t + 2) * kstepA; const char* b2 = last ? nB : cB + (size_t)(t + 2) * kstep;
;             const char* a3 = a2 + kstepA; const char* b3 = b2 + kstep;
;             if (last && has_next) S.a_ready(nxt);
;             if constexpr (SP2) {
;             PG8_LDB(B0, 0, 0); PG8_LDB(B1, 0, 1); PG8_SCHED; PG8_LDA(At, 0, 0); PG8_STAGE(PG8_SA(1, 1), a1 + hstepA, voffA);
;             PG8_WAIT_V(8); PG8_WAIT_L(0); PG8_BAR; PG8_MMA(0, 0, At, B0); PG8_MMA(0, 1, At, B1); PG8_BAR; PG8_SCHED;
;             PG8_LDA(At, 0, 1); PG8_STAGE(PG8_SB(0, 0), b2, voffB); PG8_STAGE(PG8_SB(0, 1), b2 + hstep, voffB); PG8_STAGE(PG8_SA(0, 0), a2, voffA);
;             PG8_WAIT_V(8); PG8_WAIT_L(0); PG8_BAR; PG8_MMA(1, 0, At, B0); PG8_MMA(1, 1, At, B1); PG8_BAR; PG8_SCHED;
.LBB0_1631:
	ds_read_b128 v[144:147], v155
	ds_read_b128 v[148:151], v155 offset:1024
	ds_read_b128 v[160:163], v155 offset:2048
	ds_read_b128 v[164:167], v155 offset:3072
	ds_read_b128 v[168:171], v156
	ds_read_b128 v[172:175], v156 offset:1024
	ds_read_b128 v[176:179], v156 offset:2048
	ds_read_b128 v[180:183], v156 offset:3072
	s_add_u32 s65, s84, 0xfff00080
	s_addc_u32 s66, s85, -1
	s_cmp_eq_u32 s64, 60
	s_cselect_b32 s89, s25, s66
	s_cselect_b32 s88, s35, s65
	s_cselect_b32 s87, s23, s63
	s_cselect_b32 s86, s61, s62
	s_add_i32 m0, s29, 0xc000
	ds_read_b128 v[184:187], v157
	ds_read_b128 v[188:191], v157 offset:1024
	ds_read_b128 v[192:195], v157 offset:2048
	ds_read_b128 v[196:199], v157 offset:3072
	ds_read_b128 v[200:203], v157 offset:4096
	ds_read_b128 v[204:207], v157 offset:5120
	ds_read_b128 v[208:211], v157 offset:6144
	ds_read_b128 v[212:215], v157 offset:7168
	global_load_lds_dwordx4 v136, s[84:85]
	s_add_i32 m0, s29, 0xe000
	s_nop 0
	global_load_lds_dwordx4 v138, s[84:85]
	s_waitcnt vmcnt(8) lgkmcnt(0)
	s_barrier
	v_mfma_f32_16x16x32_bf16 v[124:127], v[144:147], v[184:187], v[124:127]
	v_mfma_f32_16x16x32_bf16 v[120:123], v[160:163], v[184:187], v[120:123]
	v_mfma_f32_16x16x32_bf16 v[108:111], v[144:147], v[192:195], v[108:111]
	v_mfma_f32_16x16x32_bf16 v[32:35], v[160:163], v[192:195], v[32:35]
	v_mfma_f32_16x16x32_bf16 v[100:103], v[144:147], v[200:203], v[100:103]
	v_mfma_f32_16x16x32_bf16 v[52:55], v[160:163], v[200:203], v[52:55]
	v_mfma_f32_16x16x32_bf16 v[92:95], v[144:147], v[208:211], v[92:95]
	v_mfma_f32_16x16x32_bf16 v[72:75], v[160:163], v[208:211], v[72:75]
	v_mfma_f32_16x16x32_bf16 v[124:127], v[148:151], v[188:191], v[124:127]
	v_mfma_f32_16x16x32_bf16 v[120:123], v[164:167], v[188:191], v[120:123]
	v_mfma_f32_16x16x32_bf16 v[108:111], v[148:151], v[196:199], v[108:111]
	v_mfma_f32_16x16x32_bf16 v[32:35], v[164:167], v[196:199], v[32:35]
	v_mfma_f32_16x16x32_bf16 v[100:103], v[148:151], v[204:207], v[100:103]
	v_mfma_f32_16x16x32_bf16 v[52:55], v[164:167], v[204:207], v[52:55]
	v_mfma_f32_16x16x32_bf16 v[92:95], v[148:151], v[212:215], v[92:95]
	v_mfma_f32_16x16x32_bf16 v[72:75], v[164:167], v[212:215], v[72:75]
	v_mfma_f32_16x16x32_bf16 v[116:119], v[168:171], v[184:187], v[116:119]
	v_mfma_f32_16x16x32_bf16 v[112:115], v[176:179], v[184:187], v[112:115]
	v_mfma_f32_16x16x32_bf16 v[104:107], v[168:171], v[192:195], v[104:107]
	v_mfma_f32_16x16x32_bf16 v[44:47], v[176:179], v[192:195], v[44:47]
	v_mfma_f32_16x16x32_bf16 v[96:99], v[168:171], v[200:203], v[96:99]
	v_mfma_f32_16x16x32_bf16 v[68:71], v[176:179], v[200:203], v[68:71]
	v_mfma_f32_16x16x32_bf16 v[88:91], v[168:171], v[208:211], v[88:91]
	v_mfma_f32_16x16x32_bf16 v[84:87], v[176:179], v[208:211], v[84:87]
	v_mfma_f32_16x16x32_bf16 v[116:119], v[172:175], v[188:191], v[116:119]
	v_mfma_f32_16x16x32_bf16 v[112:115], v[180:183], v[188:191], v[112:115]
	v_mfma_f32_16x16x32_bf16 v[104:107], v[172:175], v[196:199], v[104:107]
	v_mfma_f32_16x16x32_bf16 v[44:47], v[180:183], v[196:199], v[44:47]
	v_mfma_f32_16x16x32_bf16 v[96:99], v[172:175], v[204:207], v[96:99]
	v_mfma_f32_16x16x32_bf16 v[68:71], v[180:183], v[204:207], v[68:71]
	v_mfma_f32_16x16x32_bf16 v[88:91], v[172:175], v[212:215], v[88:91]
	v_mfma_f32_16x16x32_bf16 v[84:87], v[180:183], v[212:215], v[84:87]
	s_barrier
	s_add_u32 s98, s86, s18
	s_addc_u32 s99, s87, s19
	s_add_u32 s100, s88, s18
	s_addc_u32 s101, s89, s19
	s_add_i32 s65, s58, s3
	s_mov_b32 m0, s65
	ds_read_b128 v[184:187], v157 offset:16384
	ds_read_b128 v[188:191], v157 offset:17408
	ds_read_b128 v[192:195], v157 offset:18432
	ds_read_b128 v[196:199], v157 offset:19456
	ds_read_b128 v[200:203], v157 offset:20480
	ds_read_b128 v[204:207], v157 offset:21504
	ds_read_b128 v[208:211], v157 offset:22528
	ds_read_b128 v[212:215], v157 offset:23552
	global_load_lds_dwordx4 v130, s[86:87]
	s_add_i32 m0, s65, 0x2000
	s_add_u32 s66, s86, 0x100000
	s_addc_u32 s67, s87, 0
	s_add_i32 s65, s59, s3
	global_load_lds_dwordx4 v134, s[86:87]
	s_mov_b32 m0, s65
	s_nop 0
	global_load_lds_dwordx4 v130, s[66:67]
	s_add_i32 m0, s65, 0x2000
	s_nop 0
	global_load_lds_dwordx4 v134, s[66:67]
	s_mov_b32 m0, s29
	s_nop 0
	global_load_lds_dwordx4 v128, s[88:89]
	s_mov_b32 m0, s33
	s_nop 0
	global_load_lds_dwordx4 v132, s[88:89]
	s_waitcnt vmcnt(8) lgkmcnt(0)
	s_barrier
	v_mfma_f32_16x16x32_bf16 v[80:83], v[144:147], v[184:187], v[80:83]
	v_mfma_f32_16x16x32_bf16 v[76:79], v[160:163], v[184:187], v[76:79]
	v_mfma_f32_16x16x32_bf16 v[56:59], v[144:147], v[192:195], v[56:59]
	v_mfma_f32_16x16x32_bf16 v[48:51], v[160:163], v[192:195], v[48:51]
	v_mfma_f32_16x16x32_bf16 v[28:31], v[144:147], v[200:203], v[28:31]
	v_mfma_f32_16x16x32_bf16 v[24:27], v[160:163], v[200:203], v[24:27]
	v_mfma_f32_16x16x32_bf16 v[12:15], v[144:147], v[208:211], v[12:15]
	v_mfma_f32_16x16x32_bf16 v[8:11], v[160:163], v[208:211], v[8:11]
	v_mfma_f32_16x16x32_bf16 v[80:83], v[148:151], v[188:191], v[80:83]
	v_mfma_f32_16x16x32_bf16 v[76:79], v[164:167], v[188:191], v[76:79]
	v_mfma_f32_16x16x32_bf16 v[56:59], v[148:151], v[196:199], v[56:59]
	v_mfma_f32_16x16x32_bf16 v[48:51], v[164:167], v[196:199], v[48:51]
	v_mfma_f32_16x16x32_bf16 v[28:31], v[148:151], v[204:207], v[28:31]
	v_mfma_f32_16x16x32_bf16 v[24:27], v[164:167], v[204:207], v[24:27]
	v_mfma_f32_16x16x32_bf16 v[12:15], v[148:151], v[212:215], v[12:15]
	v_mfma_f32_16x16x32_bf16 v[8:11], v[164:167], v[212:215], v[8:11]
	v_mfma_f32_16x16x32_bf16 v[64:67], v[168:171], v[184:187], v[64:67]
	v_mfma_f32_16x16x32_bf16 v[60:63], v[176:179], v[184:187], v[60:63]
	v_mfma_f32_16x16x32_bf16 v[40:43], v[168:171], v[192:195], v[40:43]
	v_mfma_f32_16x16x32_bf16 v[36:39], v[176:179], v[192:195], v[36:39]
	v_mfma_f32_16x16x32_bf16 v[20:23], v[168:171], v[200:203], v[20:23]
	v_mfma_f32_16x16x32_bf16 v[16:19], v[176:179], v[200:203], v[16:19]
	v_mfma_f32_16x16x32_bf16 v[4:7], v[168:171], v[208:211], v[4:7]
	v_mfma_f32_16x16x32_bf16 v[0:3], v[176:179], v[208:211], v[0:3]
	v_mfma_f32_16x16x32_bf16 v[64:67], v[172:175], v[188:191], v[64:67]
	v_mfma_f32_16x16x32_bf16 v[60:63], v[180:183], v[188:191], v[60:63]
	v_mfma_f32_16x16x32_bf16 v[40:43], v[172:175], v[196:199], v[40:43]
	v_mfma_f32_16x16x32_bf16 v[36:39], v[180:183], v[196:199], v[36:39]
	v_mfma_f32_16x16x32_bf16 v[20:23], v[172:175], v[204:207], v[20:23]
	v_mfma_f32_16x16x32_bf16 v[16:19], v[180:183], v[204:207], v[16:19]
	v_mfma_f32_16x16x32_bf16 v[4:7], v[172:175], v[212:215], v[4:7]
	v_mfma_f32_16x16x32_bf16 v[0:3], v[180:183], v[212:215], v[0:3]
	s_barrier
; #define PG8_STAGE(bufoff, gbase, voff) do { _Pragma("unroll") for (int _i = 0; _i < 2; ++_i) \
;         __builtin_amdgcn_global_load_lds((const unsigned*)((const char*)(gbase) + (voff)[_i]), (PG8_LAS unsigned*)(lds + (bufoff) + ldsw + _i * 8192), 16, 0, 0); } while (0)
; #define PG8_LDA(dst, b, h) do { _Pragma("unroll") for (int m = 0; m < 4; ++m) _Pragma("unroll") for (int k = 0; k < 2; ++k) dst[m][k] = *(const PG8_LAS bf16x8*)(lds + PG8_SA(b, h) + aoff + m * 2048 + k * 1024); } while (0)
; #define PG8_LDB(dst, b, h) do { _Pragma("unroll") for (int n = 0; n < 2; ++n) _Pragma("unroll") for (int k = 0; k < 2; ++k) dst[n][k] = *(const PG8_LAS bf16x8*)(lds + PG8_SB(b, h) + boff + n * 2048 + k * 1024); } while (0)
; #define PG8_MMA(ai, bj, At, Bt) do { __builtin_amdgcn_s_setprio(1); _Pragma("unroll") for (int m = 0; m < 4; ++m) _Pragma("unroll") for (int n = 0; n < 2; ++n) _Pragma("unroll") for (int k = 0; k < 2; ++k) \
;         acc[ai][bj][m][n] = __builtin_amdgcn_mfma_f32_16x16x32_bf16(Bt[n][k], At[m][k], acc[ai][bj][m][n], 0, 0, 0); __builtin_amdgcn_s_setprio(0); } while (0)
; #define PG8_WAIT_V(n) asm volatile("s_waitcnt vmcnt(" #n ")" ::: "memory")
; #define PG8_WAIT_L(n) asm volatile("s_waitcnt lgkmcnt(" #n ")" ::: "memory")
; #define PG8_BAR __builtin_amdgcn_s_barrier()
; template <class Epi, class Sched, bool ALIGN_EPI = false, bool SP2 = false>
; __device__ __forceinline__ void gemm_phase(PG8_LAS unsigned char* lds, const Gemm g, const Sched& S, const Epi& E) {
;     ...
;         for (int t = 0; t < nt; t += 2) {
;             const bool last = (t == nt - 2);
;             const char* a1 = cA + (size_t)(t + 1) * kstepA;
;             const char* a2 = last ? nA : cA + (size_t)(t + 2) * kstepA; const char* b2 = last ? nB : cB + (size_t)(t + 2) * kstep;
;             const char* a3 = a2 + kstepA; const char* b3 = b2 + kstep;
;     ...
;             PG8_LDB(B0, 1, 0); PG8_LDB(B1, 1, 1); PG8_SCHED; PG8_LDA(At, 1, 0); PG8_STAGE(PG8_SA(0, 1), a2 + hstepA, voffA);
;             PG8_WAIT_V(8); PG8_WAIT_L(0); PG8_BAR; PG8_MMA(0, 0, At, B0); PG8_MMA(0, 1, At, B1); PG8_BAR; PG8_SCHED;
;             PG8_LDA(At, 1, 1); PG8_STAGE(PG8_SB(1, 0), b3, voffB); PG8_STAGE(PG8_SB(1, 1), b3 + hstep, voffB); PG8_STAGE(PG8_SA(1, 0), a3, voffA);
;             PG8_WAIT_V(8); PG8_WAIT_L(0); PG8_BAR; PG8_MMA(1, 0, At, B0); PG8_MMA(1, 1, At, B1); PG8_BAR; PG8_SCHED;
	s_add_i32 s65, 0, 0x18000
	s_add_i32 s68, 0, 0x1c000
	ds_read_b128 v[144:147], v216
	ds_read_b128 v[148:151], v216 offset:1024
	ds_read_b128 v[160:163], v216 offset:2048
	ds_read_b128 v[164:167], v216 offset:3072
	ds_read_b128 v[168:171], v217
	ds_read_b128 v[172:175], v217 offset:1024
	ds_read_b128 v[176:179], v217 offset:2048
	ds_read_b128 v[180:183], v217 offset:3072
	s_add_u32 s66, s88, 0x100000
	s_addc_u32 s67, s89, 0
	s_mov_b32 m0, s41
	ds_read_b128 v[184:187], v157 offset:32768
	ds_read_b128 v[188:191], v157 offset:33792
	ds_read_b128 v[192:195], v157 offset:34816
	ds_read_b128 v[196:199], v157 offset:35840
	ds_read_b128 v[200:203], v157 offset:36864
	ds_read_b128 v[204:207], v157 offset:37888
	ds_read_b128 v[208:211], v157 offset:38912
	ds_read_b128 v[212:215], v157 offset:39936
	global_load_lds_dwordx4 v128, s[66:67]
	s_mov_b32 m0, s52
	s_nop 0
	global_load_lds_dwordx4 v132, s[66:67]
	s_waitcnt vmcnt(8) lgkmcnt(0)
	s_barrier
	v_mfma_f32_16x16x32_bf16 v[124:127], v[144:147], v[184:187], v[124:127]
	v_mfma_f32_16x16x32_bf16 v[120:123], v[160:163], v[184:187], v[120:123]
	v_mfma_f32_16x16x32_bf16 v[108:111], v[144:147], v[192:195], v[108:111]
	v_mfma_f32_16x16x32_bf16 v[32:35], v[160:163], v[192:195], v[32:35]
	v_mfma_f32_16x16x32_bf16 v[100:103], v[144:147], v[200:203], v[100:103]
	v_mfma_f32_16x16x32_bf16 v[52:55], v[160:163], v[200:203], v[52:55]
	v_mfma_f32_16x16x32_bf16 v[92:95], v[144:147], v[208:211], v[92:95]
	v_mfma_f32_16x16x32_bf16 v[72:75], v[160:163], v[208:211], v[72:75]
	v_mfma_f32_16x16x32_bf16 v[124:127], v[148:151], v[188:191], v[124:127]
	v_mfma_f32_16x16x32_bf16 v[120:123], v[164:167], v[188:191], v[120:123]
	v_mfma_f32_16x16x32_bf16 v[108:111], v[148:151], v[196:199], v[108:111]
	v_mfma_f32_16x16x32_bf16 v[32:35], v[164:167], v[196:199], v[32:35]
	v_mfma_f32_16x16x32_bf16 v[100:103], v[148:151], v[204:207], v[100:103]
	v_mfma_f32_16x16x32_bf16 v[52:55], v[164:167], v[204:207], v[52:55]
	v_mfma_f32_16x16x32_bf16 v[92:95], v[148:151], v[212:215], v[92:95]
	v_mfma_f32_16x16x32_bf16 v[72:75], v[164:167], v[212:215], v[72:75]
	v_mfma_f32_16x16x32_bf16 v[116:119], v[168:171], v[184:187], v[116:119]
	v_mfma_f32_16x16x32_bf16 v[112:115], v[176:179], v[184:187], v[112:115]
	v_mfma_f32_16x16x32_bf16 v[104:107], v[168:171], v[192:195], v[104:107]
	v_mfma_f32_16x16x32_bf16 v[44:47], v[176:179], v[192:195], v[44:47]
	v_mfma_f32_16x16x32_bf16 v[96:99], v[168:171], v[200:203], v[96:99]
	v_mfma_f32_16x16x32_bf16 v[68:71], v[176:179], v[200:203], v[68:71]
	v_mfma_f32_16x16x32_bf16 v[88:91], v[168:171], v[208:211], v[88:91]
	v_mfma_f32_16x16x32_bf16 v[84:87], v[176:179], v[208:211], v[84:87]
	v_mfma_f32_16x16x32_bf16 v[116:119], v[172:175], v[188:191], v[116:119]
	v_mfma_f32_16x16x32_bf16 v[112:115], v[180:183], v[188:191], v[112:115]
	v_mfma_f32_16x16x32_bf16 v[104:107], v[172:175], v[196:199], v[104:107]
	v_mfma_f32_16x16x32_bf16 v[44:47], v[180:183], v[196:199], v[44:47]
	v_mfma_f32_16x16x32_bf16 v[96:99], v[172:175], v[204:207], v[96:99]
	v_mfma_f32_16x16x32_bf16 v[68:71], v[180:183], v[204:207], v[68:71]
	v_mfma_f32_16x16x32_bf16 v[88:91], v[172:175], v[212:215], v[88:91]
	v_mfma_f32_16x16x32_bf16 v[84:87], v[180:183], v[212:215], v[84:87]
	s_barrier
	s_add_i32 s65, s65, s3
	s_mov_b32 m0, s65
	ds_read_b128 v[184:187], v157 offset:49152
	ds_read_b128 v[188:191], v157 offset:50176
	ds_read_b128 v[192:195], v157 offset:51200
	ds_read_b128 v[196:199], v157 offset:52224
	ds_read_b128 v[200:203], v157 offset:53248
	ds_read_b128 v[204:207], v157 offset:54272
	ds_read_b128 v[208:211], v157 offset:55296
	ds_read_b128 v[212:215], v157 offset:56320
	global_load_lds_dwordx4 v130, s[98:99]
	s_add_i32 m0, s65, 0x2000
	s_add_u32 s66, s86, 0x100080
	s_addc_u32 s67, s87, 0
	s_add_i32 s65, s68, s3
	global_load_lds_dwordx4 v134, s[98:99]
	s_mov_b32 m0, s65
	s_nop 0
	global_load_lds_dwordx4 v130, s[66:67]
	s_add_i32 m0, s65, 0x2000
	s_nop 0
	global_load_lds_dwordx4 v134, s[66:67]
	s_mov_b32 m0, s54
	s_nop 0
	global_load_lds_dwordx4 v128, s[100:101]
	s_mov_b32 m0, s55
	s_nop 0
	global_load_lds_dwordx4 v132, s[100:101]
	s_add_i32 s64, s64, 2
	s_add_u32 s84, s84, 0x100
	s_addc_u32 s85, s85, 0
	s_add_u32 s62, s62, 0x100
	s_addc_u32 s63, s63, 0
	s_cmp_gt_u32 s64, 61
	s_waitcnt vmcnt(8) lgkmcnt(0)
	s_barrier
	v_mfma_f32_16x16x32_bf16 v[80:83], v[144:147], v[184:187], v[80:83]
	v_mfma_f32_16x16x32_bf16 v[76:79], v[160:163], v[184:187], v[76:79]
	v_mfma_f32_16x16x32_bf16 v[56:59], v[144:147], v[192:195], v[56:59]
	v_mfma_f32_16x16x32_bf16 v[48:51], v[160:163], v[192:195], v[48:51]
	v_mfma_f32_16x16x32_bf16 v[28:31], v[144:147], v[200:203], v[28:31]
	v_mfma_f32_16x16x32_bf16 v[24:27], v[160:163], v[200:203], v[24:27]
	v_mfma_f32_16x16x32_bf16 v[12:15], v[144:147], v[208:211], v[12:15]
	v_mfma_f32_16x16x32_bf16 v[8:11], v[160:163], v[208:211], v[8:11]
	v_mfma_f32_16x16x32_bf16 v[80:83], v[148:151], v[188:191], v[80:83]
	v_mfma_f32_16x16x32_bf16 v[76:79], v[164:167], v[188:191], v[76:79]
	v_mfma_f32_16x16x32_bf16 v[56:59], v[148:151], v[196:199], v[56:59]
	v_mfma_f32_16x16x32_bf16 v[48:51], v[164:167], v[196:199], v[48:51]
	v_mfma_f32_16x16x32_bf16 v[28:31], v[148:151], v[204:207], v[28:31]
	v_mfma_f32_16x16x32_bf16 v[24:27], v[164:167], v[204:207], v[24:27]
	v_mfma_f32_16x16x32_bf16 v[12:15], v[148:151], v[212:215], v[12:15]
	v_mfma_f32_16x16x32_bf16 v[8:11], v[164:167], v[212:215], v[8:11]
	v_mfma_f32_16x16x32_bf16 v[64:67], v[168:171], v[184:187], v[64:67]
	v_mfma_f32_16x16x32_bf16 v[60:63], v[176:179], v[184:187], v[60:63]
	v_mfma_f32_16x16x32_bf16 v[40:43], v[168:171], v[192:195], v[40:43]
	v_mfma_f32_16x16x32_bf16 v[36:39], v[176:179], v[192:195], v[36:39]
	v_mfma_f32_16x16x32_bf16 v[20:23], v[168:171], v[200:203], v[20:23]
	v_mfma_f32_16x16x32_bf16 v[16:19], v[176:179], v[200:203], v[16:19]
	v_mfma_f32_16x16x32_bf16 v[4:7], v[168:171], v[208:211], v[4:7]
	v_mfma_f32_16x16x32_bf16 v[0:3], v[176:179], v[208:211], v[0:3]
	v_mfma_f32_16x16x32_bf16 v[64:67], v[172:175], v[188:191], v[64:67]
	v_mfma_f32_16x16x32_bf16 v[60:63], v[180:183], v[188:191], v[60:63]
	v_mfma_f32_16x16x32_bf16 v[40:43], v[172:175], v[196:199], v[40:43]
	v_mfma_f32_16x16x32_bf16 v[36:39], v[180:183], v[196:199], v[36:39]
	v_mfma_f32_16x16x32_bf16 v[20:23], v[172:175], v[204:207], v[20:23]
	v_mfma_f32_16x16x32_bf16 v[16:19], v[180:183], v[204:207], v[16:19]
	v_mfma_f32_16x16x32_bf16 v[4:7], v[172:175], v[212:215], v[4:7]
	v_mfma_f32_16x16x32_bf16 v[0:3], v[180:183], v[212:215], v[0:3]
	s_barrier
	s_cbranch_scc0 .LBB0_1631
	s_and_b64 vcc, exec, s[20:21]
	s_cbranch_vccz .LBB0_1634
	s_barrier

; #define PG8_STAGE(bufoff, gbase, voff) do { _Pragma("unroll") for (int _i = 0; _i < 2; ++_i) \
;         __builtin_amdgcn_global_load_lds((const unsigned*)((const char*)(gbase) + (voff)[_i]), (PG8_LAS unsigned*)(lds + (bufoff) + ldsw + _i * 8192), 16, 0, 0); } while (0)
; #define PG8_LDA(dst, b, h) do { _Pragma("unroll") for (int m = 0; m < 4; ++m) _Pragma("unroll") for (int k = 0; k < 2; ++k) dst[m][k] = *(const PG8_LAS bf16x8*)(lds + PG8_SA(b, h) + aoff + m * 2048 + k * 1024); } while (0)
; #define PG8_LDB(dst, b, h) do { _Pragma("unroll") for (int n = 0; n < 2; ++n) _Pragma("unroll") for (int k = 0; k < 2; ++k) dst[n][k] = *(const PG8_LAS bf16x8*)(lds + PG8_SB(b, h) + boff + n * 2048 + k * 1024); } while (0)
; #define PG8_WAIT_V(n) asm volatile("s_waitcnt vmcnt(" #n ")" ::: "memory")
; #define PG8_WAIT_L(n) asm volatile("s_waitcnt lgkmcnt(" #n ")" ::: "memory")
; #define PG8_BAR __builtin_amdgcn_s_barrier()
; #define PG8_SCHED __builtin_amdgcn_sched_barrier(0)
; template <class Epi, class Sched, bool ALIGN_EPI = false, bool SP2 = false>
; __device__ __forceinline__ void gemm_phase(PG8_LAS unsigned char* lds, const Gemm g, const Sched& S, const Epi& E) {
;     ...
;         const char* nA = has_next ? (const char*)g.A + (size_t)nxt.pm * tstep : cA; const char* nB = has_next ? (const char*)g.Bt + (size_t)nxt.pn * tstep : cB;
;         for (int t = 0; t < nt; t += 2) {
;             const bool last = (t == nt - 2);
;             const char* a1 = cA + (size_t)(t + 1) * kstepA;
;             const char* a2 = last ? nA : cA + (size_t)(t + 2) * kstepA; const char* b2 = last ? nB : cB + (size_t)(t + 2) * kstep;
;             const char* a3 = a2 + kstepA; const char* b3 = b2 + kstep;
;             if (last && has_next) S.a_ready(nxt);
;             if constexpr (SP2) {
;             PG8_LDB(B0, 0, 0); PG8_LDB(B1, 0, 1); PG8_SCHED; PG8_LDA(At, 0, 0); PG8_STAGE(PG8_SA(1, 1), a1 + hstepA, voffA);
;             PG8_WAIT_V(8); PG8_WAIT_L(0); PG8_BAR; PG8_MMA(0, 0, At, B0); PG8_MMA(0, 1, At, B1); PG8_BAR; PG8_SCHED;
;             PG8_LDA(At, 0, 1); PG8_STAGE(PG8_SB(0, 0), b2, voffB); PG8_STAGE(PG8_SB(0, 1), b2 + hstep, voffB); PG8_STAGE(PG8_SA(0, 0), a2, voffA);
;             PG8_WAIT_V(8); PG8_WAIT_L(0); PG8_BAR; PG8_MMA(1, 0, At, B0); PG8_MMA(1, 1, At, B1); PG8_BAR; PG8_SCHED;
.LBB0_1741:
	ds_read_b128 v[150:153], v158
	ds_read_b128 v[162:165], v158 offset:1024
	ds_read_b128 v[166:169], v158 offset:2048
	ds_read_b128 v[170:173], v158 offset:3072
	ds_read_b128 v[174:177], v159
	ds_read_b128 v[178:181], v159 offset:1024
	ds_read_b128 v[182:185], v159 offset:2048
	ds_read_b128 v[186:189], v159 offset:3072
	s_add_u32 s40, s34, 0xfff00080
	s_addc_u32 s41, s35, -1
	s_cmp_eq_u32 s67, 60
	s_cselect_b32 s85, s21, s41
	s_cselect_b32 s84, s27, s40
	s_cselect_b32 s41, s19, s66
	s_cselect_b32 s40, s31, s65
	s_add_i32 m0, s53, 0xc000
	ds_read_b128 v[190:193], v160
	ds_read_b128 v[194:197], v160 offset:1024
	ds_read_b128 v[198:201], v160 offset:2048
	ds_read_b128 v[202:205], v160 offset:3072
	ds_read_b128 v[206:209], v160 offset:4096
	ds_read_b128 v[210:213], v160 offset:5120
	ds_read_b128 v[214:217], v160 offset:6144
	ds_read_b128 v[218:221], v160 offset:7168
	global_load_lds_dwordx4 v140, s[34:35]
	s_add_i32 m0, s53, 0xe000
	s_nop 0
	global_load_lds_dwordx4 v142, s[34:35]
	s_waitcnt vmcnt(8) lgkmcnt(0)
	s_barrier
	v_mfma_f32_16x16x32_bf16 v[124:127], v[150:153], v[190:193], v[124:127]
	v_mfma_f32_16x16x32_bf16 v[120:123], v[166:169], v[190:193], v[120:123]
	v_mfma_f32_16x16x32_bf16 v[108:111], v[150:153], v[198:201], v[108:111]
	v_mfma_f32_16x16x32_bf16 v[104:107], v[166:169], v[198:201], v[104:107]
	v_mfma_f32_16x16x32_bf16 v[92:95], v[150:153], v[206:209], v[92:95]
	v_mfma_f32_16x16x32_bf16 v[88:91], v[166:169], v[206:209], v[88:91]
	v_mfma_f32_16x16x32_bf16 v[76:79], v[150:153], v[214:217], v[76:79]
	v_mfma_f32_16x16x32_bf16 v[72:75], v[166:169], v[214:217], v[72:75]
	v_mfma_f32_16x16x32_bf16 v[124:127], v[162:165], v[194:197], v[124:127]
	v_mfma_f32_16x16x32_bf16 v[120:123], v[170:173], v[194:197], v[120:123]
	v_mfma_f32_16x16x32_bf16 v[108:111], v[162:165], v[202:205], v[108:111]
	v_mfma_f32_16x16x32_bf16 v[104:107], v[170:173], v[202:205], v[104:107]
	v_mfma_f32_16x16x32_bf16 v[92:95], v[162:165], v[210:213], v[92:95]
	v_mfma_f32_16x16x32_bf16 v[88:91], v[170:173], v[210:213], v[88:91]
	v_mfma_f32_16x16x32_bf16 v[76:79], v[162:165], v[218:221], v[76:79]
	v_mfma_f32_16x16x32_bf16 v[72:75], v[170:173], v[218:221], v[72:75]
	v_mfma_f32_16x16x32_bf16 v[116:119], v[174:177], v[190:193], v[116:119]
	v_mfma_f32_16x16x32_bf16 v[112:115], v[182:185], v[190:193], v[112:115]
	v_mfma_f32_16x16x32_bf16 v[100:103], v[174:177], v[198:201], v[100:103]
	v_mfma_f32_16x16x32_bf16 v[96:99], v[182:185], v[198:201], v[96:99]
	v_mfma_f32_16x16x32_bf16 v[84:87], v[174:177], v[206:209], v[84:87]
	v_mfma_f32_16x16x32_bf16 v[80:83], v[182:185], v[206:209], v[80:83]
	v_mfma_f32_16x16x32_bf16 v[68:71], v[174:177], v[214:217], v[68:71]
	v_mfma_f32_16x16x32_bf16 v[64:67], v[182:185], v[214:217], v[64:67]
	v_mfma_f32_16x16x32_bf16 v[116:119], v[178:181], v[194:197], v[116:119]
	v_mfma_f32_16x16x32_bf16 v[112:115], v[186:189], v[194:197], v[112:115]
	v_mfma_f32_16x16x32_bf16 v[100:103], v[178:181], v[202:205], v[100:103]
	v_mfma_f32_16x16x32_bf16 v[96:99], v[186:189], v[202:205], v[96:99]
	v_mfma_f32_16x16x32_bf16 v[84:87], v[178:181], v[210:213], v[84:87]
	v_mfma_f32_16x16x32_bf16 v[80:83], v[186:189], v[210:213], v[80:83]
	v_mfma_f32_16x16x32_bf16 v[68:71], v[178:181], v[218:221], v[68:71]
	v_mfma_f32_16x16x32_bf16 v[64:67], v[186:189], v[218:221], v[64:67]
	s_barrier
	s_add_u32 s98, s40, s12
	s_addc_u32 s99, s41, s13
	s_add_u32 s100, s84, s12
	s_addc_u32 s101, s85, s13
	s_add_i32 s68, s62, s33
	s_mov_b32 m0, s68
	ds_read_b128 v[190:193], v160 offset:16384
	ds_read_b128 v[194:197], v160 offset:17408
	ds_read_b128 v[198:201], v160 offset:18432
	ds_read_b128 v[202:205], v160 offset:19456
	ds_read_b128 v[206:209], v160 offset:20480
	ds_read_b128 v[210:213], v160 offset:21504
	ds_read_b128 v[214:217], v160 offset:22528
	ds_read_b128 v[218:221], v160 offset:23552
	global_load_lds_dwordx4 v132, s[40:41]
	s_add_i32 m0, s68, 0x2000
	s_add_u32 s68, s40, 0x100000
	s_addc_u32 s69, s41, 0
	s_add_i32 s70, s63, s33
	global_load_lds_dwordx4 v128, s[40:41]
	s_mov_b32 m0, s70
	s_nop 0
	global_load_lds_dwordx4 v132, s[68:69]
	s_add_i32 m0, s70, 0x2000
	s_nop 0
	global_load_lds_dwordx4 v128, s[68:69]
	s_mov_b32 m0, s53
	s_nop 0
	global_load_lds_dwordx4 v134, s[84:85]
	s_mov_b32 m0, s54
	s_nop 0
	global_load_lds_dwordx4 v130, s[84:85]
	s_waitcnt vmcnt(8) lgkmcnt(0)
	s_barrier
	v_mfma_f32_16x16x32_bf16 v[60:63], v[150:153], v[190:193], v[60:63]
	v_mfma_f32_16x16x32_bf16 v[56:59], v[166:169], v[190:193], v[56:59]
	v_mfma_f32_16x16x32_bf16 v[44:47], v[150:153], v[198:201], v[44:47]
	v_mfma_f32_16x16x32_bf16 v[40:43], v[166:169], v[198:201], v[40:43]
	v_mfma_f32_16x16x32_bf16 v[28:31], v[150:153], v[206:209], v[28:31]
	v_mfma_f32_16x16x32_bf16 v[24:27], v[166:169], v[206:209], v[24:27]
	v_mfma_f32_16x16x32_bf16 v[12:15], v[150:153], v[214:217], v[12:15]
	v_mfma_f32_16x16x32_bf16 v[8:11], v[166:169], v[214:217], v[8:11]
	v_mfma_f32_16x16x32_bf16 v[60:63], v[162:165], v[194:197], v[60:63]
	v_mfma_f32_16x16x32_bf16 v[56:59], v[170:173], v[194:197], v[56:59]
	v_mfma_f32_16x16x32_bf16 v[44:47], v[162:165], v[202:205], v[44:47]
	v_mfma_f32_16x16x32_bf16 v[40:43], v[170:173], v[202:205], v[40:43]
	v_mfma_f32_16x16x32_bf16 v[28:31], v[162:165], v[210:213], v[28:31]
	v_mfma_f32_16x16x32_bf16 v[24:27], v[170:173], v[210:213], v[24:27]
	v_mfma_f32_16x16x32_bf16 v[12:15], v[162:165], v[218:221], v[12:15]
	v_mfma_f32_16x16x32_bf16 v[8:11], v[170:173], v[218:221], v[8:11]
	v_mfma_f32_16x16x32_bf16 v[52:55], v[174:177], v[190:193], v[52:55]
	v_mfma_f32_16x16x32_bf16 v[48:51], v[182:185], v[190:193], v[48:51]
	v_mfma_f32_16x16x32_bf16 v[36:39], v[174:177], v[198:201], v[36:39]
	v_mfma_f32_16x16x32_bf16 v[32:35], v[182:185], v[198:201], v[32:35]
	v_mfma_f32_16x16x32_bf16 v[20:23], v[174:177], v[206:209], v[20:23]
	v_mfma_f32_16x16x32_bf16 v[16:19], v[182:185], v[206:209], v[16:19]
	v_mfma_f32_16x16x32_bf16 v[4:7], v[174:177], v[214:217], v[4:7]
	v_mfma_f32_16x16x32_bf16 v[0:3], v[182:185], v[214:217], v[0:3]
	v_mfma_f32_16x16x32_bf16 v[52:55], v[178:181], v[194:197], v[52:55]
	v_mfma_f32_16x16x32_bf16 v[48:51], v[186:189], v[194:197], v[48:51]
	v_mfma_f32_16x16x32_bf16 v[36:39], v[178:181], v[202:205], v[36:39]
	v_mfma_f32_16x16x32_bf16 v[32:35], v[186:189], v[202:205], v[32:35]
	v_mfma_f32_16x16x32_bf16 v[20:23], v[178:181], v[210:213], v[20:23]
	v_mfma_f32_16x16x32_bf16 v[16:19], v[186:189], v[210:213], v[16:19]
	v_mfma_f32_16x16x32_bf16 v[4:7], v[178:181], v[218:221], v[4:7]
	v_mfma_f32_16x16x32_bf16 v[0:3], v[186:189], v[218:221], v[0:3]
	s_barrier
; #define PG8_STAGE(bufoff, gbase, voff) do { _Pragma("unroll") for (int _i = 0; _i < 2; ++_i) \
;         __builtin_amdgcn_global_load_lds((const unsigned*)((const char*)(gbase) + (voff)[_i]), (PG8_LAS unsigned*)(lds + (bufoff) + ldsw + _i * 8192), 16, 0, 0); } while (0)
; #define PG8_LDA(dst, b, h) do { _Pragma("unroll") for (int m = 0; m < 4; ++m) _Pragma("unroll") for (int k = 0; k < 2; ++k) dst[m][k] = *(const PG8_LAS bf16x8*)(lds + PG8_SA(b, h) + aoff + m * 2048 + k * 1024); } while (0)
; #define PG8_LDB(dst, b, h) do { _Pragma("unroll") for (int n = 0; n < 2; ++n) _Pragma("unroll") for (int k = 0; k < 2; ++k) dst[n][k] = *(const PG8_LAS bf16x8*)(lds + PG8_SB(b, h) + boff + n * 2048 + k * 1024); } while (0)
; #define PG8_MMA(ai, bj, At, Bt) do { __builtin_amdgcn_s_setprio(1); _Pragma("unroll") for (int m = 0; m < 4; ++m) _Pragma("unroll") for (int n = 0; n < 2; ++n) _Pragma("unroll") for (int k = 0; k < 2; ++k) \
;         acc[ai][bj][m][n] = __builtin_amdgcn_mfma_f32_16x16x32_bf16(Bt[n][k], At[m][k], acc[ai][bj][m][n], 0, 0, 0); __builtin_amdgcn_s_setprio(0); } while (0)
; #define PG8_WAIT_V(n) asm volatile("s_waitcnt vmcnt(" #n ")" ::: "memory")
; #define PG8_WAIT_L(n) asm volatile("s_waitcnt lgkmcnt(" #n ")" ::: "memory")
; #define PG8_BAR __builtin_amdgcn_s_barrier()
; template <class Epi, class Sched, bool ALIGN_EPI = false, bool SP2 = false>
; __device__ __forceinline__ void gemm_phase(PG8_LAS unsigned char* lds, const Gemm g, const Sched& S, const Epi& E) {
;     ...
;         for (int t = 0; t < nt; t += 2) {
;             const bool last = (t == nt - 2);
;             const char* a1 = cA + (size_t)(t + 1) * kstepA;
;             const char* a2 = last ? nA : cA + (size_t)(t + 2) * kstepA; const char* b2 = last ? nB : cB + (size_t)(t + 2) * kstep;
;             const char* a3 = a2 + kstepA; const char* b3 = b2 + kstep;
;     ...
;             PG8_LDB(B0, 1, 0); PG8_LDB(B1, 1, 1); PG8_SCHED; PG8_LDA(At, 1, 0); PG8_STAGE(PG8_SA(0, 1), a2 + hstepA, voffA);
;             PG8_WAIT_V(8); PG8_WAIT_L(0); PG8_BAR; PG8_MMA(0, 0, At, B0); PG8_MMA(0, 1, At, B1); PG8_BAR; PG8_SCHED;
;             PG8_LDA(At, 1, 1); PG8_STAGE(PG8_SB(1, 0), b3, voffB); PG8_STAGE(PG8_SB(1, 1), b3 + hstep, voffB); PG8_STAGE(PG8_SA(1, 0), a3, voffA);
;             PG8_WAIT_V(8); PG8_WAIT_L(0); PG8_BAR; PG8_MMA(1, 0, At, B0); PG8_MMA(1, 1, At, B1); PG8_BAR; PG8_SCHED;
	s_add_i32 s70, 0, 0x18000
	s_add_i32 s71, 0, 0x1c000
	ds_read_b128 v[150:153], v154
	ds_read_b128 v[162:165], v154 offset:1024
	ds_read_b128 v[166:169], v154 offset:2048
	ds_read_b128 v[170:173], v154 offset:3072
	ds_read_b128 v[174:177], v155
	ds_read_b128 v[178:181], v155 offset:1024
	ds_read_b128 v[182:185], v155 offset:2048
	ds_read_b128 v[186:189], v155 offset:3072
	s_add_u32 s68, s84, 0x100000
	s_addc_u32 s69, s85, 0
	s_mov_b32 m0, s55
	ds_read_b128 v[190:193], v160 offset:32768
	ds_read_b128 v[194:197], v160 offset:33792
	ds_read_b128 v[198:201], v160 offset:34816
	ds_read_b128 v[202:205], v160 offset:35840
	ds_read_b128 v[206:209], v160 offset:36864
	ds_read_b128 v[210:213], v160 offset:37888
	ds_read_b128 v[214:217], v160 offset:38912
	ds_read_b128 v[218:221], v160 offset:39936
	global_load_lds_dwordx4 v134, s[68:69]
	s_mov_b32 m0, s56
	s_nop 0
	global_load_lds_dwordx4 v130, s[68:69]
	s_waitcnt vmcnt(8) lgkmcnt(0)
	s_barrier
	v_mfma_f32_16x16x32_bf16 v[124:127], v[150:153], v[190:193], v[124:127]
	v_mfma_f32_16x16x32_bf16 v[120:123], v[166:169], v[190:193], v[120:123]
	v_mfma_f32_16x16x32_bf16 v[108:111], v[150:153], v[198:201], v[108:111]
	v_mfma_f32_16x16x32_bf16 v[104:107], v[166:169], v[198:201], v[104:107]
	v_mfma_f32_16x16x32_bf16 v[92:95], v[150:153], v[206:209], v[92:95]
	v_mfma_f32_16x16x32_bf16 v[88:91], v[166:169], v[206:209], v[88:91]
	v_mfma_f32_16x16x32_bf16 v[76:79], v[150:153], v[214:217], v[76:79]
	v_mfma_f32_16x16x32_bf16 v[72:75], v[166:169], v[214:217], v[72:75]
	v_mfma_f32_16x16x32_bf16 v[124:127], v[162:165], v[194:197], v[124:127]
	v_mfma_f32_16x16x32_bf16 v[120:123], v[170:173], v[194:197], v[120:123]
	v_mfma_f32_16x16x32_bf16 v[108:111], v[162:165], v[202:205], v[108:111]
	v_mfma_f32_16x16x32_bf16 v[104:107], v[170:173], v[202:205], v[104:107]
	v_mfma_f32_16x16x32_bf16 v[92:95], v[162:165], v[210:213], v[92:95]
	v_mfma_f32_16x16x32_bf16 v[88:91], v[170:173], v[210:213], v[88:91]
	v_mfma_f32_16x16x32_bf16 v[76:79], v[162:165], v[218:221], v[76:79]
	v_mfma_f32_16x16x32_bf16 v[72:75], v[170:173], v[218:221], v[72:75]
	v_mfma_f32_16x16x32_bf16 v[116:119], v[174:177], v[190:193], v[116:119]
	v_mfma_f32_16x16x32_bf16 v[112:115], v[182:185], v[190:193], v[112:115]
	v_mfma_f32_16x16x32_bf16 v[100:103], v[174:177], v[198:201], v[100:103]
	v_mfma_f32_16x16x32_bf16 v[96:99], v[182:185], v[198:201], v[96:99]
	v_mfma_f32_16x16x32_bf16 v[84:87], v[174:177], v[206:209], v[84:87]
	v_mfma_f32_16x16x32_bf16 v[80:83], v[182:185], v[206:209], v[80:83]
	v_mfma_f32_16x16x32_bf16 v[68:71], v[174:177], v[214:217], v[68:71]
	v_mfma_f32_16x16x32_bf16 v[64:67], v[182:185], v[214:217], v[64:67]
	v_mfma_f32_16x16x32_bf16 v[116:119], v[178:181], v[194:197], v[116:119]
	v_mfma_f32_16x16x32_bf16 v[112:115], v[186:189], v[194:197], v[112:115]
	v_mfma_f32_16x16x32_bf16 v[100:103], v[178:181], v[202:205], v[100:103]
	v_mfma_f32_16x16x32_bf16 v[96:99], v[186:189], v[202:205], v[96:99]
	v_mfma_f32_16x16x32_bf16 v[84:87], v[178:181], v[210:213], v[84:87]
	v_mfma_f32_16x16x32_bf16 v[80:83], v[186:189], v[210:213], v[80:83]
	v_mfma_f32_16x16x32_bf16 v[68:71], v[178:181], v[218:221], v[68:71]
	v_mfma_f32_16x16x32_bf16 v[64:67], v[186:189], v[218:221], v[64:67]
	s_barrier
	s_add_i32 s68, s70, s33
	s_mov_b32 m0, s68
	ds_read_b128 v[190:193], v160 offset:49152
	ds_read_b128 v[194:197], v160 offset:50176
	ds_read_b128 v[198:201], v160 offset:51200
	ds_read_b128 v[202:205], v160 offset:52224
	ds_read_b128 v[206:209], v160 offset:53248
	ds_read_b128 v[210:213], v160 offset:54272
	ds_read_b128 v[214:217], v160 offset:55296
	ds_read_b128 v[218:221], v160 offset:56320
	global_load_lds_dwordx4 v132, s[98:99]
	s_add_i32 m0, s68, 0x2000
	s_add_u32 s40, s40, 0x100080
	s_addc_u32 s41, s41, 0
	s_add_i32 s68, s71, s33
	global_load_lds_dwordx4 v128, s[98:99]
	s_mov_b32 m0, s68
	s_nop 0
	global_load_lds_dwordx4 v132, s[40:41]
	s_add_i32 m0, s68, 0x2000
	s_nop 0
	global_load_lds_dwordx4 v128, s[40:41]
	s_mov_b32 m0, s60
	s_nop 0
	global_load_lds_dwordx4 v134, s[100:101]
	s_mov_b32 m0, s61
	s_nop 0
	global_load_lds_dwordx4 v130, s[100:101]
	s_add_i32 s67, s67, 2
	s_add_u32 s34, s34, 0x100
	s_addc_u32 s35, s35, 0
	s_add_u32 s65, s65, 0x100
	s_addc_u32 s66, s66, 0
	s_cmp_gt_u32 s67, 61
	s_waitcnt vmcnt(8) lgkmcnt(0)
	s_barrier
	v_mfma_f32_16x16x32_bf16 v[60:63], v[150:153], v[190:193], v[60:63]
	v_mfma_f32_16x16x32_bf16 v[56:59], v[166:169], v[190:193], v[56:59]
	v_mfma_f32_16x16x32_bf16 v[44:47], v[150:153], v[198:201], v[44:47]
	v_mfma_f32_16x16x32_bf16 v[40:43], v[166:169], v[198:201], v[40:43]
	v_mfma_f32_16x16x32_bf16 v[28:31], v[150:153], v[206:209], v[28:31]
	v_mfma_f32_16x16x32_bf16 v[24:27], v[166:169], v[206:209], v[24:27]
	v_mfma_f32_16x16x32_bf16 v[12:15], v[150:153], v[214:217], v[12:15]
	v_mfma_f32_16x16x32_bf16 v[8:11], v[166:169], v[214:217], v[8:11]
	v_mfma_f32_16x16x32_bf16 v[60:63], v[162:165], v[194:197], v[60:63]
	v_mfma_f32_16x16x32_bf16 v[56:59], v[170:173], v[194:197], v[56:59]
	v_mfma_f32_16x16x32_bf16 v[44:47], v[162:165], v[202:205], v[44:47]
	v_mfma_f32_16x16x32_bf16 v[40:43], v[170:173], v[202:205], v[40:43]
	v_mfma_f32_16x16x32_bf16 v[28:31], v[162:165], v[210:213], v[28:31]
	v_mfma_f32_16x16x32_bf16 v[24:27], v[170:173], v[210:213], v[24:27]
	v_mfma_f32_16x16x32_bf16 v[12:15], v[162:165], v[218:221], v[12:15]
	v_mfma_f32_16x16x32_bf16 v[8:11], v[170:173], v[218:221], v[8:11]
	v_mfma_f32_16x16x32_bf16 v[52:55], v[174:177], v[190:193], v[52:55]
	v_mfma_f32_16x16x32_bf16 v[48:51], v[182:185], v[190:193], v[48:51]
	v_mfma_f32_16x16x32_bf16 v[36:39], v[174:177], v[198:201], v[36:39]
	v_mfma_f32_16x16x32_bf16 v[32:35], v[182:185], v[198:201], v[32:35]
	v_mfma_f32_16x16x32_bf16 v[20:23], v[174:177], v[206:209], v[20:23]
	v_mfma_f32_16x16x32_bf16 v[16:19], v[182:185], v[206:209], v[16:19]
	v_mfma_f32_16x16x32_bf16 v[4:7], v[174:177], v[214:217], v[4:7]
	v_mfma_f32_16x16x32_bf16 v[0:3], v[182:185], v[214:217], v[0:3]
	v_mfma_f32_16x16x32_bf16 v[52:55], v[178:181], v[194:197], v[52:55]
	v_mfma_f32_16x16x32_bf16 v[48:51], v[186:189], v[194:197], v[48:51]
	v_mfma_f32_16x16x32_bf16 v[36:39], v[178:181], v[202:205], v[36:39]
	v_mfma_f32_16x16x32_bf16 v[32:35], v[186:189], v[202:205], v[32:35]
	v_mfma_f32_16x16x32_bf16 v[20:23], v[178:181], v[210:213], v[20:23]
	v_mfma_f32_16x16x32_bf16 v[16:19], v[186:189], v[210:213], v[16:19]
	v_mfma_f32_16x16x32_bf16 v[4:7], v[178:181], v[218:221], v[4:7]
	v_mfma_f32_16x16x32_bf16 v[0:3], v[186:189], v[218:221], v[0:3]
	s_barrier
	s_cbranch_scc0 .LBB0_1741
	s_and_b64 vcc, exec, s[14:15]
	s_cbranch_vccz .LBB0_1744
	s_barrier

; #define PG8_STAGE(bufoff, gbase, voff) do { _Pragma("unroll") for (int _i = 0; _i < 2; ++_i) \
;         __builtin_amdgcn_global_load_lds((const unsigned*)((const char*)(gbase) + (voff)[_i]), (PG8_LAS unsigned*)(lds + (bufoff) + ldsw + _i * 8192), 16, 0, 0); } while (0)
; #define PG8_LDA(dst, b, h) do { _Pragma("unroll") for (int m = 0; m < 4; ++m) _Pragma("unroll") for (int k = 0; k < 2; ++k) dst[m][k] = *(const PG8_LAS bf16x8*)(lds + PG8_SA(b, h) + aoff + m * 2048 + k * 1024); } while (0)
; #define PG8_LDB(dst, b, h) do { _Pragma("unroll") for (int n = 0; n < 2; ++n) _Pragma("unroll") for (int k = 0; k < 2; ++k) dst[n][k] = *(const PG8_LAS bf16x8*)(lds + PG8_SB(b, h) + boff + n * 2048 + k * 1024); } while (0)
; #define PG8_WAIT_V(n) asm volatile("s_waitcnt vmcnt(" #n ")" ::: "memory")
; #define PG8_WAIT_L(n) asm volatile("s_waitcnt lgkmcnt(" #n ")" ::: "memory")
; #define PG8_BAR __builtin_amdgcn_s_barrier()
; #define PG8_SCHED __builtin_amdgcn_sched_barrier(0)
; template <class Epi, class Sched, bool ALIGN_EPI = false, bool SP2 = false>
; __device__ __forceinline__ void gemm_phase(PG8_LAS unsigned char* lds, const Gemm g, const Sched& S, const Epi& E) {
;     ...
;         const char* nA = has_next ? (const char*)g.A + (size_t)nxt.pm * tstep : cA; const char* nB = has_next ? (const char*)g.Bt + (size_t)nxt.pn * tstep : cB;
;         for (int t = 0; t < nt; t += 2) {
;             const bool last = (t == nt - 2);
;             const char* a1 = cA + (size_t)(t + 1) * kstepA;
;             const char* a2 = last ? nA : cA + (size_t)(t + 2) * kstepA; const char* b2 = last ? nB : cB + (size_t)(t + 2) * kstep;
;             const char* a3 = a2 + kstepA; const char* b3 = b2 + kstep;
;             if (last && has_next) S.a_ready(nxt);
;             if constexpr (SP2) {
;             PG8_LDB(B0, 0, 0); PG8_LDB(B1, 0, 1); PG8_SCHED; PG8_LDA(At, 0, 0); PG8_STAGE(PG8_SA(1, 1), a1 + hstepA, voffA);
;             PG8_WAIT_V(8); PG8_WAIT_L(0); PG8_BAR; PG8_MMA(0, 0, At, B0); PG8_MMA(0, 1, At, B1); PG8_BAR; PG8_SCHED;
;             PG8_LDA(At, 0, 1); PG8_STAGE(PG8_SB(0, 0), b2, voffB); PG8_STAGE(PG8_SB(0, 1), b2 + hstep, voffB); PG8_STAGE(PG8_SA(0, 0), a2, voffA);
;             PG8_WAIT_V(8); PG8_WAIT_L(0); PG8_BAR; PG8_MMA(1, 0, At, B0); PG8_MMA(1, 1, At, B1); PG8_BAR; PG8_SCHED;
.LBB0_2770:
	ds_read_b128 v[144:147], v153
	ds_read_b128 v[158:161], v153 offset:1024
	ds_read_b128 v[162:165], v153 offset:2048
	ds_read_b128 v[166:169], v153 offset:3072
	ds_read_b128 v[170:173], v154
	ds_read_b128 v[174:177], v154 offset:1024
	ds_read_b128 v[178:181], v154 offset:2048
	ds_read_b128 v[182:185], v154 offset:3072
	s_add_u32 s48, s46, 0xfff00080
	s_addc_u32 s49, s47, -1
	s_cmp_eq_u32 s69, 60
	s_cselect_b32 s51, s31, s49
	s_cselect_b32 s50, s43, s48
	s_cselect_b32 s49, s27, s68
	s_cselect_b32 s48, s66, s67
	s_add_i32 m0, s45, 0xc000
	ds_read_b128 v[186:189], v155
	ds_read_b128 v[190:193], v155 offset:1024
	ds_read_b128 v[194:197], v155 offset:2048
	ds_read_b128 v[198:201], v155 offset:3072
	ds_read_b128 v[202:205], v155 offset:4096
	ds_read_b128 v[206:209], v155 offset:5120
	ds_read_b128 v[210:213], v155 offset:6144
	ds_read_b128 v[214:217], v155 offset:7168
	global_load_lds_dwordx4 v136, s[46:47]
	s_add_i32 m0, s45, 0xe000
	s_nop 0
	global_load_lds_dwordx4 v138, s[46:47]
	s_waitcnt vmcnt(8) lgkmcnt(0)
	s_barrier
	v_mfma_f32_16x16x32_bf16 v[124:127], v[144:147], v[186:189], v[124:127]
	v_mfma_f32_16x16x32_bf16 v[120:123], v[162:165], v[186:189], v[120:123]
	v_mfma_f32_16x16x32_bf16 v[108:111], v[144:147], v[194:197], v[108:111]
	v_mfma_f32_16x16x32_bf16 v[104:107], v[162:165], v[194:197], v[104:107]
	v_mfma_f32_16x16x32_bf16 v[92:95], v[144:147], v[202:205], v[92:95]
	v_mfma_f32_16x16x32_bf16 v[88:91], v[162:165], v[202:205], v[88:91]
	v_mfma_f32_16x16x32_bf16 v[76:79], v[144:147], v[210:213], v[76:79]
	v_mfma_f32_16x16x32_bf16 v[72:75], v[162:165], v[210:213], v[72:75]
	v_mfma_f32_16x16x32_bf16 v[124:127], v[158:161], v[190:193], v[124:127]
	v_mfma_f32_16x16x32_bf16 v[120:123], v[166:169], v[190:193], v[120:123]
	v_mfma_f32_16x16x32_bf16 v[108:111], v[158:161], v[198:201], v[108:111]
	v_mfma_f32_16x16x32_bf16 v[104:107], v[166:169], v[198:201], v[104:107]
	v_mfma_f32_16x16x32_bf16 v[92:95], v[158:161], v[206:209], v[92:95]
	v_mfma_f32_16x16x32_bf16 v[88:91], v[166:169], v[206:209], v[88:91]
	v_mfma_f32_16x16x32_bf16 v[76:79], v[158:161], v[214:217], v[76:79]
	v_mfma_f32_16x16x32_bf16 v[72:75], v[166:169], v[214:217], v[72:75]
	v_mfma_f32_16x16x32_bf16 v[116:119], v[170:173], v[186:189], v[116:119]
	v_mfma_f32_16x16x32_bf16 v[112:115], v[178:181], v[186:189], v[112:115]
	v_mfma_f32_16x16x32_bf16 v[100:103], v[170:173], v[194:197], v[100:103]
	v_mfma_f32_16x16x32_bf16 v[96:99], v[178:181], v[194:197], v[96:99]
	v_mfma_f32_16x16x32_bf16 v[84:87], v[170:173], v[202:205], v[84:87]
	v_mfma_f32_16x16x32_bf16 v[80:83], v[178:181], v[202:205], v[80:83]
	v_mfma_f32_16x16x32_bf16 v[68:71], v[170:173], v[210:213], v[68:71]
	v_mfma_f32_16x16x32_bf16 v[64:67], v[178:181], v[210:213], v[64:67]
	v_mfma_f32_16x16x32_bf16 v[116:119], v[174:177], v[190:193], v[116:119]
	v_mfma_f32_16x16x32_bf16 v[112:115], v[182:185], v[190:193], v[112:115]
	v_mfma_f32_16x16x32_bf16 v[100:103], v[174:177], v[198:201], v[100:103]
	v_mfma_f32_16x16x32_bf16 v[96:99], v[182:185], v[198:201], v[96:99]
	v_mfma_f32_16x16x32_bf16 v[84:87], v[174:177], v[206:209], v[84:87]
	v_mfma_f32_16x16x32_bf16 v[80:83], v[182:185], v[206:209], v[80:83]
	v_mfma_f32_16x16x32_bf16 v[68:71], v[174:177], v[214:217], v[68:71]
	v_mfma_f32_16x16x32_bf16 v[64:67], v[182:185], v[214:217], v[64:67]
	s_barrier
	s_add_u32 s98, s48, s16
	s_addc_u32 s99, s49, s17
	s_add_u32 s100, s50, s16
	s_addc_u32 s101, s51, s17
	s_add_i32 s70, s60, s33
	s_mov_b32 m0, s70
	ds_read_b128 v[186:189], v155 offset:16384
	ds_read_b128 v[190:193], v155 offset:17408
	ds_read_b128 v[194:197], v155 offset:18432
	ds_read_b128 v[198:201], v155 offset:19456
	ds_read_b128 v[202:205], v155 offset:20480
	ds_read_b128 v[206:209], v155 offset:21504
	ds_read_b128 v[210:213], v155 offset:22528
	ds_read_b128 v[214:217], v155 offset:23552
	global_load_lds_dwordx4 v130, s[48:49]
	s_add_i32 m0, s70, 0x2000
	s_add_u32 s70, s48, 0x100000
	s_addc_u32 s71, s49, 0
	s_add_i32 s72, s61, s33
	global_load_lds_dwordx4 v134, s[48:49]
	s_mov_b32 m0, s72
	s_nop 0
	global_load_lds_dwordx4 v130, s[70:71]
	s_add_i32 m0, s72, 0x2000
	s_nop 0
	global_load_lds_dwordx4 v134, s[70:71]
	s_mov_b32 m0, s45
	s_nop 0
	global_load_lds_dwordx4 v128, s[50:51]
	s_mov_b32 m0, s52
	s_nop 0
	global_load_lds_dwordx4 v132, s[50:51]
	s_waitcnt vmcnt(8) lgkmcnt(0)
	s_barrier
	v_mfma_f32_16x16x32_bf16 v[60:63], v[144:147], v[186:189], v[60:63]
	v_mfma_f32_16x16x32_bf16 v[56:59], v[162:165], v[186:189], v[56:59]
	v_mfma_f32_16x16x32_bf16 v[44:47], v[144:147], v[194:197], v[44:47]
	v_mfma_f32_16x16x32_bf16 v[40:43], v[162:165], v[194:197], v[40:43]
	v_mfma_f32_16x16x32_bf16 v[28:31], v[144:147], v[202:205], v[28:31]
	v_mfma_f32_16x16x32_bf16 v[24:27], v[162:165], v[202:205], v[24:27]
	v_mfma_f32_16x16x32_bf16 v[12:15], v[144:147], v[210:213], v[12:15]
	v_mfma_f32_16x16x32_bf16 v[8:11], v[162:165], v[210:213], v[8:11]
	v_mfma_f32_16x16x32_bf16 v[60:63], v[158:161], v[190:193], v[60:63]
	v_mfma_f32_16x16x32_bf16 v[56:59], v[166:169], v[190:193], v[56:59]
	v_mfma_f32_16x16x32_bf16 v[44:47], v[158:161], v[198:201], v[44:47]
	v_mfma_f32_16x16x32_bf16 v[40:43], v[166:169], v[198:201], v[40:43]
	v_mfma_f32_16x16x32_bf16 v[28:31], v[158:161], v[206:209], v[28:31]
	v_mfma_f32_16x16x32_bf16 v[24:27], v[166:169], v[206:209], v[24:27]
	v_mfma_f32_16x16x32_bf16 v[12:15], v[158:161], v[214:217], v[12:15]
	v_mfma_f32_16x16x32_bf16 v[8:11], v[166:169], v[214:217], v[8:11]
	v_mfma_f32_16x16x32_bf16 v[52:55], v[170:173], v[186:189], v[52:55]
	v_mfma_f32_16x16x32_bf16 v[48:51], v[178:181], v[186:189], v[48:51]
	v_mfma_f32_16x16x32_bf16 v[36:39], v[170:173], v[194:197], v[36:39]
	v_mfma_f32_16x16x32_bf16 v[32:35], v[178:181], v[194:197], v[32:35]
	v_mfma_f32_16x16x32_bf16 v[20:23], v[170:173], v[202:205], v[20:23]
	v_mfma_f32_16x16x32_bf16 v[16:19], v[178:181], v[202:205], v[16:19]
	v_mfma_f32_16x16x32_bf16 v[4:7], v[170:173], v[210:213], v[4:7]
	v_mfma_f32_16x16x32_bf16 v[0:3], v[178:181], v[210:213], v[0:3]
	v_mfma_f32_16x16x32_bf16 v[52:55], v[174:177], v[190:193], v[52:55]
	v_mfma_f32_16x16x32_bf16 v[48:51], v[182:185], v[190:193], v[48:51]
	v_mfma_f32_16x16x32_bf16 v[36:39], v[174:177], v[198:201], v[36:39]
	v_mfma_f32_16x16x32_bf16 v[32:35], v[182:185], v[198:201], v[32:35]
	v_mfma_f32_16x16x32_bf16 v[20:23], v[174:177], v[206:209], v[20:23]
	v_mfma_f32_16x16x32_bf16 v[16:19], v[182:185], v[206:209], v[16:19]
	v_mfma_f32_16x16x32_bf16 v[4:7], v[174:177], v[214:217], v[4:7]
	v_mfma_f32_16x16x32_bf16 v[0:3], v[182:185], v[214:217], v[0:3]
	s_barrier
; #define PG8_STAGE(bufoff, gbase, voff) do { _Pragma("unroll") for (int _i = 0; _i < 2; ++_i) \
;         __builtin_amdgcn_global_load_lds((const unsigned*)((const char*)(gbase) + (voff)[_i]), (PG8_LAS unsigned*)(lds + (bufoff) + ldsw + _i * 8192), 16, 0, 0); } while (0)
; #define PG8_LDA(dst, b, h) do { _Pragma("unroll") for (int m = 0; m < 4; ++m) _Pragma("unroll") for (int k = 0; k < 2; ++k) dst[m][k] = *(const PG8_LAS bf16x8*)(lds + PG8_SA(b, h) + aoff + m * 2048 + k * 1024); } while (0)
; #define PG8_LDB(dst, b, h) do { _Pragma("unroll") for (int n = 0; n < 2; ++n) _Pragma("unroll") for (int k = 0; k < 2; ++k) dst[n][k] = *(const PG8_LAS bf16x8*)(lds + PG8_SB(b, h) + boff + n * 2048 + k * 1024); } while (0)
; #define PG8_MMA(ai, bj, At, Bt) do { __builtin_amdgcn_s_setprio(1); _Pragma("unroll") for (int m = 0; m < 4; ++m) _Pragma("unroll") for (int n = 0; n < 2; ++n) _Pragma("unroll") for (int k = 0; k < 2; ++k) \
;         acc[ai][bj][m][n] = __builtin_amdgcn_mfma_f32_16x16x32_bf16(Bt[n][k], At[m][k], acc[ai][bj][m][n], 0, 0, 0); __builtin_amdgcn_s_setprio(0); } while (0)
; #define PG8_WAIT_V(n) asm volatile("s_waitcnt vmcnt(" #n ")" ::: "memory")
; #define PG8_WAIT_L(n) asm volatile("s_waitcnt lgkmcnt(" #n ")" ::: "memory")
; #define PG8_BAR __builtin_amdgcn_s_barrier()
; template <class Epi, class Sched, bool ALIGN_EPI = false, bool SP2 = false>
; __device__ __forceinline__ void gemm_phase(PG8_LAS unsigned char* lds, const Gemm g, const Sched& S, const Epi& E) {
;     ...
;         for (int t = 0; t < nt; t += 2) {
;             const bool last = (t == nt - 2);
;             const char* a1 = cA + (size_t)(t + 1) * kstepA;
;             const char* a2 = last ? nA : cA + (size_t)(t + 2) * kstepA; const char* b2 = last ? nB : cB + (size_t)(t + 2) * kstep;
;             const char* a3 = a2 + kstepA; const char* b3 = b2 + kstep;
;     ...
;             PG8_LDB(B0, 1, 0); PG8_LDB(B1, 1, 1); PG8_SCHED; PG8_LDA(At, 1, 0); PG8_STAGE(PG8_SA(0, 1), a2 + hstepA, voffA);
;             PG8_WAIT_V(8); PG8_WAIT_L(0); PG8_BAR; PG8_MMA(0, 0, At, B0); PG8_MMA(0, 1, At, B1); PG8_BAR; PG8_SCHED;
;             PG8_LDA(At, 1, 1); PG8_STAGE(PG8_SB(1, 0), b3, voffB); PG8_STAGE(PG8_SB(1, 1), b3 + hstep, voffB); PG8_STAGE(PG8_SA(1, 0), a3, voffA);
;             PG8_WAIT_V(8); PG8_WAIT_L(0); PG8_BAR; PG8_MMA(1, 0, At, B0); PG8_MMA(1, 1, At, B1); PG8_BAR; PG8_SCHED;
	s_add_i32 s70, 0, 0x18000
	s_add_i32 s71, 0, 0x1c000
	ds_read_b128 v[144:147], v148
	ds_read_b128 v[158:161], v148 offset:1024
	ds_read_b128 v[162:165], v148 offset:2048
	ds_read_b128 v[166:169], v148 offset:3072
	ds_read_b128 v[170:173], v149
	ds_read_b128 v[174:177], v149 offset:1024
	ds_read_b128 v[178:181], v149 offset:2048
	ds_read_b128 v[182:185], v149 offset:3072
	s_add_u32 s50, s50, 0x100000
	s_addc_u32 s51, s51, 0
	s_mov_b32 m0, s53
	ds_read_b128 v[186:189], v155 offset:32768
	ds_read_b128 v[190:193], v155 offset:33792
	ds_read_b128 v[194:197], v155 offset:34816
	ds_read_b128 v[198:201], v155 offset:35840
	ds_read_b128 v[202:205], v155 offset:36864
	ds_read_b128 v[206:209], v155 offset:37888
	ds_read_b128 v[210:213], v155 offset:38912
	ds_read_b128 v[214:217], v155 offset:39936
	global_load_lds_dwordx4 v128, s[50:51]
	s_mov_b32 m0, s54
	s_nop 0
	global_load_lds_dwordx4 v132, s[50:51]
	s_waitcnt vmcnt(8) lgkmcnt(0)
	s_barrier
	v_mfma_f32_16x16x32_bf16 v[124:127], v[144:147], v[186:189], v[124:127]
	v_mfma_f32_16x16x32_bf16 v[120:123], v[162:165], v[186:189], v[120:123]
	v_mfma_f32_16x16x32_bf16 v[108:111], v[144:147], v[194:197], v[108:111]
	v_mfma_f32_16x16x32_bf16 v[104:107], v[162:165], v[194:197], v[104:107]
	v_mfma_f32_16x16x32_bf16 v[92:95], v[144:147], v[202:205], v[92:95]
	v_mfma_f32_16x16x32_bf16 v[88:91], v[162:165], v[202:205], v[88:91]
	v_mfma_f32_16x16x32_bf16 v[76:79], v[144:147], v[210:213], v[76:79]
	v_mfma_f32_16x16x32_bf16 v[72:75], v[162:165], v[210:213], v[72:75]
	v_mfma_f32_16x16x32_bf16 v[124:127], v[158:161], v[190:193], v[124:127]
	v_mfma_f32_16x16x32_bf16 v[120:123], v[166:169], v[190:193], v[120:123]
	v_mfma_f32_16x16x32_bf16 v[108:111], v[158:161], v[198:201], v[108:111]
	v_mfma_f32_16x16x32_bf16 v[104:107], v[166:169], v[198:201], v[104:107]
	v_mfma_f32_16x16x32_bf16 v[92:95], v[158:161], v[206:209], v[92:95]
	v_mfma_f32_16x16x32_bf16 v[88:91], v[166:169], v[206:209], v[88:91]
	v_mfma_f32_16x16x32_bf16 v[76:79], v[158:161], v[214:217], v[76:79]
	v_mfma_f32_16x16x32_bf16 v[72:75], v[166:169], v[214:217], v[72:75]
	v_mfma_f32_16x16x32_bf16 v[116:119], v[170:173], v[186:189], v[116:119]
	v_mfma_f32_16x16x32_bf16 v[112:115], v[178:181], v[186:189], v[112:115]
	v_mfma_f32_16x16x32_bf16 v[100:103], v[170:173], v[194:197], v[100:103]
	v_mfma_f32_16x16x32_bf16 v[96:99], v[178:181], v[194:197], v[96:99]
	v_mfma_f32_16x16x32_bf16 v[84:87], v[170:173], v[202:205], v[84:87]
	v_mfma_f32_16x16x32_bf16 v[80:83], v[178:181], v[202:205], v[80:83]
	v_mfma_f32_16x16x32_bf16 v[68:71], v[170:173], v[210:213], v[68:71]
	v_mfma_f32_16x16x32_bf16 v[64:67], v[178:181], v[210:213], v[64:67]
	v_mfma_f32_16x16x32_bf16 v[116:119], v[174:177], v[190:193], v[116:119]
	v_mfma_f32_16x16x32_bf16 v[112:115], v[182:185], v[190:193], v[112:115]
	v_mfma_f32_16x16x32_bf16 v[100:103], v[174:177], v[198:201], v[100:103]
	v_mfma_f32_16x16x32_bf16 v[96:99], v[182:185], v[198:201], v[96:99]
	v_mfma_f32_16x16x32_bf16 v[84:87], v[174:177], v[206:209], v[84:87]
	v_mfma_f32_16x16x32_bf16 v[80:83], v[182:185], v[206:209], v[80:83]
	v_mfma_f32_16x16x32_bf16 v[68:71], v[174:177], v[214:217], v[68:71]
	v_mfma_f32_16x16x32_bf16 v[64:67], v[182:185], v[214:217], v[64:67]
	s_barrier
	s_add_i32 s50, s70, s33
	s_mov_b32 m0, s50
	ds_read_b128 v[186:189], v155 offset:49152
	ds_read_b128 v[190:193], v155 offset:50176
	ds_read_b128 v[194:197], v155 offset:51200
	ds_read_b128 v[198:201], v155 offset:52224
	ds_read_b128 v[202:205], v155 offset:53248
	ds_read_b128 v[206:209], v155 offset:54272
	ds_read_b128 v[210:213], v155 offset:55296
	ds_read_b128 v[214:217], v155 offset:56320
	global_load_lds_dwordx4 v130, s[98:99]
	s_add_i32 m0, s50, 0x2000
	s_add_u32 s48, s48, 0x100080
	s_addc_u32 s49, s49, 0
	s_add_i32 s50, s71, s33
	global_load_lds_dwordx4 v134, s[98:99]
	s_mov_b32 m0, s50
	s_nop 0
	global_load_lds_dwordx4 v130, s[48:49]
	s_add_i32 m0, s50, 0x2000
	s_nop 0
	global_load_lds_dwordx4 v134, s[48:49]
	s_mov_b32 m0, s56
	s_nop 0
	global_load_lds_dwordx4 v128, s[100:101]
	s_mov_b32 m0, s57
	s_nop 0
	global_load_lds_dwordx4 v132, s[100:101]
	s_add_i32 s69, s69, 2
	s_add_u32 s46, s46, 0x100
	s_addc_u32 s47, s47, 0
	s_add_u32 s67, s67, 0x100
	s_addc_u32 s68, s68, 0
	s_cmp_gt_u32 s69, 61
	s_waitcnt vmcnt(8) lgkmcnt(0)
	s_barrier
	v_mfma_f32_16x16x32_bf16 v[60:63], v[144:147], v[186:189], v[60:63]
	v_mfma_f32_16x16x32_bf16 v[56:59], v[162:165], v[186:189], v[56:59]
	v_mfma_f32_16x16x32_bf16 v[44:47], v[144:147], v[194:197], v[44:47]
	v_mfma_f32_16x16x32_bf16 v[40:43], v[162:165], v[194:197], v[40:43]
	v_mfma_f32_16x16x32_bf16 v[28:31], v[144:147], v[202:205], v[28:31]
	v_mfma_f32_16x16x32_bf16 v[24:27], v[162:165], v[202:205], v[24:27]
	v_mfma_f32_16x16x32_bf16 v[12:15], v[144:147], v[210:213], v[12:15]
	v_mfma_f32_16x16x32_bf16 v[8:11], v[162:165], v[210:213], v[8:11]
	v_mfma_f32_16x16x32_bf16 v[60:63], v[158:161], v[190:193], v[60:63]
	v_mfma_f32_16x16x32_bf16 v[56:59], v[166:169], v[190:193], v[56:59]
	v_mfma_f32_16x16x32_bf16 v[44:47], v[158:161], v[198:201], v[44:47]
	v_mfma_f32_16x16x32_bf16 v[40:43], v[166:169], v[198:201], v[40:43]
	v_mfma_f32_16x16x32_bf16 v[28:31], v[158:161], v[206:209], v[28:31]
	v_mfma_f32_16x16x32_bf16 v[24:27], v[166:169], v[206:209], v[24:27]
	v_mfma_f32_16x16x32_bf16 v[12:15], v[158:161], v[214:217], v[12:15]
	v_mfma_f32_16x16x32_bf16 v[8:11], v[166:169], v[214:217], v[8:11]
	v_mfma_f32_16x16x32_bf16 v[52:55], v[170:173], v[186:189], v[52:55]
	v_mfma_f32_16x16x32_bf16 v[48:51], v[178:181], v[186:189], v[48:51]
	v_mfma_f32_16x16x32_bf16 v[36:39], v[170:173], v[194:197], v[36:39]
	v_mfma_f32_16x16x32_bf16 v[32:35], v[178:181], v[194:197], v[32:35]
	v_mfma_f32_16x16x32_bf16 v[20:23], v[170:173], v[202:205], v[20:23]
	v_mfma_f32_16x16x32_bf16 v[16:19], v[178:181], v[202:205], v[16:19]
	v_mfma_f32_16x16x32_bf16 v[4:7], v[170:173], v[210:213], v[4:7]
	v_mfma_f32_16x16x32_bf16 v[0:3], v[178:181], v[210:213], v[0:3]
	v_mfma_f32_16x16x32_bf16 v[52:55], v[174:177], v[190:193], v[52:55]
	v_mfma_f32_16x16x32_bf16 v[48:51], v[182:185], v[190:193], v[48:51]
	v_mfma_f32_16x16x32_bf16 v[36:39], v[174:177], v[198:201], v[36:39]
	v_mfma_f32_16x16x32_bf16 v[32:35], v[182:185], v[198:201], v[32:35]
	v_mfma_f32_16x16x32_bf16 v[20:23], v[174:177], v[206:209], v[20:23]
	v_mfma_f32_16x16x32_bf16 v[16:19], v[182:185], v[206:209], v[16:19]
	v_mfma_f32_16x16x32_bf16 v[4:7], v[174:177], v[214:217], v[4:7]
	v_mfma_f32_16x16x32_bf16 v[0:3], v[182:185], v[214:217], v[0:3]
	s_barrier
	s_cbranch_scc0 .LBB0_2770
	s_and_b64 vcc, exec, s[18:19]
	s_cbranch_vccz .LBB0_2773
	s_barrier

; #define PG8_STAGE(bufoff, gbase, voff) do { _Pragma("unroll") for (int _i = 0; _i < 2; ++_i) \
;         __builtin_amdgcn_global_load_lds((const unsigned*)((const char*)(gbase) + (voff)[_i]), (PG8_LAS unsigned*)(lds + (bufoff) + ldsw + _i * 8192), 16, 0, 0); } while (0)
; #define PG8_LDA(dst, b, h) do { _Pragma("unroll") for (int m = 0; m < 4; ++m) _Pragma("unroll") for (int k = 0; k < 2; ++k) dst[m][k] = *(const PG8_LAS bf16x8*)(lds + PG8_SA(b, h) + aoff + m * 2048 + k * 1024); } while (0)
; #define PG8_LDB(dst, b, h) do { _Pragma("unroll") for (int n = 0; n < 2; ++n) _Pragma("unroll") for (int k = 0; k < 2; ++k) dst[n][k] = *(const PG8_LAS bf16x8*)(lds + PG8_SB(b, h) + boff + n * 2048 + k * 1024); } while (0)
; #define PG8_WAIT_V(n) asm volatile("s_waitcnt vmcnt(" #n ")" ::: "memory")
; #define PG8_WAIT_L(n) asm volatile("s_waitcnt lgkmcnt(" #n ")" ::: "memory")
; #define PG8_BAR __builtin_amdgcn_s_barrier()
; #define PG8_SCHED __builtin_amdgcn_sched_barrier(0)
; template <class Epi, class Sched, bool ALIGN_EPI = false, bool SP2 = false>
; __device__ __forceinline__ void gemm_phase(PG8_LAS unsigned char* lds, const Gemm g, const Sched& S, const Epi& E) {
;     ...
;         const char* nA = has_next ? (const char*)g.A + (size_t)nxt.pm * tstep : cA; const char* nB = has_next ? (const char*)g.Bt + (size_t)nxt.pn * tstep : cB;
;         for (int t = 0; t < nt; t += 2) {
;             const bool last = (t == nt - 2);
;             const char* a1 = cA + (size_t)(t + 1) * kstepA;
;             const char* a2 = last ? nA : cA + (size_t)(t + 2) * kstepA; const char* b2 = last ? nB : cB + (size_t)(t + 2) * kstep;
;             const char* a3 = a2 + kstepA; const char* b3 = b2 + kstep;
;             if (last && has_next) S.a_ready(nxt);
;             if constexpr (SP2) {
;             PG8_LDB(B0, 0, 0); PG8_LDB(B1, 0, 1); PG8_SCHED; PG8_LDA(At, 0, 0); PG8_STAGE(PG8_SA(1, 1), a1 + hstepA, voffA);
;             PG8_WAIT_V(8); PG8_WAIT_L(0); PG8_BAR; PG8_MMA(0, 0, At, B0); PG8_MMA(0, 1, At, B1); PG8_BAR; PG8_SCHED;
;             PG8_LDA(At, 0, 1); PG8_STAGE(PG8_SB(0, 0), b2, voffB); PG8_STAGE(PG8_SB(0, 1), b2 + hstep, voffB); PG8_STAGE(PG8_SA(0, 0), a2, voffA);
;             PG8_WAIT_V(8); PG8_WAIT_L(0); PG8_BAR; PG8_MMA(1, 0, At, B0); PG8_MMA(1, 1, At, B1); PG8_BAR; PG8_SCHED;
.LBB0_2882:
	ds_read_b128 v[128:131], v236
	ds_read_b128 v[132:135], v236 offset:1024
	ds_read_b128 v[136:139], v236 offset:2048
	ds_read_b128 v[140:143], v236 offset:3072
	ds_read_b128 v[144:147], v237
	ds_read_b128 v[148:151], v237 offset:1024
	ds_read_b128 v[152:155], v237 offset:2048
	ds_read_b128 v[156:159], v237 offset:3072
	s_add_u32 s10, s8, 0x100
	s_addc_u32 s11, s9, 0
	s_cmp_eq_u32 s88, 60
	s_cselect_b32 s61, s7, s11
	s_cselect_b32 s60, s51, s10
	s_cselect_b32 s59, s49, s87
	s_cselect_b32 s58, s85, s86
	v_lshl_add_u64 v[164:165], s[8:9], 0, v[178:179]
	s_add_i32 m0, s57, 0xc000
	ds_read_b128 v[160:163], v238
	ds_read_b128 v[186:189], v238 offset:1024
	ds_read_b128 v[190:193], v238 offset:2048
	ds_read_b128 v[194:197], v238 offset:3072
	ds_read_b128 v[198:201], v238 offset:4096
	ds_read_b128 v[202:205], v238 offset:5120
	ds_read_b128 v[206:209], v238 offset:6144
	ds_read_b128 v[210:213], v238 offset:7168
	global_load_lds_dwordx4 v[164:165], off
	v_lshl_add_u64 v[164:165], s[8:9], 0, v[180:181]
	s_add_i32 m0, s57, 0xe000
	s_nop 0
	global_load_lds_dwordx4 v[164:165], off
	s_waitcnt vmcnt(8) lgkmcnt(0)
	s_barrier
	v_mfma_f32_16x16x32_bf16 v[124:127], v[128:131], v[160:163], v[124:127]
	v_mfma_f32_16x16x32_bf16 v[120:123], v[136:139], v[160:163], v[120:123]
	v_mfma_f32_16x16x32_bf16 v[108:111], v[128:131], v[190:193], v[108:111]
	v_mfma_f32_16x16x32_bf16 v[104:107], v[136:139], v[190:193], v[104:107]
	v_mfma_f32_16x16x32_bf16 v[92:95], v[128:131], v[198:201], v[92:95]
	v_mfma_f32_16x16x32_bf16 v[88:91], v[136:139], v[198:201], v[88:91]
	v_mfma_f32_16x16x32_bf16 v[76:79], v[128:131], v[206:209], v[76:79]
	v_mfma_f32_16x16x32_bf16 v[72:75], v[136:139], v[206:209], v[72:75]
	v_mfma_f32_16x16x32_bf16 v[124:127], v[132:135], v[186:189], v[124:127]
	v_mfma_f32_16x16x32_bf16 v[120:123], v[140:143], v[186:189], v[120:123]
	v_mfma_f32_16x16x32_bf16 v[108:111], v[132:135], v[194:197], v[108:111]
	v_mfma_f32_16x16x32_bf16 v[104:107], v[140:143], v[194:197], v[104:107]
	v_mfma_f32_16x16x32_bf16 v[92:95], v[132:135], v[202:205], v[92:95]
	v_mfma_f32_16x16x32_bf16 v[88:91], v[140:143], v[202:205], v[88:91]
	v_mfma_f32_16x16x32_bf16 v[76:79], v[132:135], v[210:213], v[76:79]
	v_mfma_f32_16x16x32_bf16 v[72:75], v[140:143], v[210:213], v[72:75]
	v_mfma_f32_16x16x32_bf16 v[116:119], v[144:147], v[160:163], v[116:119]
	v_mfma_f32_16x16x32_bf16 v[112:115], v[152:155], v[160:163], v[112:115]
	v_mfma_f32_16x16x32_bf16 v[100:103], v[144:147], v[190:193], v[100:103]
	v_mfma_f32_16x16x32_bf16 v[96:99], v[152:155], v[190:193], v[96:99]
	v_mfma_f32_16x16x32_bf16 v[84:87], v[144:147], v[198:201], v[84:87]
	v_mfma_f32_16x16x32_bf16 v[80:83], v[152:155], v[198:201], v[80:83]
	v_mfma_f32_16x16x32_bf16 v[68:71], v[144:147], v[206:209], v[68:71]
	v_mfma_f32_16x16x32_bf16 v[64:67], v[152:155], v[206:209], v[64:67]
	v_mfma_f32_16x16x32_bf16 v[116:119], v[148:151], v[186:189], v[116:119]
	v_mfma_f32_16x16x32_bf16 v[112:115], v[156:159], v[186:189], v[112:115]
	v_mfma_f32_16x16x32_bf16 v[100:103], v[148:151], v[194:197], v[100:103]
	v_mfma_f32_16x16x32_bf16 v[96:99], v[156:159], v[194:197], v[96:99]
	v_mfma_f32_16x16x32_bf16 v[84:87], v[148:151], v[202:205], v[84:87]
	v_mfma_f32_16x16x32_bf16 v[80:83], v[156:159], v[202:205], v[80:83]
	v_mfma_f32_16x16x32_bf16 v[68:71], v[148:151], v[210:213], v[68:71]
	v_mfma_f32_16x16x32_bf16 v[64:67], v[156:159], v[210:213], v[64:67]
	s_barrier
	s_add_u32 s98, s58, s16
	s_addc_u32 s99, s59, s17
	s_add_u32 s100, s60, s16
	s_addc_u32 s101, s61, s17
	s_add_i32 s8, s72, s63
	s_mov_b32 m0, s8
	ds_read_b128 v[160:163], v238 offset:16384
	ds_read_b128 v[186:189], v238 offset:17408
	ds_read_b128 v[190:193], v238 offset:18432
	ds_read_b128 v[194:197], v238 offset:19456
	ds_read_b128 v[198:201], v238 offset:20480
	ds_read_b128 v[202:205], v238 offset:21504
	ds_read_b128 v[206:209], v238 offset:22528
	ds_read_b128 v[210:213], v238 offset:23552
	global_load_lds_dwordx4 v168, s[58:59]
	s_add_i32 m0, s8, 0x2000
	s_add_u32 s8, s58, 0x100000
	s_addc_u32 s9, s59, 0
	s_add_i32 s89, s73, s63
	global_load_lds_dwordx4 v172, s[58:59]
	s_mov_b32 m0, s89
	s_nop 0
	global_load_lds_dwordx4 v168, s[8:9]
	s_add_i32 m0, s89, 0x2000
	s_nop 0
	global_load_lds_dwordx4 v172, s[8:9]
	s_mov_b32 m0, s57
	s_nop 0
	global_load_lds_dwordx4 v166, s[60:61]
	s_mov_b32 m0, s64
	s_nop 0
	global_load_lds_dwordx4 v170, s[60:61]
	s_waitcnt vmcnt(8) lgkmcnt(0)
	s_barrier
	v_mfma_f32_16x16x32_bf16 v[60:63], v[128:131], v[160:163], v[60:63]
	v_mfma_f32_16x16x32_bf16 v[56:59], v[136:139], v[160:163], v[56:59]
	v_mfma_f32_16x16x32_bf16 v[44:47], v[128:131], v[190:193], v[44:47]
	v_mfma_f32_16x16x32_bf16 v[40:43], v[136:139], v[190:193], v[40:43]
	v_mfma_f32_16x16x32_bf16 v[28:31], v[128:131], v[198:201], v[28:31]
	v_mfma_f32_16x16x32_bf16 v[24:27], v[136:139], v[198:201], v[24:27]
	v_mfma_f32_16x16x32_bf16 v[12:15], v[128:131], v[206:209], v[12:15]
	v_mfma_f32_16x16x32_bf16 v[8:11], v[136:139], v[206:209], v[8:11]
	v_mfma_f32_16x16x32_bf16 v[60:63], v[132:135], v[186:189], v[60:63]
	v_mfma_f32_16x16x32_bf16 v[56:59], v[140:143], v[186:189], v[56:59]
	v_mfma_f32_16x16x32_bf16 v[44:47], v[132:135], v[194:197], v[44:47]
	v_mfma_f32_16x16x32_bf16 v[40:43], v[140:143], v[194:197], v[40:43]
	v_mfma_f32_16x16x32_bf16 v[28:31], v[132:135], v[202:205], v[28:31]
	v_mfma_f32_16x16x32_bf16 v[24:27], v[140:143], v[202:205], v[24:27]
	v_mfma_f32_16x16x32_bf16 v[12:15], v[132:135], v[210:213], v[12:15]
	v_mfma_f32_16x16x32_bf16 v[8:11], v[140:143], v[210:213], v[8:11]
	v_mfma_f32_16x16x32_bf16 v[52:55], v[144:147], v[160:163], v[52:55]
	v_mfma_f32_16x16x32_bf16 v[48:51], v[152:155], v[160:163], v[48:51]
	v_mfma_f32_16x16x32_bf16 v[36:39], v[144:147], v[190:193], v[36:39]
	v_mfma_f32_16x16x32_bf16 v[32:35], v[152:155], v[190:193], v[32:35]
	v_mfma_f32_16x16x32_bf16 v[20:23], v[144:147], v[198:201], v[20:23]
	v_mfma_f32_16x16x32_bf16 v[16:19], v[152:155], v[198:201], v[16:19]
	v_mfma_f32_16x16x32_bf16 v[4:7], v[144:147], v[206:209], v[4:7]
	v_mfma_f32_16x16x32_bf16 v[0:3], v[152:155], v[206:209], v[0:3]
	v_mfma_f32_16x16x32_bf16 v[52:55], v[148:151], v[186:189], v[52:55]
	v_mfma_f32_16x16x32_bf16 v[48:51], v[156:159], v[186:189], v[48:51]
	v_mfma_f32_16x16x32_bf16 v[36:39], v[148:151], v[194:197], v[36:39]
	v_mfma_f32_16x16x32_bf16 v[32:35], v[156:159], v[194:197], v[32:35]
	v_mfma_f32_16x16x32_bf16 v[20:23], v[148:151], v[202:205], v[20:23]
	v_mfma_f32_16x16x32_bf16 v[16:19], v[156:159], v[202:205], v[16:19]
	v_mfma_f32_16x16x32_bf16 v[4:7], v[148:151], v[210:213], v[4:7]
	v_mfma_f32_16x16x32_bf16 v[0:3], v[156:159], v[210:213], v[0:3]
	s_barrier
; #define PG8_STAGE(bufoff, gbase, voff) do { _Pragma("unroll") for (int _i = 0; _i < 2; ++_i) \
;         __builtin_amdgcn_global_load_lds((const unsigned*)((const char*)(gbase) + (voff)[_i]), (PG8_LAS unsigned*)(lds + (bufoff) + ldsw + _i * 8192), 16, 0, 0); } while (0)
; #define PG8_LDA(dst, b, h) do { _Pragma("unroll") for (int m = 0; m < 4; ++m) _Pragma("unroll") for (int k = 0; k < 2; ++k) dst[m][k] = *(const PG8_LAS bf16x8*)(lds + PG8_SA(b, h) + aoff + m * 2048 + k * 1024); } while (0)
; #define PG8_LDB(dst, b, h) do { _Pragma("unroll") for (int n = 0; n < 2; ++n) _Pragma("unroll") for (int k = 0; k < 2; ++k) dst[n][k] = *(const PG8_LAS bf16x8*)(lds + PG8_SB(b, h) + boff + n * 2048 + k * 1024); } while (0)
; #define PG8_MMA(ai, bj, At, Bt) do { __builtin_amdgcn_s_setprio(1); _Pragma("unroll") for (int m = 0; m < 4; ++m) _Pragma("unroll") for (int n = 0; n < 2; ++n) _Pragma("unroll") for (int k = 0; k < 2; ++k) \
;         acc[ai][bj][m][n] = __builtin_amdgcn_mfma_f32_16x16x32_bf16(Bt[n][k], At[m][k], acc[ai][bj][m][n], 0, 0, 0); __builtin_amdgcn_s_setprio(0); } while (0)
; #define PG8_WAIT_V(n) asm volatile("s_waitcnt vmcnt(" #n ")" ::: "memory")
; #define PG8_WAIT_L(n) asm volatile("s_waitcnt lgkmcnt(" #n ")" ::: "memory")
; #define PG8_BAR __builtin_amdgcn_s_barrier()
; template <class Epi, class Sched, bool ALIGN_EPI = false, bool SP2 = false>
; __device__ __forceinline__ void gemm_phase(PG8_LAS unsigned char* lds, const Gemm g, const Sched& S, const Epi& E) {
;     ...
;         for (int t = 0; t < nt; t += 2) {
;             const bool last = (t == nt - 2);
;             const char* a1 = cA + (size_t)(t + 1) * kstepA;
;             const char* a2 = last ? nA : cA + (size_t)(t + 2) * kstepA; const char* b2 = last ? nB : cB + (size_t)(t + 2) * kstep;
;             const char* a3 = a2 + kstepA; const char* b3 = b2 + kstep;
;     ...
;             PG8_LDB(B0, 1, 0); PG8_LDB(B1, 1, 1); PG8_SCHED; PG8_LDA(At, 1, 0); PG8_STAGE(PG8_SA(0, 1), a2 + hstepA, voffA);
;             PG8_WAIT_V(8); PG8_WAIT_L(0); PG8_BAR; PG8_MMA(0, 0, At, B0); PG8_MMA(0, 1, At, B1); PG8_BAR; PG8_SCHED;
;             PG8_LDA(At, 1, 1); PG8_STAGE(PG8_SB(1, 0), b3, voffB); PG8_STAGE(PG8_SB(1, 1), b3 + hstep, voffB); PG8_STAGE(PG8_SA(1, 0), a3, voffA);
;             PG8_WAIT_V(8); PG8_WAIT_L(0); PG8_BAR; PG8_MMA(1, 0, At, B0); PG8_MMA(1, 1, At, B1); PG8_BAR; PG8_SCHED;
	s_add_i32 s89, 0, 0x18000
	s_add_i32 s90, 0, 0x1c000
	ds_read_b128 v[128:131], v214
	ds_read_b128 v[132:135], v214 offset:1024
	ds_read_b128 v[136:139], v214 offset:2048
	ds_read_b128 v[140:143], v214 offset:3072
	ds_read_b128 v[144:147], v215
	ds_read_b128 v[148:151], v215 offset:1024
	ds_read_b128 v[152:155], v215 offset:2048
	ds_read_b128 v[156:159], v215 offset:3072
	s_add_u32 s8, s60, 0x100000
	s_addc_u32 s9, s61, 0
	s_mov_b32 m0, s65
	ds_read_b128 v[160:163], v238 offset:32768
	ds_read_b128 v[186:189], v238 offset:33792
	ds_read_b128 v[190:193], v238 offset:34816
	ds_read_b128 v[194:197], v238 offset:35840
	ds_read_b128 v[198:201], v238 offset:36864
	ds_read_b128 v[202:205], v238 offset:37888
	ds_read_b128 v[206:209], v238 offset:38912
	ds_read_b128 v[210:213], v238 offset:39936
	global_load_lds_dwordx4 v166, s[8:9]
	s_mov_b32 m0, s66
	s_nop 0
	global_load_lds_dwordx4 v170, s[8:9]
	s_waitcnt vmcnt(8) lgkmcnt(0)
	s_barrier
	v_mfma_f32_16x16x32_bf16 v[124:127], v[128:131], v[160:163], v[124:127]
	v_mfma_f32_16x16x32_bf16 v[120:123], v[136:139], v[160:163], v[120:123]
	v_mfma_f32_16x16x32_bf16 v[108:111], v[128:131], v[190:193], v[108:111]
	v_mfma_f32_16x16x32_bf16 v[104:107], v[136:139], v[190:193], v[104:107]
	v_mfma_f32_16x16x32_bf16 v[92:95], v[128:131], v[198:201], v[92:95]
	v_mfma_f32_16x16x32_bf16 v[88:91], v[136:139], v[198:201], v[88:91]
	v_mfma_f32_16x16x32_bf16 v[76:79], v[128:131], v[206:209], v[76:79]
	v_mfma_f32_16x16x32_bf16 v[72:75], v[136:139], v[206:209], v[72:75]
	v_mfma_f32_16x16x32_bf16 v[124:127], v[132:135], v[186:189], v[124:127]
	v_mfma_f32_16x16x32_bf16 v[120:123], v[140:143], v[186:189], v[120:123]
	v_mfma_f32_16x16x32_bf16 v[108:111], v[132:135], v[194:197], v[108:111]
	v_mfma_f32_16x16x32_bf16 v[104:107], v[140:143], v[194:197], v[104:107]
	v_mfma_f32_16x16x32_bf16 v[92:95], v[132:135], v[202:205], v[92:95]
	v_mfma_f32_16x16x32_bf16 v[88:91], v[140:143], v[202:205], v[88:91]
	v_mfma_f32_16x16x32_bf16 v[76:79], v[132:135], v[210:213], v[76:79]
	v_mfma_f32_16x16x32_bf16 v[72:75], v[140:143], v[210:213], v[72:75]
	v_mfma_f32_16x16x32_bf16 v[116:119], v[144:147], v[160:163], v[116:119]
	v_mfma_f32_16x16x32_bf16 v[112:115], v[152:155], v[160:163], v[112:115]
	v_mfma_f32_16x16x32_bf16 v[100:103], v[144:147], v[190:193], v[100:103]
	v_mfma_f32_16x16x32_bf16 v[96:99], v[152:155], v[190:193], v[96:99]
	v_mfma_f32_16x16x32_bf16 v[84:87], v[144:147], v[198:201], v[84:87]
	v_mfma_f32_16x16x32_bf16 v[80:83], v[152:155], v[198:201], v[80:83]
	v_mfma_f32_16x16x32_bf16 v[68:71], v[144:147], v[206:209], v[68:71]
	v_mfma_f32_16x16x32_bf16 v[64:67], v[152:155], v[206:209], v[64:67]
	v_mfma_f32_16x16x32_bf16 v[116:119], v[148:151], v[186:189], v[116:119]
	v_mfma_f32_16x16x32_bf16 v[112:115], v[156:159], v[186:189], v[112:115]
	v_mfma_f32_16x16x32_bf16 v[100:103], v[148:151], v[194:197], v[100:103]
	v_mfma_f32_16x16x32_bf16 v[96:99], v[156:159], v[194:197], v[96:99]
	v_mfma_f32_16x16x32_bf16 v[84:87], v[148:151], v[202:205], v[84:87]
	v_mfma_f32_16x16x32_bf16 v[80:83], v[156:159], v[202:205], v[80:83]
	v_mfma_f32_16x16x32_bf16 v[68:71], v[148:151], v[210:213], v[68:71]
	v_mfma_f32_16x16x32_bf16 v[64:67], v[156:159], v[210:213], v[64:67]
	s_barrier
	s_add_i32 s8, s89, s63
	s_mov_b32 m0, s8
	ds_read_b128 v[160:163], v238 offset:49152
	ds_read_b128 v[186:189], v238 offset:50176
	ds_read_b128 v[190:193], v238 offset:51200
	ds_read_b128 v[194:197], v238 offset:52224
	ds_read_b128 v[198:201], v238 offset:53248
	ds_read_b128 v[202:205], v238 offset:54272
	ds_read_b128 v[206:209], v238 offset:55296
	ds_read_b128 v[210:213], v238 offset:56320
	global_load_lds_dwordx4 v168, s[98:99]
	s_add_i32 m0, s8, 0x2000
	s_add_u32 s8, s58, 0x100080
	s_addc_u32 s9, s59, 0
	s_add_i32 s58, s90, s63
	global_load_lds_dwordx4 v172, s[98:99]
	s_mov_b32 m0, s58
	s_nop 0
	global_load_lds_dwordx4 v168, s[8:9]
	s_add_i32 m0, s58, 0x2000
	s_nop 0
	global_load_lds_dwordx4 v172, s[8:9]
	s_mov_b32 m0, s70
	s_nop 0
	global_load_lds_dwordx4 v166, s[100:101]
	s_mov_b32 m0, s71
	s_nop 0
	global_load_lds_dwordx4 v170, s[100:101]
	s_add_i32 s88, s88, 2
	s_add_u32 s86, s86, 0x100
	s_addc_u32 s87, s87, 0
	s_cmp_gt_u32 s88, 61
	s_mov_b64 s[8:9], s[10:11]
	s_waitcnt vmcnt(8) lgkmcnt(0)
	s_barrier
	v_mfma_f32_16x16x32_bf16 v[60:63], v[128:131], v[160:163], v[60:63]
	v_mfma_f32_16x16x32_bf16 v[56:59], v[136:139], v[160:163], v[56:59]
	v_mfma_f32_16x16x32_bf16 v[44:47], v[128:131], v[190:193], v[44:47]
	v_mfma_f32_16x16x32_bf16 v[40:43], v[136:139], v[190:193], v[40:43]
	v_mfma_f32_16x16x32_bf16 v[28:31], v[128:131], v[198:201], v[28:31]
	v_mfma_f32_16x16x32_bf16 v[24:27], v[136:139], v[198:201], v[24:27]
	v_mfma_f32_16x16x32_bf16 v[12:15], v[128:131], v[206:209], v[12:15]
	v_mfma_f32_16x16x32_bf16 v[8:11], v[136:139], v[206:209], v[8:11]
	v_mfma_f32_16x16x32_bf16 v[60:63], v[132:135], v[186:189], v[60:63]
	v_mfma_f32_16x16x32_bf16 v[56:59], v[140:143], v[186:189], v[56:59]
	v_mfma_f32_16x16x32_bf16 v[44:47], v[132:135], v[194:197], v[44:47]
	v_mfma_f32_16x16x32_bf16 v[40:43], v[140:143], v[194:197], v[40:43]
	v_mfma_f32_16x16x32_bf16 v[28:31], v[132:135], v[202:205], v[28:31]
	v_mfma_f32_16x16x32_bf16 v[24:27], v[140:143], v[202:205], v[24:27]
	v_mfma_f32_16x16x32_bf16 v[12:15], v[132:135], v[210:213], v[12:15]
	v_mfma_f32_16x16x32_bf16 v[8:11], v[140:143], v[210:213], v[8:11]
	v_mfma_f32_16x16x32_bf16 v[52:55], v[144:147], v[160:163], v[52:55]
	v_mfma_f32_16x16x32_bf16 v[48:51], v[152:155], v[160:163], v[48:51]
	v_mfma_f32_16x16x32_bf16 v[36:39], v[144:147], v[190:193], v[36:39]
	v_mfma_f32_16x16x32_bf16 v[32:35], v[152:155], v[190:193], v[32:35]
	v_mfma_f32_16x16x32_bf16 v[20:23], v[144:147], v[198:201], v[20:23]
	v_mfma_f32_16x16x32_bf16 v[16:19], v[152:155], v[198:201], v[16:19]
	v_mfma_f32_16x16x32_bf16 v[4:7], v[144:147], v[206:209], v[4:7]
	v_mfma_f32_16x16x32_bf16 v[0:3], v[152:155], v[206:209], v[0:3]
	v_mfma_f32_16x16x32_bf16 v[52:55], v[148:151], v[186:189], v[52:55]
	v_mfma_f32_16x16x32_bf16 v[48:51], v[156:159], v[186:189], v[48:51]
	v_mfma_f32_16x16x32_bf16 v[36:39], v[148:151], v[194:197], v[36:39]
	v_mfma_f32_16x16x32_bf16 v[32:35], v[156:159], v[194:197], v[32:35]
	v_mfma_f32_16x16x32_bf16 v[20:23], v[148:151], v[202:205], v[20:23]
	v_mfma_f32_16x16x32_bf16 v[16:19], v[156:159], v[202:205], v[16:19]
	v_mfma_f32_16x16x32_bf16 v[4:7], v[148:151], v[210:213], v[4:7]
	v_mfma_f32_16x16x32_bf16 v[0:3], v[156:159], v[210:213], v[0:3]
	s_barrier
	s_cbranch_scc0 .LBB0_2882
	s_and_b64 vcc, exec, s[18:19]
	s_cbranch_vccz .LBB0_2885
	s_barrier

; #define PG8_STAGE(bufoff, gbase, voff) do { _Pragma("unroll") for (int _i = 0; _i < 2; ++_i) \
;         __builtin_amdgcn_global_load_lds((const unsigned*)((const char*)(gbase) + (voff)[_i]), (PG8_LAS unsigned*)(lds + (bufoff) + ldsw + _i * 8192), 16, 0, 0); } while (0)
; #define PG8_LDA(dst, b, h) do { _Pragma("unroll") for (int m = 0; m < 4; ++m) _Pragma("unroll") for (int k = 0; k < 2; ++k) dst[m][k] = *(const PG8_LAS bf16x8*)(lds + PG8_SA(b, h) + aoff + m * 2048 + k * 1024); } while (0)
; #define PG8_LDB(dst, b, h) do { _Pragma("unroll") for (int n = 0; n < 2; ++n) _Pragma("unroll") for (int k = 0; k < 2; ++k) dst[n][k] = *(const PG8_LAS bf16x8*)(lds + PG8_SB(b, h) + boff + n * 2048 + k * 1024); } while (0)
; #define PG8_WAIT_V(n) asm volatile("s_waitcnt vmcnt(" #n ")" ::: "memory")
; #define PG8_WAIT_L(n) asm volatile("s_waitcnt lgkmcnt(" #n ")" ::: "memory")
; #define PG8_BAR __builtin_amdgcn_s_barrier()
; #define PG8_SCHED __builtin_amdgcn_sched_barrier(0)
; template <class Epi, class Sched, bool ALIGN_EPI = false, bool SP2 = false>
; __device__ __forceinline__ void gemm_phase(PG8_LAS unsigned char* lds, const Gemm g, const Sched& S, const Epi& E) {
;     ...
;         const char* nA = has_next ? (const char*)g.A + (size_t)nxt.pm * tstep : cA; const char* nB = has_next ? (const char*)g.Bt + (size_t)nxt.pn * tstep : cB;
;         for (int t = 0; t < nt; t += 2) {
;             const bool last = (t == nt - 2);
;             const char* a1 = cA + (size_t)(t + 1) * kstepA;
;             const char* a2 = last ? nA : cA + (size_t)(t + 2) * kstepA; const char* b2 = last ? nB : cB + (size_t)(t + 2) * kstep;
;             const char* a3 = a2 + kstepA; const char* b3 = b2 + kstep;
;             if (last && has_next) S.a_ready(nxt);
;             if constexpr (SP2) {
;             PG8_LDB(B0, 0, 0); PG8_LDB(B1, 0, 1); PG8_SCHED; PG8_LDA(At, 0, 0); PG8_STAGE(PG8_SA(1, 1), a1 + hstepA, voffA);
;             PG8_WAIT_V(8); PG8_WAIT_L(0); PG8_BAR; PG8_MMA(0, 0, At, B0); PG8_MMA(0, 1, At, B1); PG8_BAR; PG8_SCHED;
;             PG8_LDA(At, 0, 1); PG8_STAGE(PG8_SB(0, 0), b2, voffB); PG8_STAGE(PG8_SB(0, 1), b2 + hstep, voffB); PG8_STAGE(PG8_SA(0, 0), a2, voffA);
;             PG8_WAIT_V(8); PG8_WAIT_L(0); PG8_BAR; PG8_MMA(1, 0, At, B0); PG8_MMA(1, 1, At, B1); PG8_BAR; PG8_SCHED;
.LBB0_3087:
	ds_read_b128 v[144:147], v153
	ds_read_b128 v[158:161], v153 offset:1024
	ds_read_b128 v[162:165], v153 offset:2048
	ds_read_b128 v[166:169], v153 offset:3072
	ds_read_b128 v[170:173], v154
	ds_read_b128 v[174:177], v154 offset:1024
	ds_read_b128 v[178:181], v154 offset:2048
	ds_read_b128 v[182:185], v154 offset:3072
	s_add_u32 s36, s34, 0x4000
	s_addc_u32 s37, s35, 0
	s_cmpk_eq_i32 s65, 0xa8
	s_cselect_b32 s42, s6, s36
	s_cselect_b32 s43, s7, s37
	s_cselect_b32 s40, s30, s63
	s_cselect_b32 s41, s31, s64
	s_add_u32 s36, s42, 0x8000
	s_addc_u32 s37, s43, 0
	s_add_i32 m0, s44, 0xc000
	ds_read_b128 v[186:189], v155
	ds_read_b128 v[190:193], v155 offset:1024
	ds_read_b128 v[194:197], v155 offset:2048
	ds_read_b128 v[198:201], v155 offset:3072
	ds_read_b128 v[202:205], v155 offset:4096
	ds_read_b128 v[206:209], v155 offset:5120
	ds_read_b128 v[210:213], v155 offset:6144
	ds_read_b128 v[214:217], v155 offset:7168
	global_load_lds_dwordx4 v136, s[34:35]
	s_add_i32 m0, s44, 0xe000
	s_nop 0
	global_load_lds_dwordx4 v138, s[34:35]
	s_waitcnt vmcnt(8) lgkmcnt(0)
	s_barrier
	v_mfma_f32_16x16x32_bf16 v[124:127], v[144:147], v[186:189], v[124:127]
	v_mfma_f32_16x16x32_bf16 v[120:123], v[162:165], v[186:189], v[120:123]
	v_mfma_f32_16x16x32_bf16 v[108:111], v[144:147], v[194:197], v[108:111]
	v_mfma_f32_16x16x32_bf16 v[104:107], v[162:165], v[194:197], v[104:107]
	v_mfma_f32_16x16x32_bf16 v[92:95], v[144:147], v[202:205], v[92:95]
	v_mfma_f32_16x16x32_bf16 v[88:91], v[162:165], v[202:205], v[88:91]
	v_mfma_f32_16x16x32_bf16 v[76:79], v[144:147], v[210:213], v[76:79]
	v_mfma_f32_16x16x32_bf16 v[72:75], v[162:165], v[210:213], v[72:75]
	v_mfma_f32_16x16x32_bf16 v[124:127], v[158:161], v[190:193], v[124:127]
	v_mfma_f32_16x16x32_bf16 v[120:123], v[166:169], v[190:193], v[120:123]
	v_mfma_f32_16x16x32_bf16 v[108:111], v[158:161], v[198:201], v[108:111]
	v_mfma_f32_16x16x32_bf16 v[104:107], v[166:169], v[198:201], v[104:107]
	v_mfma_f32_16x16x32_bf16 v[92:95], v[158:161], v[206:209], v[92:95]
	v_mfma_f32_16x16x32_bf16 v[88:91], v[166:169], v[206:209], v[88:91]
	v_mfma_f32_16x16x32_bf16 v[76:79], v[158:161], v[214:217], v[76:79]
	v_mfma_f32_16x16x32_bf16 v[72:75], v[166:169], v[214:217], v[72:75]
	v_mfma_f32_16x16x32_bf16 v[116:119], v[170:173], v[186:189], v[116:119]
	v_mfma_f32_16x16x32_bf16 v[112:115], v[178:181], v[186:189], v[112:115]
	v_mfma_f32_16x16x32_bf16 v[100:103], v[170:173], v[194:197], v[100:103]
	v_mfma_f32_16x16x32_bf16 v[96:99], v[178:181], v[194:197], v[96:99]
	v_mfma_f32_16x16x32_bf16 v[84:87], v[170:173], v[202:205], v[84:87]
	v_mfma_f32_16x16x32_bf16 v[80:83], v[178:181], v[202:205], v[80:83]
	v_mfma_f32_16x16x32_bf16 v[68:71], v[170:173], v[210:213], v[68:71]
	v_mfma_f32_16x16x32_bf16 v[64:67], v[178:181], v[210:213], v[64:67]
	v_mfma_f32_16x16x32_bf16 v[116:119], v[174:177], v[190:193], v[116:119]
	v_mfma_f32_16x16x32_bf16 v[112:115], v[182:185], v[190:193], v[112:115]
	v_mfma_f32_16x16x32_bf16 v[100:103], v[174:177], v[198:201], v[100:103]
	v_mfma_f32_16x16x32_bf16 v[96:99], v[182:185], v[198:201], v[96:99]
	v_mfma_f32_16x16x32_bf16 v[84:87], v[174:177], v[206:209], v[84:87]
	v_mfma_f32_16x16x32_bf16 v[80:83], v[182:185], v[206:209], v[80:83]
	v_mfma_f32_16x16x32_bf16 v[68:71], v[174:177], v[214:217], v[68:71]
	v_mfma_f32_16x16x32_bf16 v[64:67], v[182:185], v[214:217], v[64:67]
	s_barrier
	s_add_u32 s98, s40, s16
	s_addc_u32 s99, s41, s17
	s_add_i32 s66, s53, s33
	s_mov_b32 m0, s66
	ds_read_b128 v[186:189], v155 offset:16384
	ds_read_b128 v[190:193], v155 offset:17408
	ds_read_b128 v[194:197], v155 offset:18432
	ds_read_b128 v[198:201], v155 offset:19456
	ds_read_b128 v[202:205], v155 offset:20480
	ds_read_b128 v[206:209], v155 offset:21504
	ds_read_b128 v[210:213], v155 offset:22528
	ds_read_b128 v[214:217], v155 offset:23552
	global_load_lds_dwordx4 v130, s[40:41]
	s_add_i32 m0, s66, 0x2000
	s_add_u32 s66, s40, 0x2b0000
	s_addc_u32 s67, s41, 0
	s_add_i32 s68, s54, s33
	global_load_lds_dwordx4 v134, s[40:41]
	s_mov_b32 m0, s68
	s_nop 0
	global_load_lds_dwordx4 v130, s[66:67]
	s_add_i32 m0, s68, 0x2000
	s_nop 0
	global_load_lds_dwordx4 v134, s[66:67]
	s_mov_b32 m0, s44
	s_nop 0
	global_load_lds_dwordx4 v128, s[42:43]
	s_mov_b32 m0, s45
	s_nop 0
	global_load_lds_dwordx4 v132, s[42:43]
	s_waitcnt vmcnt(8) lgkmcnt(0)
	s_barrier
	v_mfma_f32_16x16x32_bf16 v[60:63], v[144:147], v[186:189], v[60:63]
	v_mfma_f32_16x16x32_bf16 v[56:59], v[162:165], v[186:189], v[56:59]
	v_mfma_f32_16x16x32_bf16 v[44:47], v[144:147], v[194:197], v[44:47]
	v_mfma_f32_16x16x32_bf16 v[40:43], v[162:165], v[194:197], v[40:43]
	v_mfma_f32_16x16x32_bf16 v[28:31], v[144:147], v[202:205], v[28:31]
	v_mfma_f32_16x16x32_bf16 v[24:27], v[162:165], v[202:205], v[24:27]
	v_mfma_f32_16x16x32_bf16 v[12:15], v[144:147], v[210:213], v[12:15]
	v_mfma_f32_16x16x32_bf16 v[8:11], v[162:165], v[210:213], v[8:11]
	v_mfma_f32_16x16x32_bf16 v[60:63], v[158:161], v[190:193], v[60:63]
	v_mfma_f32_16x16x32_bf16 v[56:59], v[166:169], v[190:193], v[56:59]
	v_mfma_f32_16x16x32_bf16 v[44:47], v[158:161], v[198:201], v[44:47]
	v_mfma_f32_16x16x32_bf16 v[40:43], v[166:169], v[198:201], v[40:43]
	v_mfma_f32_16x16x32_bf16 v[28:31], v[158:161], v[206:209], v[28:31]
	v_mfma_f32_16x16x32_bf16 v[24:27], v[166:169], v[206:209], v[24:27]
	v_mfma_f32_16x16x32_bf16 v[12:15], v[158:161], v[214:217], v[12:15]
	v_mfma_f32_16x16x32_bf16 v[8:11], v[166:169], v[214:217], v[8:11]
	v_mfma_f32_16x16x32_bf16 v[52:55], v[170:173], v[186:189], v[52:55]
	v_mfma_f32_16x16x32_bf16 v[48:51], v[178:181], v[186:189], v[48:51]
	v_mfma_f32_16x16x32_bf16 v[36:39], v[170:173], v[194:197], v[36:39]
	v_mfma_f32_16x16x32_bf16 v[32:35], v[178:181], v[194:197], v[32:35]
	v_mfma_f32_16x16x32_bf16 v[20:23], v[170:173], v[202:205], v[20:23]
	v_mfma_f32_16x16x32_bf16 v[16:19], v[178:181], v[202:205], v[16:19]
	v_mfma_f32_16x16x32_bf16 v[4:7], v[170:173], v[210:213], v[4:7]
	v_mfma_f32_16x16x32_bf16 v[0:3], v[178:181], v[210:213], v[0:3]
	v_mfma_f32_16x16x32_bf16 v[52:55], v[174:177], v[190:193], v[52:55]
	v_mfma_f32_16x16x32_bf16 v[48:51], v[182:185], v[190:193], v[48:51]
	v_mfma_f32_16x16x32_bf16 v[36:39], v[174:177], v[198:201], v[36:39]
	v_mfma_f32_16x16x32_bf16 v[32:35], v[182:185], v[198:201], v[32:35]
	v_mfma_f32_16x16x32_bf16 v[20:23], v[174:177], v[206:209], v[20:23]
	v_mfma_f32_16x16x32_bf16 v[16:19], v[182:185], v[206:209], v[16:19]
	v_mfma_f32_16x16x32_bf16 v[4:7], v[174:177], v[214:217], v[4:7]
	v_mfma_f32_16x16x32_bf16 v[0:3], v[182:185], v[214:217], v[0:3]
	s_barrier
; #define PG8_STAGE(bufoff, gbase, voff) do { _Pragma("unroll") for (int _i = 0; _i < 2; ++_i) \
;         __builtin_amdgcn_global_load_lds((const unsigned*)((const char*)(gbase) + (voff)[_i]), (PG8_LAS unsigned*)(lds + (bufoff) + ldsw + _i * 8192), 16, 0, 0); } while (0)
; #define PG8_LDA(dst, b, h) do { _Pragma("unroll") for (int m = 0; m < 4; ++m) _Pragma("unroll") for (int k = 0; k < 2; ++k) dst[m][k] = *(const PG8_LAS bf16x8*)(lds + PG8_SA(b, h) + aoff + m * 2048 + k * 1024); } while (0)
; #define PG8_LDB(dst, b, h) do { _Pragma("unroll") for (int n = 0; n < 2; ++n) _Pragma("unroll") for (int k = 0; k < 2; ++k) dst[n][k] = *(const PG8_LAS bf16x8*)(lds + PG8_SB(b, h) + boff + n * 2048 + k * 1024); } while (0)
; template <class Epi, class Sched, bool ALIGN_EPI = false, bool SP2 = false>
; __device__ __forceinline__ void gemm_phase(PG8_LAS unsigned char* lds, const Gemm g, const Sched& S, const Epi& E) {
;     ...
;         for (int t = 0; t < nt; t += 2) {
;             const bool last = (t == nt - 2);
;             const char* a1 = cA + (size_t)(t + 1) * kstepA;
;             const char* a2 = last ? nA : cA + (size_t)(t + 2) * kstepA; const char* b2 = last ? nB : cB + (size_t)(t + 2) * kstep;
;             const char* a3 = a2 + kstepA; const char* b3 = b2 + kstep;
;             if (last && has_next) S.a_ready(nxt);
;             if constexpr (SP2) {
;             PG8_LDB(B0, 0, 0); PG8_LDB(B1, 0, 1); PG8_SCHED; PG8_LDA(At, 0, 0); PG8_STAGE(PG8_SA(1, 1), a1 + hstepA, voffA);
;             PG8_WAIT_V(8); PG8_WAIT_L(0); PG8_BAR; PG8_MMA(0, 0, At, B0); PG8_MMA(0, 1, At, B1); PG8_BAR; PG8_SCHED;
;             PG8_LDA(At, 0, 1); PG8_STAGE(PG8_SB(0, 0), b2, voffB); PG8_STAGE(PG8_SB(0, 1), b2 + hstep, voffB); PG8_STAGE(PG8_SA(0, 0), a2, voffA);
;             PG8_WAIT_V(8); PG8_WAIT_L(0); PG8_BAR; PG8_MMA(1, 0, At, B0); PG8_MMA(1, 1, At, B1); PG8_BAR; PG8_SCHED;
;             PG8_LDB(B0, 1, 0); PG8_LDB(B1, 1, 1); PG8_SCHED; PG8_LDA(At, 1, 0); PG8_STAGE(PG8_SA(0, 1), a2 + hstepA, voffA);
;             PG8_WAIT_V(8); PG8_WAIT_L(0); PG8_BAR; PG8_MMA(0, 0, At, B0); PG8_MMA(0, 1, At, B1); PG8_BAR; PG8_SCHED;
;             PG8_LDA(At, 1, 1); PG8_STAGE(PG8_SB(1, 0), b3, voffB); PG8_STAGE(PG8_SB(1, 1), b3 + hstep, voffB); PG8_STAGE(PG8_SA(1, 0), a3, voffA);
;             PG8_WAIT_V(8); PG8_WAIT_L(0); PG8_BAR; PG8_MMA(1, 0, At, B0); PG8_MMA(1, 1, At, B1); PG8_BAR; PG8_SCHED;
	s_add_i32 s66, 0, 0x18000
	s_add_i32 s67, 0, 0x1c000
	ds_read_b128 v[144:147], v148
	ds_read_b128 v[158:161], v148 offset:1024
	ds_read_b128 v[162:165], v148 offset:2048
	ds_read_b128 v[166:169], v148 offset:3072
	ds_read_b128 v[170:173], v149
	ds_read_b128 v[174:177], v149 offset:1024
	ds_read_b128 v[178:181], v149 offset:2048
	ds_read_b128 v[182:185], v149 offset:3072
	s_add_u32 s42, s42, 0x4000
	s_addc_u32 s43, s43, 0
	s_mov_b32 m0, s46
	ds_read_b128 v[186:189], v155 offset:32768
	ds_read_b128 v[190:193], v155 offset:33792
	ds_read_b128 v[194:197], v155 offset:34816
	ds_read_b128 v[198:201], v155 offset:35840
	ds_read_b128 v[202:205], v155 offset:36864
	ds_read_b128 v[206:209], v155 offset:37888
	ds_read_b128 v[210:213], v155 offset:38912
	ds_read_b128 v[214:217], v155 offset:39936
	global_load_lds_dwordx4 v128, s[42:43]
	s_mov_b32 m0, s47
	s_nop 0
	global_load_lds_dwordx4 v132, s[42:43]
	s_waitcnt vmcnt(8) lgkmcnt(0)
	s_barrier
	v_mfma_f32_16x16x32_bf16 v[124:127], v[144:147], v[186:189], v[124:127]
	v_mfma_f32_16x16x32_bf16 v[120:123], v[162:165], v[186:189], v[120:123]
	v_mfma_f32_16x16x32_bf16 v[108:111], v[144:147], v[194:197], v[108:111]
	v_mfma_f32_16x16x32_bf16 v[104:107], v[162:165], v[194:197], v[104:107]
	v_mfma_f32_16x16x32_bf16 v[92:95], v[144:147], v[202:205], v[92:95]
	v_mfma_f32_16x16x32_bf16 v[88:91], v[162:165], v[202:205], v[88:91]
	v_mfma_f32_16x16x32_bf16 v[76:79], v[144:147], v[210:213], v[76:79]
	v_mfma_f32_16x16x32_bf16 v[72:75], v[162:165], v[210:213], v[72:75]
	v_mfma_f32_16x16x32_bf16 v[124:127], v[158:161], v[190:193], v[124:127]
	v_mfma_f32_16x16x32_bf16 v[120:123], v[166:169], v[190:193], v[120:123]
	v_mfma_f32_16x16x32_bf16 v[108:111], v[158:161], v[198:201], v[108:111]
	v_mfma_f32_16x16x32_bf16 v[104:107], v[166:169], v[198:201], v[104:107]
	v_mfma_f32_16x16x32_bf16 v[92:95], v[158:161], v[206:209], v[92:95]
	v_mfma_f32_16x16x32_bf16 v[88:91], v[166:169], v[206:209], v[88:91]
	v_mfma_f32_16x16x32_bf16 v[76:79], v[158:161], v[214:217], v[76:79]
	v_mfma_f32_16x16x32_bf16 v[72:75], v[166:169], v[214:217], v[72:75]
	v_mfma_f32_16x16x32_bf16 v[116:119], v[170:173], v[186:189], v[116:119]
	v_mfma_f32_16x16x32_bf16 v[112:115], v[178:181], v[186:189], v[112:115]
	v_mfma_f32_16x16x32_bf16 v[100:103], v[170:173], v[194:197], v[100:103]
	v_mfma_f32_16x16x32_bf16 v[96:99], v[178:181], v[194:197], v[96:99]
	v_mfma_f32_16x16x32_bf16 v[84:87], v[170:173], v[202:205], v[84:87]
	v_mfma_f32_16x16x32_bf16 v[80:83], v[178:181], v[202:205], v[80:83]
	v_mfma_f32_16x16x32_bf16 v[68:71], v[170:173], v[210:213], v[68:71]
	v_mfma_f32_16x16x32_bf16 v[64:67], v[178:181], v[210:213], v[64:67]
	v_mfma_f32_16x16x32_bf16 v[116:119], v[174:177], v[190:193], v[116:119]
	v_mfma_f32_16x16x32_bf16 v[112:115], v[182:185], v[190:193], v[112:115]
	v_mfma_f32_16x16x32_bf16 v[100:103], v[174:177], v[198:201], v[100:103]
	v_mfma_f32_16x16x32_bf16 v[96:99], v[182:185], v[198:201], v[96:99]
	v_mfma_f32_16x16x32_bf16 v[84:87], v[174:177], v[206:209], v[84:87]
	v_mfma_f32_16x16x32_bf16 v[80:83], v[182:185], v[206:209], v[80:83]
	v_mfma_f32_16x16x32_bf16 v[68:71], v[174:177], v[214:217], v[68:71]
	v_mfma_f32_16x16x32_bf16 v[64:67], v[182:185], v[214:217], v[64:67]
	s_barrier
	s_add_i32 s42, s66, s33
	s_mov_b32 m0, s42
	ds_read_b128 v[186:189], v155 offset:49152
	ds_read_b128 v[190:193], v155 offset:50176
	ds_read_b128 v[194:197], v155 offset:51200
	ds_read_b128 v[198:201], v155 offset:52224
	ds_read_b128 v[202:205], v155 offset:53248
	ds_read_b128 v[206:209], v155 offset:54272
	ds_read_b128 v[210:213], v155 offset:55296
	ds_read_b128 v[214:217], v155 offset:56320
	global_load_lds_dwordx4 v130, s[98:99]
	s_add_i32 m0, s42, 0x2000
	s_add_u32 s40, s40, 0x2b0080
	s_addc_u32 s41, s41, 0
	s_add_i32 s42, s67, s33
	global_load_lds_dwordx4 v134, s[98:99]
	s_mov_b32 m0, s42
	s_nop 0
	global_load_lds_dwordx4 v130, s[40:41]
	s_add_i32 m0, s42, 0x2000
	s_nop 0
	global_load_lds_dwordx4 v134, s[40:41]
	s_mov_b32 m0, s49
	s_nop 0
	global_load_lds_dwordx4 v128, s[36:37]
	s_mov_b32 m0, s50
	s_nop 0
	global_load_lds_dwordx4 v132, s[36:37]
	s_add_i32 s65, s65, 2
	s_add_u32 s63, s63, 0x100
	s_addc_u32 s64, s64, 0
	s_add_u32 s34, s34, 0x10000
	s_addc_u32 s35, s35, 0
	s_cmpk_gt_u32 s65, 0xa9
	s_waitcnt vmcnt(8) lgkmcnt(0)
	s_barrier
	v_mfma_f32_16x16x32_bf16 v[60:63], v[144:147], v[186:189], v[60:63]
	v_mfma_f32_16x16x32_bf16 v[56:59], v[162:165], v[186:189], v[56:59]
	v_mfma_f32_16x16x32_bf16 v[44:47], v[144:147], v[194:197], v[44:47]
	v_mfma_f32_16x16x32_bf16 v[40:43], v[162:165], v[194:197], v[40:43]
	v_mfma_f32_16x16x32_bf16 v[28:31], v[144:147], v[202:205], v[28:31]
	v_mfma_f32_16x16x32_bf16 v[24:27], v[162:165], v[202:205], v[24:27]
	v_mfma_f32_16x16x32_bf16 v[12:15], v[144:147], v[210:213], v[12:15]
	v_mfma_f32_16x16x32_bf16 v[8:11], v[162:165], v[210:213], v[8:11]
	v_mfma_f32_16x16x32_bf16 v[60:63], v[158:161], v[190:193], v[60:63]
	v_mfma_f32_16x16x32_bf16 v[56:59], v[166:169], v[190:193], v[56:59]
	v_mfma_f32_16x16x32_bf16 v[44:47], v[158:161], v[198:201], v[44:47]
	v_mfma_f32_16x16x32_bf16 v[40:43], v[166:169], v[198:201], v[40:43]
	v_mfma_f32_16x16x32_bf16 v[28:31], v[158:161], v[206:209], v[28:31]
	v_mfma_f32_16x16x32_bf16 v[24:27], v[166:169], v[206:209], v[24:27]
	v_mfma_f32_16x16x32_bf16 v[12:15], v[158:161], v[214:217], v[12:15]
	v_mfma_f32_16x16x32_bf16 v[8:11], v[166:169], v[214:217], v[8:11]
	v_mfma_f32_16x16x32_bf16 v[52:55], v[170:173], v[186:189], v[52:55]
	v_mfma_f32_16x16x32_bf16 v[48:51], v[178:181], v[186:189], v[48:51]
	v_mfma_f32_16x16x32_bf16 v[36:39], v[170:173], v[194:197], v[36:39]
	v_mfma_f32_16x16x32_bf16 v[32:35], v[178:181], v[194:197], v[32:35]
	v_mfma_f32_16x16x32_bf16 v[20:23], v[170:173], v[202:205], v[20:23]
	v_mfma_f32_16x16x32_bf16 v[16:19], v[178:181], v[202:205], v[16:19]
	v_mfma_f32_16x16x32_bf16 v[4:7], v[170:173], v[210:213], v[4:7]
	v_mfma_f32_16x16x32_bf16 v[0:3], v[178:181], v[210:213], v[0:3]
	v_mfma_f32_16x16x32_bf16 v[52:55], v[174:177], v[190:193], v[52:55]
	v_mfma_f32_16x16x32_bf16 v[48:51], v[182:185], v[190:193], v[48:51]
	v_mfma_f32_16x16x32_bf16 v[36:39], v[174:177], v[198:201], v[36:39]
	v_mfma_f32_16x16x32_bf16 v[32:35], v[182:185], v[198:201], v[32:35]
	v_mfma_f32_16x16x32_bf16 v[20:23], v[174:177], v[206:209], v[20:23]
	v_mfma_f32_16x16x32_bf16 v[16:19], v[182:185], v[206:209], v[16:19]
	v_mfma_f32_16x16x32_bf16 v[4:7], v[174:177], v[214:217], v[4:7]
	v_mfma_f32_16x16x32_bf16 v[0:3], v[182:185], v[214:217], v[0:3]
	s_barrier
	s_cbranch_scc0 .LBB0_3087
	s_and_b64 vcc, exec, s[18:19]
	s_cbranch_vccz .LBB0_3090
	s_barrier

; #define PG8_STAGE(bufoff, gbase, voff) do { _Pragma("unroll") for (int _i = 0; _i < 2; ++_i) \
;         __builtin_amdgcn_global_load_lds((const unsigned*)((const char*)(gbase) + (voff)[_i]), (PG8_LAS unsigned*)(lds + (bufoff) + ldsw + _i * 8192), 16, 0, 0); } while (0)
; #define PG8_LDA(dst, b, h) do { _Pragma("unroll") for (int m = 0; m < 4; ++m) _Pragma("unroll") for (int k = 0; k < 2; ++k) dst[m][k] = *(const PG8_LAS bf16x8*)(lds + PG8_SA(b, h) + aoff + m * 2048 + k * 1024); } while (0)
; #define PG8_LDB(dst, b, h) do { _Pragma("unroll") for (int n = 0; n < 2; ++n) _Pragma("unroll") for (int k = 0; k < 2; ++k) dst[n][k] = *(const PG8_LAS bf16x8*)(lds + PG8_SB(b, h) + boff + n * 2048 + k * 1024); } while (0)
; #define PG8_MMA(ai, bj, At, Bt) do { __builtin_amdgcn_s_setprio(1); _Pragma("unroll") for (int m = 0; m < 4; ++m) _Pragma("unroll") for (int n = 0; n < 2; ++n) _Pragma("unroll") for (int k = 0; k < 2; ++k) \
;         acc[ai][bj][m][n] = __builtin_amdgcn_mfma_f32_16x16x32_bf16(Bt[n][k], At[m][k], acc[ai][bj][m][n], 0, 0, 0); __builtin_amdgcn_s_setprio(0); } while (0)
; #define PG8_WAIT_V(n) asm volatile("s_waitcnt vmcnt(" #n ")" ::: "memory")
; #define PG8_BAR __builtin_amdgcn_s_barrier()
; template <class Epi, class Sched, bool ALIGN_EPI = false, bool SP2 = false>
; __device__ __forceinline__ void gemm_phase(PG8_LAS unsigned char* lds, const Gemm g, const Sched& S, const Epi& E) {
;     ...
;         for (int t = 0; t < nt; t += 2) {
;             const bool last = (t == nt - 2);
;             const char* a1 = cA + (size_t)(t + 1) * kstepA;
;             const char* a2 = last ? nA : cA + (size_t)(t + 2) * kstepA; const char* b2 = last ? nB : cB + (size_t)(t + 2) * kstep;
;             const char* a3 = a2 + kstepA; const char* b3 = b2 + kstep;
;             if (last && has_next) S.a_ready(nxt);
;             if constexpr (SP2) {
;             PG8_LDB(B0, 0, 0); PG8_LDB(B1, 0, 1); PG8_SCHED; PG8_LDA(At, 0, 0); PG8_STAGE(PG8_SA(1, 1), a1 + hstepA, voffA);
;             PG8_WAIT_V(8); PG8_WAIT_L(0); PG8_BAR; PG8_MMA(0, 0, At, B0); PG8_MMA(0, 1, At, B1); PG8_BAR; PG8_SCHED;
;             PG8_LDA(At, 0, 1); PG8_STAGE(PG8_SB(0, 0), b2, voffB); PG8_STAGE(PG8_SB(0, 1), b2 + hstep, voffB); PG8_STAGE(PG8_SA(0, 0), a2, voffA);
;             PG8_WAIT_V(8); PG8_WAIT_L(0); PG8_BAR; PG8_MMA(1, 0, At, B0); PG8_MMA(1, 1, At, B1); PG8_BAR; PG8_SCHED;
.LBB0_3203:
	ds_read_b128 v[144:147], v155
	ds_read_b128 v[148:151], v155 offset:1024
	ds_read_b128 v[160:163], v155 offset:2048
	ds_read_b128 v[164:167], v155 offset:3072
	ds_read_b128 v[168:171], v156
	ds_read_b128 v[172:175], v156 offset:1024
	ds_read_b128 v[176:179], v156 offset:2048
	ds_read_b128 v[180:183], v156 offset:3072
	s_add_u32 s58, s56, 0xfff00080
	s_addc_u32 s59, s57, -1
	s_cmp_eq_u32 s74, 60
	s_cselect_b32 s61, s47, s59
	s_cselect_b32 s60, s53, s58
	s_cselect_b32 s59, s45, s73
	s_cselect_b32 s58, s71, s72
	s_add_i32 m0, s29, 0xc000
	ds_read_b128 v[184:187], v157
	ds_read_b128 v[188:191], v157 offset:1024
	ds_read_b128 v[192:195], v157 offset:2048
	ds_read_b128 v[196:199], v157 offset:3072
	ds_read_b128 v[200:203], v157 offset:4096
	ds_read_b128 v[204:207], v157 offset:5120
	ds_read_b128 v[208:211], v157 offset:6144
	ds_read_b128 v[212:215], v157 offset:7168
	global_load_lds_dwordx4 v136, s[56:57]
	s_add_i32 m0, s29, 0xe000
	s_nop 0
	global_load_lds_dwordx4 v138, s[56:57]
	s_waitcnt vmcnt(8) lgkmcnt(0)
	s_barrier
	v_mfma_f32_16x16x32_bf16 v[124:127], v[144:147], v[184:187], v[124:127]
	v_mfma_f32_16x16x32_bf16 v[72:75], v[160:163], v[184:187], v[72:75]
	v_mfma_f32_16x16x32_bf16 v[116:119], v[144:147], v[192:195], v[116:119]
	v_mfma_f32_16x16x32_bf16 v[68:71], v[160:163], v[192:195], v[68:71]
	v_mfma_f32_16x16x32_bf16 v[108:111], v[144:147], v[200:203], v[108:111]
	v_mfma_f32_16x16x32_bf16 v[96:99], v[160:163], v[200:203], v[96:99]
	v_mfma_f32_16x16x32_bf16 v[92:95], v[144:147], v[208:211], v[92:95]
	v_mfma_f32_16x16x32_bf16 v[88:91], v[160:163], v[208:211], v[88:91]
	v_mfma_f32_16x16x32_bf16 v[124:127], v[148:151], v[188:191], v[124:127]
	v_mfma_f32_16x16x32_bf16 v[72:75], v[164:167], v[188:191], v[72:75]
	v_mfma_f32_16x16x32_bf16 v[116:119], v[148:151], v[196:199], v[116:119]
	v_mfma_f32_16x16x32_bf16 v[68:71], v[164:167], v[196:199], v[68:71]
	v_mfma_f32_16x16x32_bf16 v[108:111], v[148:151], v[204:207], v[108:111]
	v_mfma_f32_16x16x32_bf16 v[96:99], v[164:167], v[204:207], v[96:99]
	v_mfma_f32_16x16x32_bf16 v[92:95], v[148:151], v[212:215], v[92:95]
	v_mfma_f32_16x16x32_bf16 v[88:91], v[164:167], v[212:215], v[88:91]
	v_mfma_f32_16x16x32_bf16 v[120:123], v[168:171], v[184:187], v[120:123]
	v_mfma_f32_16x16x32_bf16 v[84:87], v[176:179], v[184:187], v[84:87]
	v_mfma_f32_16x16x32_bf16 v[112:115], v[168:171], v[192:195], v[112:115]
	v_mfma_f32_16x16x32_bf16 v[80:83], v[176:179], v[192:195], v[80:83]
	v_mfma_f32_16x16x32_bf16 v[104:107], v[168:171], v[200:203], v[104:107]
	v_mfma_f32_16x16x32_bf16 v[100:103], v[176:179], v[200:203], v[100:103]
	v_mfma_f32_16x16x32_bf16 v[76:79], v[168:171], v[208:211], v[76:79]
	v_mfma_f32_16x16x32_bf16 v[64:67], v[176:179], v[208:211], v[64:67]
	v_mfma_f32_16x16x32_bf16 v[120:123], v[172:175], v[188:191], v[120:123]
	v_mfma_f32_16x16x32_bf16 v[84:87], v[180:183], v[188:191], v[84:87]
	v_mfma_f32_16x16x32_bf16 v[112:115], v[172:175], v[196:199], v[112:115]
	v_mfma_f32_16x16x32_bf16 v[80:83], v[180:183], v[196:199], v[80:83]
	v_mfma_f32_16x16x32_bf16 v[104:107], v[172:175], v[204:207], v[104:107]
	v_mfma_f32_16x16x32_bf16 v[100:103], v[180:183], v[204:207], v[100:103]
	v_mfma_f32_16x16x32_bf16 v[76:79], v[172:175], v[212:215], v[76:79]
	v_mfma_f32_16x16x32_bf16 v[64:67], v[180:183], v[212:215], v[64:67]
	s_barrier
	s_add_u32 s98, s58, s20
	s_addc_u32 s99, s59, s21
	s_add_u32 s100, s60, s20
	s_addc_u32 s101, s61, s21
	s_add_i32 s75, s68, s3
	s_mov_b32 m0, s75
	ds_read_b128 v[184:187], v157 offset:16384
	ds_read_b128 v[188:191], v157 offset:17408
	ds_read_b128 v[192:195], v157 offset:18432
	ds_read_b128 v[196:199], v157 offset:19456
	ds_read_b128 v[200:203], v157 offset:20480
	ds_read_b128 v[204:207], v157 offset:21504
	ds_read_b128 v[208:211], v157 offset:22528
	ds_read_b128 v[212:215], v157 offset:23552
	global_load_lds_dwordx4 v130, s[58:59]
	s_add_i32 m0, s75, 0x2000
	s_add_u32 s84, s58, 0x100000
	s_addc_u32 s85, s59, 0
	s_add_i32 s75, s69, s3
	global_load_lds_dwordx4 v134, s[58:59]
	s_mov_b32 m0, s75
	s_nop 0
	global_load_lds_dwordx4 v130, s[84:85]
	s_add_i32 m0, s75, 0x2000
	s_nop 0
	global_load_lds_dwordx4 v134, s[84:85]
	s_mov_b32 m0, s29
	s_nop 0
	global_load_lds_dwordx4 v128, s[60:61]
	s_mov_b32 m0, s33
	s_nop 0
	global_load_lds_dwordx4 v132, s[60:61]
	s_waitcnt vmcnt(8) lgkmcnt(0)
	s_barrier
	v_mfma_f32_16x16x32_bf16 v[60:63], v[144:147], v[184:187], v[60:63]
	v_mfma_f32_16x16x32_bf16 v[56:59], v[160:163], v[184:187], v[56:59]
	v_mfma_f32_16x16x32_bf16 v[44:47], v[144:147], v[192:195], v[44:47]
	v_mfma_f32_16x16x32_bf16 v[40:43], v[160:163], v[192:195], v[40:43]
	v_mfma_f32_16x16x32_bf16 v[28:31], v[144:147], v[200:203], v[28:31]
	v_mfma_f32_16x16x32_bf16 v[24:27], v[160:163], v[200:203], v[24:27]
	v_mfma_f32_16x16x32_bf16 v[12:15], v[144:147], v[208:211], v[12:15]
	v_mfma_f32_16x16x32_bf16 v[8:11], v[160:163], v[208:211], v[8:11]
	v_mfma_f32_16x16x32_bf16 v[60:63], v[148:151], v[188:191], v[60:63]
	v_mfma_f32_16x16x32_bf16 v[56:59], v[164:167], v[188:191], v[56:59]
	v_mfma_f32_16x16x32_bf16 v[44:47], v[148:151], v[196:199], v[44:47]
	v_mfma_f32_16x16x32_bf16 v[40:43], v[164:167], v[196:199], v[40:43]
	v_mfma_f32_16x16x32_bf16 v[28:31], v[148:151], v[204:207], v[28:31]
	v_mfma_f32_16x16x32_bf16 v[24:27], v[164:167], v[204:207], v[24:27]
	v_mfma_f32_16x16x32_bf16 v[12:15], v[148:151], v[212:215], v[12:15]
	v_mfma_f32_16x16x32_bf16 v[8:11], v[164:167], v[212:215], v[8:11]
	v_mfma_f32_16x16x32_bf16 v[52:55], v[168:171], v[184:187], v[52:55]
	v_mfma_f32_16x16x32_bf16 v[48:51], v[176:179], v[184:187], v[48:51]
	v_mfma_f32_16x16x32_bf16 v[36:39], v[168:171], v[192:195], v[36:39]
	v_mfma_f32_16x16x32_bf16 v[32:35], v[176:179], v[192:195], v[32:35]
	v_mfma_f32_16x16x32_bf16 v[20:23], v[168:171], v[200:203], v[20:23]
	v_mfma_f32_16x16x32_bf16 v[16:19], v[176:179], v[200:203], v[16:19]
	v_mfma_f32_16x16x32_bf16 v[4:7], v[168:171], v[208:211], v[4:7]
	v_mfma_f32_16x16x32_bf16 v[0:3], v[176:179], v[208:211], v[0:3]
	v_mfma_f32_16x16x32_bf16 v[52:55], v[172:175], v[188:191], v[52:55]
	v_mfma_f32_16x16x32_bf16 v[48:51], v[180:183], v[188:191], v[48:51]
	v_mfma_f32_16x16x32_bf16 v[36:39], v[172:175], v[196:199], v[36:39]
	v_mfma_f32_16x16x32_bf16 v[32:35], v[180:183], v[196:199], v[32:35]
	v_mfma_f32_16x16x32_bf16 v[20:23], v[172:175], v[204:207], v[20:23]
	v_mfma_f32_16x16x32_bf16 v[16:19], v[180:183], v[204:207], v[16:19]
	v_mfma_f32_16x16x32_bf16 v[4:7], v[172:175], v[212:215], v[4:7]
	v_mfma_f32_16x16x32_bf16 v[0:3], v[180:183], v[212:215], v[0:3]
	s_barrier
; #define PG8_STAGE(bufoff, gbase, voff) do { _Pragma("unroll") for (int _i = 0; _i < 2; ++_i) \
;         __builtin_amdgcn_global_load_lds((const unsigned*)((const char*)(gbase) + (voff)[_i]), (PG8_LAS unsigned*)(lds + (bufoff) + ldsw + _i * 8192), 16, 0, 0); } while (0)
; #define PG8_LDA(dst, b, h) do { _Pragma("unroll") for (int m = 0; m < 4; ++m) _Pragma("unroll") for (int k = 0; k < 2; ++k) dst[m][k] = *(const PG8_LAS bf16x8*)(lds + PG8_SA(b, h) + aoff + m * 2048 + k * 1024); } while (0)
; #define PG8_LDB(dst, b, h) do { _Pragma("unroll") for (int n = 0; n < 2; ++n) _Pragma("unroll") for (int k = 0; k < 2; ++k) dst[n][k] = *(const PG8_LAS bf16x8*)(lds + PG8_SB(b, h) + boff + n * 2048 + k * 1024); } while (0)
; template <class Epi, class Sched, bool ALIGN_EPI = false, bool SP2 = false>
; __device__ __forceinline__ void gemm_phase(PG8_LAS unsigned char* lds, const Gemm g, const Sched& S, const Epi& E) {
;     ...
;         for (int t = 0; t < nt; t += 2) {
;             const bool last = (t == nt - 2);
;             const char* a1 = cA + (size_t)(t + 1) * kstepA;
;             const char* a2 = last ? nA : cA + (size_t)(t + 2) * kstepA; const char* b2 = last ? nB : cB + (size_t)(t + 2) * kstep;
;             const char* a3 = a2 + kstepA; const char* b3 = b2 + kstep;
;             if (last && has_next) S.a_ready(nxt);
;             if constexpr (SP2) {
;             PG8_LDB(B0, 0, 0); PG8_LDB(B1, 0, 1); PG8_SCHED; PG8_LDA(At, 0, 0); PG8_STAGE(PG8_SA(1, 1), a1 + hstepA, voffA);
;             PG8_WAIT_V(8); PG8_WAIT_L(0); PG8_BAR; PG8_MMA(0, 0, At, B0); PG8_MMA(0, 1, At, B1); PG8_BAR; PG8_SCHED;
;             PG8_LDA(At, 0, 1); PG8_STAGE(PG8_SB(0, 0), b2, voffB); PG8_STAGE(PG8_SB(0, 1), b2 + hstep, voffB); PG8_STAGE(PG8_SA(0, 0), a2, voffA);
;             PG8_WAIT_V(8); PG8_WAIT_L(0); PG8_BAR; PG8_MMA(1, 0, At, B0); PG8_MMA(1, 1, At, B1); PG8_BAR; PG8_SCHED;
;             PG8_LDB(B0, 1, 0); PG8_LDB(B1, 1, 1); PG8_SCHED; PG8_LDA(At, 1, 0); PG8_STAGE(PG8_SA(0, 1), a2 + hstepA, voffA);
;             PG8_WAIT_V(8); PG8_WAIT_L(0); PG8_BAR; PG8_MMA(0, 0, At, B0); PG8_MMA(0, 1, At, B1); PG8_BAR; PG8_SCHED;
;             PG8_LDA(At, 1, 1); PG8_STAGE(PG8_SB(1, 0), b3, voffB); PG8_STAGE(PG8_SB(1, 1), b3 + hstep, voffB); PG8_STAGE(PG8_SA(1, 0), a3, voffA);
;             PG8_WAIT_V(8); PG8_WAIT_L(0); PG8_BAR; PG8_MMA(1, 0, At, B0); PG8_MMA(1, 1, At, B1); PG8_BAR; PG8_SCHED;
	s_add_i32 s75, 0, 0x18000
	s_add_i32 s84, 0, 0x1c000
	ds_read_b128 v[144:147], v216
	ds_read_b128 v[148:151], v216 offset:1024
	ds_read_b128 v[160:163], v216 offset:2048
	ds_read_b128 v[164:167], v216 offset:3072
	ds_read_b128 v[168:171], v217
	ds_read_b128 v[172:175], v217 offset:1024
	ds_read_b128 v[176:179], v217 offset:2048
	ds_read_b128 v[180:183], v217 offset:3072
	s_add_u32 s60, s60, 0x100000
	s_addc_u32 s61, s61, 0
	s_mov_b32 m0, s55
	ds_read_b128 v[184:187], v157 offset:32768
	ds_read_b128 v[188:191], v157 offset:33792
	ds_read_b128 v[192:195], v157 offset:34816
	ds_read_b128 v[196:199], v157 offset:35840
	ds_read_b128 v[200:203], v157 offset:36864
	ds_read_b128 v[204:207], v157 offset:37888
	ds_read_b128 v[208:211], v157 offset:38912
	ds_read_b128 v[212:215], v157 offset:39936
	global_load_lds_dwordx4 v128, s[60:61]
	s_mov_b32 m0, s62
	s_nop 0
	global_load_lds_dwordx4 v132, s[60:61]
	s_waitcnt vmcnt(8) lgkmcnt(0)
	s_barrier
	v_mfma_f32_16x16x32_bf16 v[124:127], v[144:147], v[184:187], v[124:127]
	v_mfma_f32_16x16x32_bf16 v[72:75], v[160:163], v[184:187], v[72:75]
	v_mfma_f32_16x16x32_bf16 v[116:119], v[144:147], v[192:195], v[116:119]
	v_mfma_f32_16x16x32_bf16 v[68:71], v[160:163], v[192:195], v[68:71]
	v_mfma_f32_16x16x32_bf16 v[108:111], v[144:147], v[200:203], v[108:111]
	v_mfma_f32_16x16x32_bf16 v[96:99], v[160:163], v[200:203], v[96:99]
	v_mfma_f32_16x16x32_bf16 v[92:95], v[144:147], v[208:211], v[92:95]
	v_mfma_f32_16x16x32_bf16 v[88:91], v[160:163], v[208:211], v[88:91]
	v_mfma_f32_16x16x32_bf16 v[124:127], v[148:151], v[188:191], v[124:127]
	v_mfma_f32_16x16x32_bf16 v[72:75], v[164:167], v[188:191], v[72:75]
	v_mfma_f32_16x16x32_bf16 v[116:119], v[148:151], v[196:199], v[116:119]
	v_mfma_f32_16x16x32_bf16 v[68:71], v[164:167], v[196:199], v[68:71]
	v_mfma_f32_16x16x32_bf16 v[108:111], v[148:151], v[204:207], v[108:111]
	v_mfma_f32_16x16x32_bf16 v[96:99], v[164:167], v[204:207], v[96:99]
	v_mfma_f32_16x16x32_bf16 v[92:95], v[148:151], v[212:215], v[92:95]
	v_mfma_f32_16x16x32_bf16 v[88:91], v[164:167], v[212:215], v[88:91]
	v_mfma_f32_16x16x32_bf16 v[120:123], v[168:171], v[184:187], v[120:123]
	v_mfma_f32_16x16x32_bf16 v[84:87], v[176:179], v[184:187], v[84:87]
	v_mfma_f32_16x16x32_bf16 v[112:115], v[168:171], v[192:195], v[112:115]
	v_mfma_f32_16x16x32_bf16 v[80:83], v[176:179], v[192:195], v[80:83]
	v_mfma_f32_16x16x32_bf16 v[104:107], v[168:171], v[200:203], v[104:107]
	v_mfma_f32_16x16x32_bf16 v[100:103], v[176:179], v[200:203], v[100:103]
	v_mfma_f32_16x16x32_bf16 v[76:79], v[168:171], v[208:211], v[76:79]
	v_mfma_f32_16x16x32_bf16 v[64:67], v[176:179], v[208:211], v[64:67]
	v_mfma_f32_16x16x32_bf16 v[120:123], v[172:175], v[188:191], v[120:123]
	v_mfma_f32_16x16x32_bf16 v[84:87], v[180:183], v[188:191], v[84:87]
	v_mfma_f32_16x16x32_bf16 v[112:115], v[172:175], v[196:199], v[112:115]
	v_mfma_f32_16x16x32_bf16 v[80:83], v[180:183], v[196:199], v[80:83]
	v_mfma_f32_16x16x32_bf16 v[104:107], v[172:175], v[204:207], v[104:107]
	v_mfma_f32_16x16x32_bf16 v[100:103], v[180:183], v[204:207], v[100:103]
	v_mfma_f32_16x16x32_bf16 v[76:79], v[172:175], v[212:215], v[76:79]
	v_mfma_f32_16x16x32_bf16 v[64:67], v[180:183], v[212:215], v[64:67]
	s_barrier
	s_add_i32 s60, s75, s3
	s_mov_b32 m0, s60
	ds_read_b128 v[184:187], v157 offset:49152
	ds_read_b128 v[188:191], v157 offset:50176
	ds_read_b128 v[192:195], v157 offset:51200
	ds_read_b128 v[196:199], v157 offset:52224
	ds_read_b128 v[200:203], v157 offset:53248
	ds_read_b128 v[204:207], v157 offset:54272
	ds_read_b128 v[208:211], v157 offset:55296
	ds_read_b128 v[212:215], v157 offset:56320
	global_load_lds_dwordx4 v130, s[98:99]
	s_add_i32 m0, s60, 0x2000
	s_add_u32 s58, s58, 0x100080
	s_addc_u32 s59, s59, 0
	s_add_i32 s60, s84, s3
	global_load_lds_dwordx4 v134, s[98:99]
	s_mov_b32 m0, s60
	s_nop 0
	global_load_lds_dwordx4 v130, s[58:59]
	s_add_i32 m0, s60, 0x2000
	s_nop 0
	global_load_lds_dwordx4 v134, s[58:59]
	s_mov_b32 m0, s64
	s_nop 0
	global_load_lds_dwordx4 v128, s[100:101]
	s_mov_b32 m0, s65
	s_nop 0
	global_load_lds_dwordx4 v132, s[100:101]
	s_add_i32 s74, s74, 2
	s_add_u32 s56, s56, 0x100
	s_addc_u32 s57, s57, 0
	s_add_u32 s72, s72, 0x100
	s_addc_u32 s73, s73, 0
	s_cmp_gt_u32 s74, 61
	s_waitcnt vmcnt(8) lgkmcnt(0)
	s_barrier
	v_mfma_f32_16x16x32_bf16 v[60:63], v[144:147], v[184:187], v[60:63]
	v_mfma_f32_16x16x32_bf16 v[56:59], v[160:163], v[184:187], v[56:59]
	v_mfma_f32_16x16x32_bf16 v[44:47], v[144:147], v[192:195], v[44:47]
	v_mfma_f32_16x16x32_bf16 v[40:43], v[160:163], v[192:195], v[40:43]
	v_mfma_f32_16x16x32_bf16 v[28:31], v[144:147], v[200:203], v[28:31]
	v_mfma_f32_16x16x32_bf16 v[24:27], v[160:163], v[200:203], v[24:27]
	v_mfma_f32_16x16x32_bf16 v[12:15], v[144:147], v[208:211], v[12:15]
	v_mfma_f32_16x16x32_bf16 v[8:11], v[160:163], v[208:211], v[8:11]
	v_mfma_f32_16x16x32_bf16 v[60:63], v[148:151], v[188:191], v[60:63]
	v_mfma_f32_16x16x32_bf16 v[56:59], v[164:167], v[188:191], v[56:59]
	v_mfma_f32_16x16x32_bf16 v[44:47], v[148:151], v[196:199], v[44:47]
	v_mfma_f32_16x16x32_bf16 v[40:43], v[164:167], v[196:199], v[40:43]
	v_mfma_f32_16x16x32_bf16 v[28:31], v[148:151], v[204:207], v[28:31]
	v_mfma_f32_16x16x32_bf16 v[24:27], v[164:167], v[204:207], v[24:27]
	v_mfma_f32_16x16x32_bf16 v[12:15], v[148:151], v[212:215], v[12:15]
	v_mfma_f32_16x16x32_bf16 v[8:11], v[164:167], v[212:215], v[8:11]
	v_mfma_f32_16x16x32_bf16 v[52:55], v[168:171], v[184:187], v[52:55]
	v_mfma_f32_16x16x32_bf16 v[48:51], v[176:179], v[184:187], v[48:51]
	v_mfma_f32_16x16x32_bf16 v[36:39], v[168:171], v[192:195], v[36:39]
	v_mfma_f32_16x16x32_bf16 v[32:35], v[176:179], v[192:195], v[32:35]
	v_mfma_f32_16x16x32_bf16 v[20:23], v[168:171], v[200:203], v[20:23]
	v_mfma_f32_16x16x32_bf16 v[16:19], v[176:179], v[200:203], v[16:19]
	v_mfma_f32_16x16x32_bf16 v[4:7], v[168:171], v[208:211], v[4:7]
	v_mfma_f32_16x16x32_bf16 v[0:3], v[176:179], v[208:211], v[0:3]
	v_mfma_f32_16x16x32_bf16 v[52:55], v[172:175], v[188:191], v[52:55]
	v_mfma_f32_16x16x32_bf16 v[48:51], v[180:183], v[188:191], v[48:51]
	v_mfma_f32_16x16x32_bf16 v[36:39], v[172:175], v[196:199], v[36:39]
	v_mfma_f32_16x16x32_bf16 v[32:35], v[180:183], v[196:199], v[32:35]
	v_mfma_f32_16x16x32_bf16 v[20:23], v[172:175], v[204:207], v[20:23]
	v_mfma_f32_16x16x32_bf16 v[16:19], v[180:183], v[204:207], v[16:19]
	v_mfma_f32_16x16x32_bf16 v[4:7], v[172:175], v[212:215], v[4:7]
	v_mfma_f32_16x16x32_bf16 v[0:3], v[180:183], v[212:215], v[0:3]
	s_barrier
	s_cbranch_scc0 .LBB0_3203
	s_and_b64 vcc, exec, s[22:23]
	s_cbranch_vccz .LBB0_3206
	s_barrier
